# E1 (no unit-start vmcnt0) + E2 colmax prefetch in last MFMA block of P1/P9
# speedup vs baseline: 1.0017x; 1.0017x over previous
; #define PG8_STAGE(bufoff, gbase, voff) do { _Pragma("unroll") for (int _i = 0; _i < 2; ++_i) \
;         __builtin_amdgcn_global_load_lds((const unsigned*)((const char*)(gbase) + (voff)[_i]), (PG8_LAS unsigned*)(lds + (bufoff) + ldsw + _i * 8192), 16, 0, 0); } while (0)
; #define PG8_WAIT_V(n) asm volatile("s_waitcnt vmcnt(" #n ")" ::: "memory")
; #define PG8_WAIT_L(n) asm volatile("s_waitcnt lgkmcnt(" #n ")" ::: "memory")
; #define PG8_BAR __builtin_amdgcn_s_barrier()
; #define PG8_SCHED __builtin_amdgcn_sched_barrier(0)
;     ...
;     for (;;) {
;         const bool has_next = S.next(ui + 1, nxt);
;         const char* nA = has_next ? (const char*)g.A + (size_t)nxt.pm * tstep : cA; const char* nB = has_next ? (const char*)g.Bt + (size_t)nxt.pn * tstep : cB;
;         for (int t = 0; t < nt; t += 2) {
;             const bool last = (t == nt - 2);
;             const char* a1 = cA + (size_t)(t + 1) * kstep;
;             const char* a2 = last ? nA : cA + (size_t)(t + 2) * kstep; const char* b2 = last ? nB : cB + (size_t)(t + 2) * kstep;
;             const char* a3 = a2 + kstep; const char* b3 = b2 + kstep;
;             if (last && has_next) S.a_ready(nxt);
;             if (last) E.pre(pre, cur, wr, fr);
;             if constexpr (MIDK > 0) { if (t == MIDK / BK) E.mid(acc, cur, wr, wc, fr, fq); }
;             if constexpr (SP2) {
;             PG8_LDB(B0, 0, 0); PG8_LDB(B1, 0, 1); PG8_SCHED; PG8_LDA(At, 0, 0); PG8_STAGE(PG8_SA(1, 1), a1 + hstep, voffA);
;             PG8_WAIT_V(8); PG8_WAIT_L(0); PG8_BAR; PG8_MMA(0, 0, At, B0); PG8_MMA(0, 1, At, B1); PG8_BAR; PG8_SCHED;
;     ...
; #pragma unroll
;         for (int a = 0; a < 2; ++a)
; #pragma unroll
;             for (int b = 0; b < 2; ++b)
; #pragma unroll
;                 for (int m = 0; m < 4; ++m)
; #pragma unroll
;                     for (int n = 0; n < 2; ++n) acc[a][b][m][n] = (f32x4){0.f, 0.f, 0.f, 0.f};
;         cur = nxt; cA = nA; cB = nB; ++ui;
.LBB0_247:
	s_ashr_i32 s25, s24, 31
	s_lshl_b64 s[34:35], s[24:25], 19
	s_add_u32 s44, s3, s34
	s_addc_u32 s45, s17, s35
	s_and_b64 s[34:35], s[4:5], exec
	s_cselect_b32 s25, s45, s55
	s_cselect_b32 s34, s44, s54
	s_ashr_i32 s21, s20, 31
	s_lshl_b64 s[48:49], s[20:21], 19
	s_add_u32 s48, s18, s48
	s_addc_u32 s49, s19, s49
	s_and_b64 s[72:73], s[4:5], exec
	s_cselect_b32 s21, s49, s53
	s_cselect_b32 s35, s48, s52
	v_lshl_add_u32 v162, s50, 8, v147
	s_add_u32 s50, s54, 0x40080
	s_addc_u32 s51, s55, 0
	v_ashrrev_i32_e32 v163, 31, v162
	s_add_u32 s72, s52, 0x100
	v_mov_b32_e32 v0, 0
	s_addc_u32 s73, s53, 0
	s_mov_b32 s74, -2
	v_mov_b32_e32 v1, v0
	v_mov_b32_e32 v2, v0
	v_mov_b32_e32 v3, v0
	v_mov_b32_e32 v8, v0
	v_mov_b32_e32 v9, v0
	v_mov_b32_e32 v10, v0
	v_mov_b32_e32 v11, v0
	v_mov_b32_e32 v16, v0
	v_mov_b32_e32 v17, v0
	v_mov_b32_e32 v18, v0
	v_mov_b32_e32 v19, v0
	v_mov_b32_e32 v24, v0
	v_mov_b32_e32 v25, v0
	v_mov_b32_e32 v26, v0
	v_mov_b32_e32 v27, v0
	v_mov_b32_e32 v32, v0
	v_mov_b32_e32 v33, v0
	v_mov_b32_e32 v34, v0
	v_mov_b32_e32 v35, v0
	v_mov_b32_e32 v40, v0
	v_mov_b32_e32 v41, v0
	v_mov_b32_e32 v42, v0
	v_mov_b32_e32 v43, v0
	v_mov_b32_e32 v48, v0
	v_mov_b32_e32 v49, v0
	v_mov_b32_e32 v50, v0
	v_mov_b32_e32 v51, v0
	v_mov_b32_e32 v56, v0
	v_mov_b32_e32 v57, v0
	v_mov_b32_e32 v58, v0
	v_mov_b32_e32 v59, v0
	v_mov_b32_e32 v4, v0
	v_mov_b32_e32 v5, v0
	v_mov_b32_e32 v6, v0
	v_mov_b32_e32 v7, v0
	v_mov_b32_e32 v12, v0
	v_mov_b32_e32 v13, v0
	v_mov_b32_e32 v14, v0
	v_mov_b32_e32 v15, v0
	v_mov_b32_e32 v20, v0
	v_mov_b32_e32 v21, v0
	v_mov_b32_e32 v22, v0
	v_mov_b32_e32 v23, v0
	v_mov_b32_e32 v28, v0
	v_mov_b32_e32 v29, v0
	v_mov_b32_e32 v30, v0
	v_mov_b32_e32 v31, v0
	v_mov_b32_e32 v36, v0
	v_mov_b32_e32 v37, v0
	v_mov_b32_e32 v38, v0
	v_mov_b32_e32 v39, v0
	v_mov_b32_e32 v44, v0
	v_mov_b32_e32 v45, v0
	v_mov_b32_e32 v46, v0
	v_mov_b32_e32 v47, v0
	v_mov_b32_e32 v52, v0
	v_mov_b32_e32 v53, v0
	v_mov_b32_e32 v54, v0
	v_mov_b32_e32 v55, v0
	v_mov_b32_e32 v60, v0
	v_mov_b32_e32 v61, v0
	v_mov_b32_e32 v62, v0
	v_mov_b32_e32 v63, v0
	v_mov_b32_e32 v64, v0
	v_mov_b32_e32 v65, v0
	v_mov_b32_e32 v66, v0
	v_mov_b32_e32 v67, v0
	v_mov_b32_e32 v72, v0
	v_mov_b32_e32 v73, v0
	v_mov_b32_e32 v74, v0
	v_mov_b32_e32 v75, v0
	v_mov_b32_e32 v80, v0
	v_mov_b32_e32 v81, v0
	v_mov_b32_e32 v82, v0
	v_mov_b32_e32 v83, v0
	v_mov_b32_e32 v88, v0
	v_mov_b32_e32 v89, v0
	v_mov_b32_e32 v90, v0
	v_mov_b32_e32 v91, v0
	v_mov_b32_e32 v96, v0
	v_mov_b32_e32 v97, v0
	v_mov_b32_e32 v98, v0
	v_mov_b32_e32 v99, v0
	v_mov_b32_e32 v104, v0
	v_mov_b32_e32 v105, v0
	v_mov_b32_e32 v106, v0
	v_mov_b32_e32 v107, v0
	v_mov_b32_e32 v112, v0
	v_mov_b32_e32 v113, v0
	v_mov_b32_e32 v114, v0
	v_mov_b32_e32 v115, v0
	v_mov_b32_e32 v120, v0
	v_mov_b32_e32 v121, v0
	v_mov_b32_e32 v122, v0
	v_mov_b32_e32 v123, v0
	v_mov_b32_e32 v68, v0
	v_mov_b32_e32 v69, v0
	v_mov_b32_e32 v70, v0
	v_mov_b32_e32 v71, v0
	v_mov_b32_e32 v76, v0
	v_mov_b32_e32 v77, v0
	v_mov_b32_e32 v78, v0
	v_mov_b32_e32 v79, v0
	v_mov_b32_e32 v84, v0
	v_mov_b32_e32 v85, v0
	v_mov_b32_e32 v86, v0
	v_mov_b32_e32 v87, v0
	v_mov_b32_e32 v92, v0
	v_mov_b32_e32 v93, v0
	v_mov_b32_e32 v94, v0
	v_mov_b32_e32 v95, v0
	v_mov_b32_e32 v100, v0
	v_mov_b32_e32 v101, v0
	v_mov_b32_e32 v102, v0
	v_mov_b32_e32 v103, v0
	v_mov_b32_e32 v108, v0
	v_mov_b32_e32 v109, v0
	v_mov_b32_e32 v110, v0
	v_mov_b32_e32 v111, v0
	v_mov_b32_e32 v116, v0
	v_mov_b32_e32 v117, v0
	v_mov_b32_e32 v118, v0
	v_mov_b32_e32 v119, v0
	v_mov_b32_e32 v124, v0
	v_mov_b32_e32 v125, v0
	v_mov_b32_e32 v126, v0
	v_mov_b32_e32 v127, v0
	v_lshl_add_u64 v[164:165], v[162:163], 2, s[8:9]
	s_branch .LBB0_249
.LBB0_248:
	v_add_u32_e32 v155, s68, v149
	ds_read_b128 v[166:169], v155
	ds_read_b128 v[170:173], v155 offset:1024
	ds_read_b128 v[174:177], v155 offset:2048
	ds_read_b128 v[178:181], v155 offset:3072
	v_add_u32_e32 v155, s69, v149
	ds_read_b128 v[182:185], v155
	ds_read_b128 v[186:189], v155 offset:1024
	ds_read_b128 v[190:193], v155 offset:2048
	ds_read_b128 v[194:197], v155 offset:3072
	s_add_u32 s33, s50, 0xfffc0080
	s_addc_u32 s54, s51, -1
	s_and_b64 s[52:53], s[52:53], exec
	s_cselect_b32 s55, s25, s54
	s_cselect_b32 s54, s34, s33
	s_cselect_b32 s53, s21, s73
	s_cselect_b32 s52, s35, s72
	v_lshl_add_u64 v[210:211], s[50:51], 0, v[138:139]
	s_add_i32 m0, s59, 0xc000
	ds_read_b128 v[198:201], v153
	ds_read_b128 v[202:205], v153 offset:1024
	ds_read_b128 v[206:209], v153 offset:2048
	ds_read_b128 v[214:217], v153 offset:3072
	ds_read_b128 v[218:221], v153 offset:4096
	ds_read_b128 v[222:225], v153 offset:5120
	ds_read_b128 v[226:229], v153 offset:6144
	ds_read_b128 v[230:233], v153 offset:7168
	global_load_lds_dwordx4 v[210:211], off
	v_lshl_add_u64 v[210:211], s[50:51], 0, v[140:141]
	s_add_i32 m0, s59, 0xe000
	s_nop 0
	global_load_lds_dwordx4 v[210:211], off
	s_waitcnt vmcnt(8)
	s_waitcnt lgkmcnt(0)
	s_barrier
; #define PG8_STAGE(bufoff, gbase, voff) do { _Pragma("unroll") for (int _i = 0; _i < 2; ++_i) \
;         __builtin_amdgcn_global_load_lds((const unsigned*)((const char*)(gbase) + (voff)[_i]), (PG8_LAS unsigned*)(lds + (bufoff) + ldsw + _i * 8192), 16, 0, 0); } while (0)
; #define PG8_WAIT_V(n) asm volatile("s_waitcnt vmcnt(" #n ")" ::: "memory")
; #define PG8_WAIT_L(n) asm volatile("s_waitcnt lgkmcnt(" #n ")" ::: "memory")
; #define PG8_BAR __builtin_amdgcn_s_barrier()
; #define PG8_SCHED __builtin_amdgcn_sched_barrier(0)
;     ...
;             PG8_WAIT_V(8); PG8_WAIT_L(0); PG8_BAR; PG8_MMA(0, 0, At, B0); PG8_MMA(0, 1, At, B1); PG8_BAR; PG8_SCHED;
;             PG8_LDA(At, 0, 1); PG8_STAGE(PG8_SB(0, 0), b2, voffB); PG8_STAGE(PG8_SB(0, 1), b2 + hstep, voffB); PG8_STAGE(PG8_SA(0, 0), a2, voffA);
;             PG8_WAIT_V(8); PG8_WAIT_L(0); PG8_BAR; PG8_MMA(1, 0, At, B0); PG8_MMA(1, 1, At, B1); PG8_BAR; PG8_SCHED;
	s_setprio 1
	s_waitcnt lgkmcnt(0)
	v_mfma_i32_16x16x64_i8 v[124:127], v[166:169], v[198:201], v[124:127]
	v_mfma_i32_16x16x64_i8 v[116:119], v[174:177], v[198:201], v[116:119]
	v_mfma_i32_16x16x64_i8 v[108:111], v[166:169], v[206:209], v[108:111]
	v_mfma_i32_16x16x64_i8 v[100:103], v[174:177], v[206:209], v[100:103]
	v_mfma_i32_16x16x64_i8 v[92:95], v[166:169], v[218:221], v[92:95]
	v_mfma_i32_16x16x64_i8 v[84:87], v[174:177], v[218:221], v[84:87]
	v_mfma_i32_16x16x64_i8 v[76:79], v[166:169], v[226:229], v[76:79]
	v_mfma_i32_16x16x64_i8 v[68:71], v[174:177], v[226:229], v[68:71]
	v_mfma_i32_16x16x64_i8 v[124:127], v[170:173], v[202:205], v[124:127]
	v_mfma_i32_16x16x64_i8 v[116:119], v[178:181], v[202:205], v[116:119]
	v_mfma_i32_16x16x64_i8 v[108:111], v[170:173], v[214:217], v[108:111]
	v_mfma_i32_16x16x64_i8 v[100:103], v[178:181], v[214:217], v[100:103]
	v_mfma_i32_16x16x64_i8 v[92:95], v[170:173], v[222:225], v[92:95]
	v_mfma_i32_16x16x64_i8 v[84:87], v[178:181], v[222:225], v[84:87]
	v_mfma_i32_16x16x64_i8 v[76:79], v[170:173], v[230:233], v[76:79]
	v_mfma_i32_16x16x64_i8 v[68:71], v[178:181], v[230:233], v[68:71]
	s_setprio 0
	s_setprio 1
	v_mfma_i32_16x16x64_i8 v[120:123], v[182:185], v[198:201], v[120:123]
	v_mfma_i32_16x16x64_i8 v[112:115], v[190:193], v[198:201], v[112:115]
	v_mfma_i32_16x16x64_i8 v[104:107], v[182:185], v[206:209], v[104:107]
	v_mfma_i32_16x16x64_i8 v[96:99], v[190:193], v[206:209], v[96:99]
	v_mfma_i32_16x16x64_i8 v[88:91], v[182:185], v[218:221], v[88:91]
	v_mfma_i32_16x16x64_i8 v[80:83], v[190:193], v[218:221], v[80:83]
	v_mfma_i32_16x16x64_i8 v[72:75], v[182:185], v[226:229], v[72:75]
	v_mfma_i32_16x16x64_i8 v[64:67], v[190:193], v[226:229], v[64:67]
	v_mfma_i32_16x16x64_i8 v[120:123], v[186:189], v[202:205], v[120:123]
	v_mfma_i32_16x16x64_i8 v[112:115], v[194:197], v[202:205], v[112:115]
	v_mfma_i32_16x16x64_i8 v[104:107], v[186:189], v[214:217], v[104:107]
	v_mfma_i32_16x16x64_i8 v[96:99], v[194:197], v[214:217], v[96:99]
	v_mfma_i32_16x16x64_i8 v[88:91], v[186:189], v[222:225], v[88:91]
	v_mfma_i32_16x16x64_i8 v[80:83], v[194:197], v[222:225], v[80:83]
	v_mfma_i32_16x16x64_i8 v[72:75], v[186:189], v[230:233], v[72:75]
	v_mfma_i32_16x16x64_i8 v[64:67], v[194:197], v[230:233], v[64:67]
	s_setprio 0
	s_barrier
	s_add_i32 s33, s68, s56
	v_lshl_add_u64 v[210:211], s[52:53], 0, v[132:133]
	s_mov_b32 m0, s33
	ds_read_b128 v[198:201], v153 offset:16384
	ds_read_b128 v[202:205], v153 offset:17408
	ds_read_b128 v[206:209], v153 offset:18432
	ds_read_b128 v[214:217], v153 offset:19456
	ds_read_b128 v[218:221], v153 offset:20480
	ds_read_b128 v[222:225], v153 offset:21504
	ds_read_b128 v[226:229], v153 offset:22528
	ds_read_b128 v[230:233], v153 offset:23552
	global_load_lds_dwordx4 v[210:211], off
	s_add_i32 m0, s33, 0x2000
	s_add_u32 s76, s52, 0x40000
	v_lshl_add_u64 v[234:235], s[52:53], 0, v[128:129]
	s_addc_u32 s77, s53, 0
	s_add_i32 s33, s69, s56
	global_load_lds_dwordx4 v[234:235], off
	v_lshl_add_u64 v[236:237], s[76:77], 0, v[132:133]
	s_mov_b32 m0, s33
	v_lshl_add_u64 v[238:239], s[54:55], 0, v[130:131]
	global_load_lds_dwordx4 v[236:237], off
	v_lshl_add_u64 v[236:237], s[76:77], 0, v[128:129]
	s_add_i32 m0, s33, 0x2000
	s_nop 0
	global_load_lds_dwordx4 v[236:237], off
	v_lshl_add_u64 v[236:237], s[54:55], 0, v[134:135]
	s_mov_b32 m0, s59
	s_nop 0
	global_load_lds_dwordx4 v[236:237], off
	s_mov_b32 m0, s60
	s_nop 0
	global_load_lds_dwordx4 v[238:239], off
	s_waitcnt vmcnt(8)
	s_waitcnt lgkmcnt(0)
	s_barrier
	s_setprio 1
	s_waitcnt lgkmcnt(0)
	v_mfma_i32_16x16x64_i8 v[60:63], v[166:169], v[198:201], v[60:63]
	v_mfma_i32_16x16x64_i8 v[52:55], v[174:177], v[198:201], v[52:55]
	v_mfma_i32_16x16x64_i8 v[44:47], v[166:169], v[206:209], v[44:47]
	v_mfma_i32_16x16x64_i8 v[36:39], v[174:177], v[206:209], v[36:39]
	v_mfma_i32_16x16x64_i8 v[28:31], v[166:169], v[218:221], v[28:31]
	v_mfma_i32_16x16x64_i8 v[20:23], v[174:177], v[218:221], v[20:23]
	v_mfma_i32_16x16x64_i8 v[12:15], v[166:169], v[226:229], v[12:15]
	v_mfma_i32_16x16x64_i8 v[4:7], v[174:177], v[226:229], v[4:7]
	v_mfma_i32_16x16x64_i8 v[60:63], v[170:173], v[202:205], v[60:63]
	v_mfma_i32_16x16x64_i8 v[52:55], v[178:181], v[202:205], v[52:55]
	v_mfma_i32_16x16x64_i8 v[44:47], v[170:173], v[214:217], v[44:47]
	v_mfma_i32_16x16x64_i8 v[36:39], v[178:181], v[214:217], v[36:39]
	v_mfma_i32_16x16x64_i8 v[28:31], v[170:173], v[222:225], v[28:31]
	v_mfma_i32_16x16x64_i8 v[20:23], v[178:181], v[222:225], v[20:23]
	v_mfma_i32_16x16x64_i8 v[12:15], v[170:173], v[230:233], v[12:15]
	v_mfma_i32_16x16x64_i8 v[4:7], v[178:181], v[230:233], v[4:7]
	s_setprio 0
	s_setprio 1
	v_mfma_i32_16x16x64_i8 v[56:59], v[182:185], v[198:201], v[56:59]
	v_mfma_i32_16x16x64_i8 v[48:51], v[190:193], v[198:201], v[48:51]
	v_mfma_i32_16x16x64_i8 v[40:43], v[182:185], v[206:209], v[40:43]
	v_mfma_i32_16x16x64_i8 v[32:35], v[190:193], v[206:209], v[32:35]
	v_mfma_i32_16x16x64_i8 v[24:27], v[182:185], v[218:221], v[24:27]
	v_mfma_i32_16x16x64_i8 v[16:19], v[190:193], v[218:221], v[16:19]
	v_mfma_i32_16x16x64_i8 v[8:11], v[182:185], v[226:229], v[8:11]
	v_mfma_i32_16x16x64_i8 v[0:3], v[190:193], v[226:229], v[0:3]
	v_mfma_i32_16x16x64_i8 v[56:59], v[186:189], v[202:205], v[56:59]
	v_mfma_i32_16x16x64_i8 v[48:51], v[194:197], v[202:205], v[48:51]
	v_mfma_i32_16x16x64_i8 v[40:43], v[186:189], v[214:217], v[40:43]
	v_mfma_i32_16x16x64_i8 v[32:35], v[194:197], v[214:217], v[32:35]
	v_mfma_i32_16x16x64_i8 v[24:27], v[186:189], v[222:225], v[24:27]
	v_mfma_i32_16x16x64_i8 v[16:19], v[194:197], v[222:225], v[16:19]
	v_mfma_i32_16x16x64_i8 v[8:11], v[186:189], v[230:233], v[8:11]
	v_mfma_i32_16x16x64_i8 v[0:3], v[194:197], v[230:233], v[0:3]
	s_setprio 0
	s_barrier
; #define PG8_STAGE(bufoff, gbase, voff) do { _Pragma("unroll") for (int _i = 0; _i < 2; ++_i) \
;         __builtin_amdgcn_global_load_lds((const unsigned*)((const char*)(gbase) + (voff)[_i]), (PG8_LAS unsigned*)(lds + (bufoff) + ldsw + _i * 8192), 16, 0, 0); } while (0)
; #define PG8_WAIT_V(n) asm volatile("s_waitcnt vmcnt(" #n ")" ::: "memory")
; #define PG8_WAIT_L(n) asm volatile("s_waitcnt lgkmcnt(" #n ")" ::: "memory")
; #define PG8_BAR __builtin_amdgcn_s_barrier()
; #define PG8_SCHED __builtin_amdgcn_sched_barrier(0)
;     __device__ __forceinline__ void operator()(const f32x4 (&acc)[2][2][4][2], const Unit& u, int wr, int wc, int fr, int fq, const float (&pr)[8]) const {
;     ...
;             for (int n = 0; n < 2; ++n) { const u32x4 a = *(const u32x4*)(colmax + u.pn * BM + wc * 32 + 8 * fq + 4 * n), b = *(const u32x4*)(colmax + u.pn * BM + HALF + wc * 32 + 8 * fq + 4 * n);
;                 csg[n] = (f32x4){__uint_as_float(a.x), __uint_as_float(a.y), __uint_as_float(a.z), __uint_as_float(a.w)} * (1.0f / 127.0f);
;                 csu[n] = (f32x4){__uint_as_float(b.x), __uint_as_float(b.y), __uint_as_float(b.z), __uint_as_float(b.w)} * (1.0f / 127.0f); }
;     ...
;             PG8_LDB(B0, 1, 0); PG8_LDB(B1, 1, 1); PG8_SCHED; PG8_LDA(At, 1, 0); PG8_STAGE(PG8_SA(0, 1), a2 + hstep, voffA);
;             PG8_WAIT_V(8); PG8_WAIT_L(0); PG8_BAR; PG8_MMA(0, 0, At, B0); PG8_MMA(0, 1, At, B1); PG8_BAR; PG8_SCHED;
;             PG8_LDA(At, 1, 1); PG8_STAGE(PG8_SB(1, 0), b3, voffB); PG8_STAGE(PG8_SB(1, 1), b3 + hstep, voffB); PG8_STAGE(PG8_SA(1, 0), a3, voffA);
;             PG8_WAIT_V(8); PG8_WAIT_L(0); PG8_BAR; PG8_MMA(1, 0, At, B0); PG8_MMA(1, 1, At, B1); PG8_BAR; PG8_SCHED;
	s_add_i32 s33, 0, 0x18000
	v_add_u32_e32 v155, s33, v149
	s_add_i32 s75, 0, 0x1c000
	ds_read_b128 v[166:169], v155
	ds_read_b128 v[170:173], v155 offset:1024
	ds_read_b128 v[174:177], v155 offset:2048
	ds_read_b128 v[178:181], v155 offset:3072
	v_add_u32_e32 v155, s75, v149
	ds_read_b128 v[182:185], v155
	ds_read_b128 v[186:189], v155 offset:1024
	ds_read_b128 v[190:193], v155 offset:2048
	ds_read_b128 v[194:197], v155 offset:3072
	s_add_u32 s54, s54, 0x40000
	s_addc_u32 s55, s55, 0
	s_mov_b32 m0, s61
	v_lshl_add_u64 v[240:241], s[54:55], 0, v[134:135]
	ds_read_b128 v[198:201], v153 offset:32768
	ds_read_b128 v[202:205], v153 offset:33792
	ds_read_b128 v[206:209], v153 offset:34816
	ds_read_b128 v[214:217], v153 offset:35840
	ds_read_b128 v[218:221], v153 offset:36864
	ds_read_b128 v[222:225], v153 offset:37888
	ds_read_b128 v[226:229], v153 offset:38912
	ds_read_b128 v[230:233], v153 offset:39936
	global_load_lds_dwordx4 v[240:241], off
	v_lshl_add_u64 v[240:241], s[54:55], 0, v[130:131]
	s_mov_b32 m0, s62
	s_nop 0
	global_load_lds_dwordx4 v[240:241], off
	s_waitcnt vmcnt(8)
	s_waitcnt lgkmcnt(0)
	s_barrier
	s_setprio 1
	s_waitcnt lgkmcnt(0)
	v_mfma_i32_16x16x64_i8 v[124:127], v[166:169], v[198:201], v[124:127]
	v_mfma_i32_16x16x64_i8 v[116:119], v[174:177], v[198:201], v[116:119]
	v_mfma_i32_16x16x64_i8 v[108:111], v[166:169], v[206:209], v[108:111]
	v_mfma_i32_16x16x64_i8 v[100:103], v[174:177], v[206:209], v[100:103]
	v_mfma_i32_16x16x64_i8 v[92:95], v[166:169], v[218:221], v[92:95]
	v_mfma_i32_16x16x64_i8 v[84:87], v[174:177], v[218:221], v[84:87]
	v_mfma_i32_16x16x64_i8 v[76:79], v[166:169], v[226:229], v[76:79]
	v_mfma_i32_16x16x64_i8 v[68:71], v[174:177], v[226:229], v[68:71]
	v_mfma_i32_16x16x64_i8 v[124:127], v[170:173], v[202:205], v[124:127]
	v_mfma_i32_16x16x64_i8 v[116:119], v[178:181], v[202:205], v[116:119]
	v_mfma_i32_16x16x64_i8 v[108:111], v[170:173], v[214:217], v[108:111]
	v_mfma_i32_16x16x64_i8 v[100:103], v[178:181], v[214:217], v[100:103]
	v_mfma_i32_16x16x64_i8 v[92:95], v[170:173], v[222:225], v[92:95]
	v_mfma_i32_16x16x64_i8 v[84:87], v[178:181], v[222:225], v[84:87]
	v_mfma_i32_16x16x64_i8 v[76:79], v[170:173], v[230:233], v[76:79]
	v_mfma_i32_16x16x64_i8 v[68:71], v[178:181], v[230:233], v[68:71]
	s_setprio 0
	s_setprio 1
	v_mfma_i32_16x16x64_i8 v[120:123], v[182:185], v[198:201], v[120:123]
	v_mfma_i32_16x16x64_i8 v[112:115], v[190:193], v[198:201], v[112:115]
	v_mfma_i32_16x16x64_i8 v[104:107], v[182:185], v[206:209], v[104:107]
	v_mfma_i32_16x16x64_i8 v[96:99], v[190:193], v[206:209], v[96:99]
	v_mfma_i32_16x16x64_i8 v[88:91], v[182:185], v[218:221], v[88:91]
	v_mfma_i32_16x16x64_i8 v[80:83], v[190:193], v[218:221], v[80:83]
	v_mfma_i32_16x16x64_i8 v[72:75], v[182:185], v[226:229], v[72:75]
	v_mfma_i32_16x16x64_i8 v[64:67], v[190:193], v[226:229], v[64:67]
	v_mfma_i32_16x16x64_i8 v[120:123], v[186:189], v[202:205], v[120:123]
	v_mfma_i32_16x16x64_i8 v[112:115], v[194:197], v[202:205], v[112:115]
	v_mfma_i32_16x16x64_i8 v[104:107], v[186:189], v[214:217], v[104:107]
	v_mfma_i32_16x16x64_i8 v[96:99], v[194:197], v[214:217], v[96:99]
	v_mfma_i32_16x16x64_i8 v[88:91], v[186:189], v[222:225], v[88:91]
	v_mfma_i32_16x16x64_i8 v[80:83], v[194:197], v[222:225], v[80:83]
	v_mfma_i32_16x16x64_i8 v[72:75], v[186:189], v[230:233], v[72:75]
	v_mfma_i32_16x16x64_i8 v[64:67], v[194:197], v[230:233], v[64:67]
	s_setprio 0
	s_barrier
	s_add_i32 s33, s33, s56
	v_lshl_add_u64 v[210:211], v[210:211], 0, s[10:11]
	s_mov_b32 m0, s33
	ds_read_b128 v[198:201], v153 offset:49152
	ds_read_b128 v[202:205], v153 offset:50176
	ds_read_b128 v[206:209], v153 offset:51200
	ds_read_b128 v[214:217], v153 offset:52224
	ds_read_b128 v[218:221], v153 offset:53248
	ds_read_b128 v[222:225], v153 offset:54272
	ds_read_b128 v[226:229], v153 offset:55296
	ds_read_b128 v[230:233], v153 offset:56320
	global_load_lds_dwordx4 v[210:211], off
	s_add_i32 m0, s33, 0x2000
	s_add_u32 s52, s52, 0x40080
	v_lshl_add_u64 v[210:211], v[234:235], 0, s[10:11]
	s_addc_u32 s53, s53, 0
	s_add_i32 s33, s75, s56
	global_load_lds_dwordx4 v[210:211], off
	v_lshl_add_u64 v[210:211], s[52:53], 0, v[132:133]
	s_mov_b32 m0, s33
	s_nop 0
	global_load_lds_dwordx4 v[210:211], off
	v_lshl_add_u64 v[210:211], s[52:53], 0, v[128:129]
	s_add_i32 m0, s33, 0x2000
	s_nop 0
	global_load_lds_dwordx4 v[210:211], off
	v_lshl_add_u64 v[210:211], v[236:237], 0, s[10:11]
	s_mov_b32 m0, s64
	s_nop 0
	global_load_lds_dwordx4 v[210:211], off
	v_lshl_add_u64 v[210:211], v[238:239], 0, s[10:11]
	s_mov_b32 m0, s65
	s_nop 0
	global_load_lds_dwordx4 v[210:211], off
	s_waitcnt vmcnt(8)
	s_waitcnt lgkmcnt(0)
	s_barrier
	s_cmp_eq_u32 s74, 12
	s_cbranch_scc1 .Lp1_cm_load
; #define PG8_STAGE(bufoff, gbase, voff) do { _Pragma("unroll") for (int _i = 0; _i < 2; ++_i) \
;         __builtin_amdgcn_global_load_lds((const unsigned*)((const char*)(gbase) + (voff)[_i]), (PG8_LAS unsigned*)(lds + (bufoff) + ldsw + _i * 8192), 16, 0, 0); } while (0)
; #define PG8_WAIT_V(n) asm volatile("s_waitcnt vmcnt(" #n ")" ::: "memory")
; #define PG8_WAIT_L(n) asm volatile("s_waitcnt lgkmcnt(" #n ")" ::: "memory")
; #define PG8_BAR __builtin_amdgcn_s_barrier()
; #define PG8_SCHED __builtin_amdgcn_sched_barrier(0)
;     ...
;         for (int t = 0; t < nt; t += 2) {
;             const bool last = (t == nt - 2);
;             const char* a1 = cA + (size_t)(t + 1) * kstep;
;             const char* a2 = last ? nA : cA + (size_t)(t + 2) * kstep; const char* b2 = last ? nB : cB + (size_t)(t + 2) * kstep;
;             const char* a3 = a2 + kstep; const char* b3 = b2 + kstep;
;             if (last && has_next) S.a_ready(nxt);
;             if (last) E.pre(pre, cur, wr, fr);
;             if constexpr (MIDK > 0) { if (t == MIDK / BK) E.mid(acc, cur, wr, wc, fr, fq); }
;             if constexpr (SP2) {
;             PG8_LDB(B0, 0, 0); PG8_LDB(B1, 0, 1); PG8_SCHED; PG8_LDA(At, 0, 0); PG8_STAGE(PG8_SA(1, 1), a1 + hstep, voffA);
;             PG8_WAIT_V(8); PG8_WAIT_L(0); PG8_BAR; PG8_MMA(0, 0, At, B0); PG8_MMA(0, 1, At, B1); PG8_BAR; PG8_SCHED;
;             PG8_LDA(At, 0, 1); PG8_STAGE(PG8_SB(0, 0), b2, voffB); PG8_STAGE(PG8_SB(0, 1), b2 + hstep, voffB); PG8_STAGE(PG8_SA(0, 0), a2, voffA);
;             PG8_WAIT_V(8); PG8_WAIT_L(0); PG8_BAR; PG8_MMA(1, 0, At, B0); PG8_MMA(1, 1, At, B1); PG8_BAR; PG8_SCHED;
;             PG8_LDB(B0, 1, 0); PG8_LDB(B1, 1, 1); PG8_SCHED; PG8_LDA(At, 1, 0); PG8_STAGE(PG8_SA(0, 1), a2 + hstep, voffA);
;             PG8_WAIT_V(8); PG8_WAIT_L(0); PG8_BAR; PG8_MMA(0, 0, At, B0); PG8_MMA(0, 1, At, B1); PG8_BAR; PG8_SCHED;
;             PG8_LDA(At, 1, 1); PG8_STAGE(PG8_SB(1, 0), b3, voffB); PG8_STAGE(PG8_SB(1, 1), b3 + hstep, voffB); PG8_STAGE(PG8_SA(1, 0), a3, voffA);
;             PG8_WAIT_V(8); PG8_WAIT_L(0); PG8_BAR; PG8_MMA(1, 0, At, B0); PG8_MMA(1, 1, At, B1); PG8_BAR; PG8_SCHED;
.Lp1_cm_back:
	s_setprio 1
	s_waitcnt lgkmcnt(0)
	v_mfma_i32_16x16x64_i8 v[60:63], v[166:169], v[198:201], v[60:63]
	v_mfma_i32_16x16x64_i8 v[52:55], v[174:177], v[198:201], v[52:55]
	v_mfma_i32_16x16x64_i8 v[44:47], v[166:169], v[206:209], v[44:47]
	v_mfma_i32_16x16x64_i8 v[36:39], v[174:177], v[206:209], v[36:39]
	v_mfma_i32_16x16x64_i8 v[28:31], v[166:169], v[218:221], v[28:31]
	v_mfma_i32_16x16x64_i8 v[20:23], v[174:177], v[218:221], v[20:23]
	v_mfma_i32_16x16x64_i8 v[12:15], v[166:169], v[226:229], v[12:15]
	v_mfma_i32_16x16x64_i8 v[4:7], v[174:177], v[226:229], v[4:7]
	v_mfma_i32_16x16x64_i8 v[60:63], v[170:173], v[202:205], v[60:63]
	v_mfma_i32_16x16x64_i8 v[52:55], v[178:181], v[202:205], v[52:55]
	v_mfma_i32_16x16x64_i8 v[44:47], v[170:173], v[214:217], v[44:47]
	v_mfma_i32_16x16x64_i8 v[36:39], v[178:181], v[214:217], v[36:39]
	v_mfma_i32_16x16x64_i8 v[28:31], v[170:173], v[222:225], v[28:31]
	v_mfma_i32_16x16x64_i8 v[20:23], v[178:181], v[222:225], v[20:23]
	v_mfma_i32_16x16x64_i8 v[12:15], v[170:173], v[230:233], v[12:15]
	v_mfma_i32_16x16x64_i8 v[4:7], v[178:181], v[230:233], v[4:7]
	s_setprio 0
	s_setprio 1
	v_mfma_i32_16x16x64_i8 v[56:59], v[182:185], v[198:201], v[56:59]
	v_mfma_i32_16x16x64_i8 v[48:51], v[190:193], v[198:201], v[48:51]
	v_mfma_i32_16x16x64_i8 v[40:43], v[182:185], v[206:209], v[40:43]
	v_mfma_i32_16x16x64_i8 v[32:35], v[190:193], v[206:209], v[32:35]
	v_mfma_i32_16x16x64_i8 v[24:27], v[182:185], v[218:221], v[24:27]
	v_mfma_i32_16x16x64_i8 v[16:19], v[190:193], v[218:221], v[16:19]
	v_mfma_i32_16x16x64_i8 v[8:11], v[182:185], v[226:229], v[8:11]
	v_mfma_i32_16x16x64_i8 v[0:3], v[190:193], v[226:229], v[0:3]
	v_mfma_i32_16x16x64_i8 v[56:59], v[186:189], v[202:205], v[56:59]
	v_mfma_i32_16x16x64_i8 v[48:51], v[194:197], v[202:205], v[48:51]
	v_mfma_i32_16x16x64_i8 v[40:43], v[186:189], v[214:217], v[40:43]
	v_mfma_i32_16x16x64_i8 v[32:35], v[194:197], v[214:217], v[32:35]
	v_mfma_i32_16x16x64_i8 v[24:27], v[186:189], v[222:225], v[24:27]
	v_mfma_i32_16x16x64_i8 v[16:19], v[194:197], v[222:225], v[16:19]
	v_mfma_i32_16x16x64_i8 v[8:11], v[186:189], v[230:233], v[8:11]
	v_mfma_i32_16x16x64_i8 v[0:3], v[194:197], v[230:233], v[0:3]
	s_setprio 0
	s_barrier
	s_add_i32 s74, s74, 2
	s_add_u32 s50, s50, 0x100
	s_addc_u32 s51, s51, 0
	s_add_u32 s72, s72, 0x100
	s_addc_u32 s73, s73, 0
	s_cmp_gt_u32 s74, 13
	s_cbranch_scc1 .LBB0_251

; __device__ __forceinline__ unsigned pack4_fp8(const f32x4 v) { int w = __builtin_amdgcn_cvt_pk_fp8_f32(clamp448(v[0]), clamp448(v[1]), 0, false); w = __builtin_amdgcn_cvt_pk_fp8_f32(clamp448(v[2]), clamp448(v[3]), w, true); return (unsigned)w; }
; __device__ __forceinline__ float silu_f(float g) { return g * fast_rcp(1.0f + fast_exp(-g)); }
;     __device__ __forceinline__ void operator()(const f32x4 (&acc)[2][2][4][2], const Unit& u, int wr, int wc, int fr, int fq, const float (&pr)[8]) const {
;         const int row0 = u.pm * BM + wr * 64 + fr, col0 = u.pn * 128 + wc * 32 + 8 * fq;
;         f32x4 csg[2], csu[2];
;         if constexpr (I8IN) {
; #pragma unroll
;             for (int n = 0; n < 2; ++n) { const u32x4 a = *(const u32x4*)(colmax + u.pn * BM + wc * 32 + 8 * fq + 4 * n), b = *(const u32x4*)(colmax + u.pn * BM + HALF + wc * 32 + 8 * fq + 4 * n);
;                 csg[n] = (f32x4){__uint_as_float(a.x), __uint_as_float(a.y), __uint_as_float(a.z), __uint_as_float(a.w)} * (1.0f / 127.0f);
;                 csu[n] = (f32x4){__uint_as_float(b.x), __uint_as_float(b.y), __uint_as_float(b.z), __uint_as_float(b.w)} * (1.0f / 127.0f); }
;         }
; #pragma unroll
;         for (int ai = 0; ai < 2; ++ai)
; #pragma unroll
;             for (int m = 0; m < 4; ++m) { const int row = row0 + ai * HALF + m * 16; const float s = pr[ai * 4 + m];
;                 f32x4 h[2];
; #pragma unroll
;                 for (int n = 0; n < 2; ++n) { f32x4 g, uu;
;                     if constexpr (I8IN) { const i32x4 gi = __builtin_bit_cast(i32x4, acc[ai][0][m][n]), ui = __builtin_bit_cast(i32x4, acc[ai][1][m][n]);
;                         g = (f32x4){(float)gi[0], (float)gi[1], (float)gi[2], (float)gi[3]} * (csg[n] * s); uu = (f32x4){(float)ui[0], (float)ui[1], (float)ui[2], (float)ui[3]} * (csu[n] * s); }
;                     else { g = acc[ai][0][m][n] * s; uu = acc[ai][1][m][n] * s; }
; #pragma unroll
;                     for (int j = 0; j < 4; ++j) h[n][j] = silu_f(g[j]) * uu[j]; }
;                 if constexpr (F8OUT) { u32x2 w; w.x = pack4_fp8(h[0] * hscale); w.y = pack4_fp8(h[1] * hscale); *(u32x2*)((unsigned char*)H + (size_t)row * ldh + col0) = w; }
;                 else *(u32x4*)(H + (size_t)row * ldh + col0) = pack8(h[0], h[1]); }
.LBB0_253:
	s_lshl_b32 s34, s71, 8
	s_ashr_i32 s35, s34, 31
	v_cvt_f32_i32_e32 v187, v126
	v_cvt_f32_i32_e32 v127, v127
	v_cvt_f32_i32_e32 v126, v123
	v_cvt_f32_i32_e32 v182, v120
	v_cvt_f32_i32_e32 v184, v121
	v_cvt_f32_i32_e32 v190, v114
	v_cvt_f32_i32_e32 v192, v115
	v_cvt_f32_i32_e32 v185, v125
	v_cvt_f32_i32_e32 v186, v122
	v_cvt_f32_i32_e32 v122, v112
	v_cvt_f32_i32_e32 v188, v113
	v_cvt_f32_i32_e32 v123, v116
	v_cvt_f32_i32_e32 v191, v118
	v_cvt_f32_i32_e32 v183, v124
	v_cvt_f32_i32_e32 v189, v117
	v_cvt_f32_i32_e32 v193, v119
	v_cvt_f32_i32_e32 v109, v109
	v_lshl_or_b32 v180, s71, 7, v151
	v_ashrrev_i32_e32 v181, 31, v180
	v_cvt_f32_i32_e32 v111, v111
	v_cvt_f32_i32_e32 v101, v101
	v_cvt_f32_i32_e32 v103, v103
	v_cvt_f32_i32_e32 v93, v93
	v_cvt_f32_i32_e32 v95, v95
	v_cvt_f32_i32_e32 v85, v85
	v_cvt_f32_i32_e32 v87, v87
	v_cvt_f32_i32_e32 v77, v77
	v_cvt_f32_i32_e32 v79, v79
	v_cvt_f32_i32_e32 v69, v69
	v_cvt_f32_i32_e32 v71, v71
	v_cvt_f32_i32_e32 v61, v61
	v_cvt_f32_i32_e32 v63, v63
	v_cvt_f32_i32_e32 v53, v53
	v_cvt_f32_i32_e32 v55, v55
	v_cvt_f32_i32_e32 v45, v45
	v_cvt_f32_i32_e32 v47, v47
	v_cvt_f32_i32_e32 v37, v37
	v_cvt_f32_i32_e32 v39, v39
	v_cvt_f32_i32_e32 v29, v29
	v_cvt_f32_i32_e32 v31, v31
	v_cvt_f32_i32_e32 v21, v21
	v_cvt_f32_i32_e32 v23, v23
	v_cvt_f32_i32_e32 v13, v13
	v_cvt_f32_i32_e32 v15, v15
	v_cvt_f32_i32_e32 v5, v5
	v_cvt_f32_i32_e32 v7, v7
	s_andn2_b64 vcc, exec, s[4:5]
	s_mov_b64 s[4:5], -1
	s_waitcnt vmcnt(0)
	v_mov_b64_e32 v[164:165], v[242:243]
	v_mov_b64_e32 v[166:167], v[244:245]
	v_mov_b64_e32 v[168:169], v[246:247]
	v_mov_b64_e32 v[170:171], v[248:249]
	v_mov_b64_e32 v[172:173], v[250:251]
	v_mov_b64_e32 v[174:175], v[252:253]
	v_mov_b32_e32 v176, v157
	v_mov_b32_e32 v177, v159
	v_mov_b32_e32 v178, v161
	v_mov_b32_e32 v179, v163
	v_pk_mul_f32 v[120:121], v[166:167], s[16:17] op_sel_hi:[1,0]
	v_pk_mul_f32 v[114:115], v[170:171], s[16:17] op_sel_hi:[1,0]
	v_mov_b32_e32 v125, v120
	v_mov_b32_e32 v120, v115
	v_pk_mul_f32 v[112:113], v[174:175], s[16:17] op_sel_hi:[1,0]
	v_pk_mul_f32 v[174:175], v[146:147], v[120:121] op_sel_hi:[0,1]
	v_pk_mul_f32 v[126:127], v[174:175], v[126:127]
	v_pk_mul_f32 v[164:165], v[164:165], s[16:17] op_sel_hi:[1,0]
	v_mul_f32_e32 v161, 0xbfb8aa3b, v127
	v_exp_f32_e32 v161, v161
	v_pk_mul_f32 v[118:119], v[168:169], s[16:17] op_sel_hi:[1,0]
	v_pk_mul_f32 v[116:117], v[172:173], s[16:17] op_sel_hi:[1,0]
	v_pk_mul_f32 v[168:169], v[178:179], s[16:17] op_sel_hi:[1,0]
	v_pk_mul_f32 v[170:171], v[176:177], s[16:17] op_sel_hi:[1,0]
	v_mov_b32_e32 v166, v118
	v_mov_b32_e32 v167, v164
	v_mov_b32_e32 v164, v119
	v_mov_b32_e32 v124, v114
	v_mov_b32_e32 v118, v170
	v_mov_b32_e32 v119, v116
	v_mov_b32_e32 v114, v168
	v_mov_b32_e32 v115, v112
	v_mov_b32_e32 v116, v171
	v_mov_b32_e32 v112, v169
	v_pk_mul_f32 v[176:177], v[146:147], v[118:119] op_sel_hi:[0,1]
	v_pk_mul_f32 v[194:195], v[146:147], v[114:115] op_sel_hi:[0,1]
	v_pk_mul_f32 v[168:169], v[146:147], v[166:167] op_sel_hi:[0,1]
	v_pk_mul_f32 v[170:171], v[146:147], v[164:165] op_sel_hi:[0,1]
	v_pk_mul_f32 v[172:173], v[146:147], v[124:125] op_sel_hi:[0,1]
	v_pk_mul_f32 v[178:179], v[146:147], v[116:117] op_sel_hi:[0,1]
	v_pk_mul_f32 v[196:197], v[146:147], v[112:113] op_sel_hi:[0,1]
	v_pk_mul_f32 v[122:123], v[176:177], v[122:123]
	v_pk_mul_f32 v[176:177], v[194:195], v[190:191]
	v_add_f32_e32 v161, 1.0, v161
	v_pk_mul_f32 v[168:169], v[168:169], v[182:183]
	v_pk_mul_f32 v[170:171], v[170:171], v[184:185]
	v_pk_mul_f32 v[172:173], v[172:173], v[186:187]
	v_pk_mul_f32 v[174:175], v[178:179], v[188:189]
	v_pk_mul_f32 v[178:179], v[196:197], v[192:193]
	v_mul_f32_e32 v163, 0xbfb8aa3b, v123
	v_mul_f32_e32 v183, 0xbfb8aa3b, v177
	v_rcp_f32_e32 v161, v161
	v_mul_f32_e32 v155, 0xbfb8aa3b, v169
	v_mul_f32_e32 v157, 0xbfb8aa3b, v171
	v_mul_f32_e32 v159, 0xbfb8aa3b, v173
	v_mul_f32_e32 v182, 0xbfb8aa3b, v175
	v_mul_f32_e32 v184, 0xbfb8aa3b, v179
	v_exp_f32_e32 v163, v163
	v_exp_f32_e32 v183, v183
	v_exp_f32_e32 v155, v155
	v_exp_f32_e32 v157, v157
	v_exp_f32_e32 v159, v159
	v_exp_f32_e32 v182, v182
	v_exp_f32_e32 v184, v184
	v_mul_f32_e32 v127, v127, v161
	v_add_f32_e32 v163, 1.0, v163
	v_mul_f32_e32 v126, v126, v127
	v_add_f32_e32 v127, 1.0, v183
	v_add_f32_e32 v155, 1.0, v155
	v_add_f32_e32 v157, 1.0, v157
	v_add_f32_e32 v159, 1.0, v159
	v_add_f32_e32 v182, 1.0, v182
	v_rcp_f32_e32 v163, v163
	v_rcp_f32_e32 v127, v127
	v_add_f32_e32 v161, 1.0, v184
	v_rcp_f32_e32 v155, v155
	v_rcp_f32_e32 v157, v157
	v_rcp_f32_e32 v159, v159
	v_rcp_f32_e32 v182, v182
	v_rcp_f32_e32 v161, v161
	v_mul_f32_e32 v123, v123, v163
	v_mul_f32_e32 v127, v177, v127
	v_mul_f32_e32 v155, v169, v155
	v_mul_f32_e32 v157, v171, v157
	v_mul_f32_e32 v159, v173, v159
	v_mul_f32_e32 v122, v122, v123
	v_mul_f32_e32 v123, v175, v182
	v_mul_f32_e32 v127, v176, v127
	v_mul_f32_e32 v161, v179, v161
	v_mul_f32_e32 v155, v168, v155
	v_mul_f32_e32 v157, v170, v157
	v_mul_f32_e32 v159, v172, v159
	v_mul_f32_e32 v123, v174, v123
	v_mul_f32_e32 v161, v178, v161
	v_cvt_pk_bf16_f32 v168, v155, v157
	v_cvt_pk_bf16_f32 v169, v159, v126
	v_cvt_pk_bf16_f32 v170, v122, v123
	v_cvt_pk_bf16_f32 v171, v127, v161
	v_cvt_f32_i32_e32 v127, v108
	v_cvt_f32_i32_e32 v126, v104
	v_pk_mul_f32 v[174:175], v[148:149], v[166:167] op_sel_hi:[0,1]
	v_cvt_f32_i32_e32 v108, v105
	v_mov_b64_e32 v[122:123], s[14:15]
	v_pk_mul_f32 v[174:175], v[174:175], v[126:127]
	v_mad_i64_i32 v[172:173], s[34:35], v162, s70, v[122:123]
	v_mul_f32_e32 v104, 0xbfb8aa3b, v175
	v_exp_f32_e32 v104, v104
	v_lshlrev_b64 v[126:127], 1, v[180:181]
	v_add_f32_e32 v104, 1.0, v104
	v_rcp_f32_e32 v155, v104
; __device__ __forceinline__ unsigned pack4_fp8(const f32x4 v) { int w = __builtin_amdgcn_cvt_pk_fp8_f32(clamp448(v[0]), clamp448(v[1]), 0, false); w = __builtin_amdgcn_cvt_pk_fp8_f32(clamp448(v[2]), clamp448(v[3]), w, true); return (unsigned)w; }
; __device__ __forceinline__ float silu_f(float g) { return g * fast_rcp(1.0f + fast_exp(-g)); }
; __device__ __forceinline__ u32x4 pack8(const f32x4 a, const f32x4 b) { u32x4 w; w.x = cvt_pk_bf16(a[0], a[1]); w.y = cvt_pk_bf16(a[2], a[3]); w.z = cvt_pk_bf16(b[0], b[1]); w.w = cvt_pk_bf16(b[2], b[3]); return w; }
;     __device__ __forceinline__ void operator()(const f32x4 (&acc)[2][2][4][2], const Unit& u, int wr, int wc, int fr, int fq, const float (&pr)[8]) const {
;     ...
; #pragma unroll
;         for (int ai = 0; ai < 2; ++ai)
; #pragma unroll
;             for (int m = 0; m < 4; ++m) { const int row = row0 + ai * HALF + m * 16; const float s = pr[ai * 4 + m];
;                 f32x4 h[2];
; #pragma unroll
;                 for (int n = 0; n < 2; ++n) { f32x4 g, uu;
;                     if constexpr (I8IN) { const i32x4 gi = __builtin_bit_cast(i32x4, acc[ai][0][m][n]), ui = __builtin_bit_cast(i32x4, acc[ai][1][m][n]);
;                         g = (f32x4){(float)gi[0], (float)gi[1], (float)gi[2], (float)gi[3]} * (csg[n] * s); uu = (f32x4){(float)ui[0], (float)ui[1], (float)ui[2], (float)ui[3]} * (csu[n] * s); }
;                     else { g = acc[ai][0][m][n] * s; uu = acc[ai][1][m][n] * s; }
; #pragma unroll
;                     for (int j = 0; j < 4; ++j) h[n][j] = silu_f(g[j]) * uu[j]; }
;                 if constexpr (F8OUT) { u32x2 w; w.x = pack4_fp8(h[0] * hscale); w.y = pack4_fp8(h[1] * hscale); *(u32x2*)((unsigned char*)H + (size_t)row * ldh + col0) = w; }
;                 else *(u32x4*)(H + (size_t)row * ldh + col0) = pack8(h[0], h[1]); }
	v_pk_mul_f32 v[104:105], v[148:149], v[164:165] op_sel_hi:[0,1]
	v_pk_mul_f32 v[104:105], v[104:105], v[108:109]
	v_mul_f32_e32 v155, v175, v155
	v_mul_f32_e32 v108, 0xbfb8aa3b, v105
	v_exp_f32_e32 v157, v108
	v_lshl_add_u64 v[108:109], v[172:173], 0, v[126:127]
	global_store_dwordx4 v[108:109], v[168:171], off
	v_cvt_f32_i32_e32 v109, v110
	v_add_f32_e32 v108, 1.0, v157
	v_rcp_f32_e32 v157, v108
	v_cvt_f32_i32_e32 v108, v106
	v_pk_mul_f32 v[168:169], v[148:149], v[124:125] op_sel_hi:[0,1]
	v_cvt_f32_i32_e32 v110, v107
	v_mul_f32_e32 v105, v105, v157
	v_pk_mul_f32 v[108:109], v[168:169], v[108:109]
	v_mul_f32_e32 v157, v104, v105
	v_mul_f32_e32 v106, 0xbfb8aa3b, v109
	v_exp_f32_e32 v106, v106
	v_pk_mul_f32 v[104:105], v[148:149], v[120:121] op_sel_hi:[0,1]
	v_pk_mul_f32 v[104:105], v[104:105], v[110:111]
	v_mul_f32_e32 v155, v174, v155
	v_mul_f32_e32 v107, 0xbfb8aa3b, v105
	v_add_f32_e32 v106, 1.0, v106
	v_exp_f32_e32 v110, v107
	v_rcp_f32_e32 v159, v106
	v_cvt_f32_i32_e32 v107, v100
	v_cvt_f32_i32_e32 v106, v96
	v_add_f32_e32 v96, 1.0, v110
	v_pk_mul_f32 v[110:111], v[148:149], v[118:119] op_sel_hi:[0,1]
	v_rcp_f32_e32 v96, v96
	v_pk_mul_f32 v[106:107], v[110:111], v[106:107]
	v_mul_f32_e32 v109, v109, v159
	v_mul_f32_e32 v100, 0xbfb8aa3b, v107
	v_exp_f32_e32 v100, v100
	v_mul_f32_e32 v96, v105, v96
	v_mul_f32_e32 v108, v108, v109
	v_mul_f32_e32 v109, v104, v96
	v_add_f32_e32 v100, 1.0, v100
	v_rcp_f32_e32 v105, v100
	v_cvt_f32_i32_e32 v100, v97
	v_pk_mul_f32 v[96:97], v[148:149], v[116:117] op_sel_hi:[0,1]
	v_mul_f32_e32 v104, v107, v105
	v_pk_mul_f32 v[96:97], v[96:97], v[100:101]
	v_cvt_f32_i32_e32 v101, v102
	v_mul_f32_e32 v100, 0xbfb8aa3b, v97
	v_exp_f32_e32 v105, v100
	v_cvt_f32_i32_e32 v100, v98
	v_mul_f32_e32 v106, v106, v104
	v_cvt_f32_i32_e32 v102, v99
	v_add_f32_e32 v98, 1.0, v105
	v_pk_mul_f32 v[104:105], v[148:149], v[114:115] op_sel_hi:[0,1]
	v_pk_mul_f32 v[100:101], v[104:105], v[100:101]
	v_rcp_f32_e32 v107, v98
	v_mul_f32_e32 v98, 0xbfb8aa3b, v101
	v_exp_f32_e32 v104, v98
	v_pk_mul_f32 v[98:99], v[148:149], v[112:113] op_sel_hi:[0,1]
	v_pk_mul_f32 v[98:99], v[98:99], v[102:103]
	v_mul_f32_e32 v97, v97, v107
	v_mul_f32_e32 v102, 0xbfb8aa3b, v99
	v_exp_f32_e32 v102, v102
	v_add_f32_e32 v103, 1.0, v104
	v_rcp_f32_e32 v103, v103
	v_mul_f32_e32 v104, v96, v97
	v_add_f32_e32 v102, 1.0, v102
	v_rcp_f32_e32 v102, v102
	v_mul_f32_e32 v96, v101, v103
	v_mul_f32_e32 v103, v100, v96
	v_cvt_f32_i32_e32 v101, v92
	v_cvt_f32_i32_e32 v100, v88
	v_mul_f32_e32 v96, v99, v102
	v_mul_f32_e32 v99, v98, v96
	v_cvt_pk_bf16_f32 v96, v155, v157
	v_cvt_pk_bf16_f32 v97, v108, v109
	v_cvt_pk_bf16_f32 v98, v106, v104
	v_cvt_pk_bf16_f32 v99, v103, v99
	v_pk_mul_f32 v[102:103], v[150:151], v[166:167] op_sel_hi:[0,1]
	v_pk_mul_f32 v[100:101], v[102:103], v[100:101]
	v_cvt_f32_i32_e32 v92, v89
	v_mul_f32_e32 v88, 0xbfb8aa3b, v101
	v_exp_f32_e32 v88, v88
	v_or_b32_e32 v105, 16, v162
	v_mad_i64_i32 v[102:103], s[34:35], v105, s70, v[122:123]
	v_add_f32_e32 v88, 1.0, v88
	v_rcp_f32_e32 v104, v88
	v_pk_mul_f32 v[88:89], v[150:151], v[164:165] op_sel_hi:[0,1]
	v_pk_mul_f32 v[88:89], v[88:89], v[92:93]
	s_nop 0
	v_mul_f32_e32 v92, 0xbfb8aa3b, v89
	v_exp_f32_e32 v105, v92
	v_lshl_add_u64 v[92:93], v[102:103], 0, v[126:127]
	global_store_dwordx4 v[92:93], v[96:99], off
	v_cvt_f32_i32_e32 v93, v94
	v_add_f32_e32 v92, 1.0, v105
	v_rcp_f32_e32 v97, v92
	v_cvt_f32_i32_e32 v92, v90
	v_mul_f32_e32 v96, v101, v104
	v_mul_f32_e32 v98, v100, v96
	v_mul_f32_e32 v89, v89, v97
	v_pk_mul_f32 v[96:97], v[150:151], v[124:125] op_sel_hi:[0,1]
	v_pk_mul_f32 v[92:93], v[96:97], v[92:93]
	v_cvt_f32_i32_e32 v94, v91
	v_mul_f32_e32 v90, 0xbfb8aa3b, v93
	v_exp_f32_e32 v90, v90
	v_mul_f32_e32 v96, v88, v89
	v_pk_mul_f32 v[88:89], v[150:151], v[120:121] op_sel_hi:[0,1]
	v_pk_mul_f32 v[88:89], v[88:89], v[94:95]
	v_add_f32_e32 v90, 1.0, v90
	v_mul_f32_e32 v91, 0xbfb8aa3b, v89
	v_exp_f32_e32 v94, v91
	v_rcp_f32_e32 v97, v90
	v_cvt_f32_i32_e32 v91, v84
	v_cvt_f32_i32_e32 v90, v80
	v_add_f32_e32 v80, 1.0, v94
	v_pk_mul_f32 v[94:95], v[150:151], v[118:119] op_sel_hi:[0,1]
	v_rcp_f32_e32 v80, v80
	v_pk_mul_f32 v[90:91], v[94:95], v[90:91]
	v_mul_f32_e32 v93, v93, v97
	v_mul_f32_e32 v84, 0xbfb8aa3b, v91
	v_exp_f32_e32 v84, v84
	v_mul_f32_e32 v80, v89, v80
	v_mul_f32_e32 v92, v92, v93
	v_mul_f32_e32 v93, v88, v80
	v_add_f32_e32 v84, 1.0, v84
	v_rcp_f32_e32 v89, v84
	v_cvt_f32_i32_e32 v84, v81
	v_pk_mul_f32 v[80:81], v[150:151], v[116:117] op_sel_hi:[0,1]
	v_mul_f32_e32 v88, v91, v89
	v_pk_mul_f32 v[80:81], v[80:81], v[84:85]
	v_cvt_f32_i32_e32 v85, v86
	v_mul_f32_e32 v84, 0xbfb8aa3b, v81
	v_exp_f32_e32 v89, v84
	v_cvt_f32_i32_e32 v84, v82
	v_mul_f32_e32 v90, v90, v88
	v_cvt_f32_i32_e32 v86, v83
	v_add_f32_e32 v82, 1.0, v89
	v_pk_mul_f32 v[88:89], v[150:151], v[114:115] op_sel_hi:[0,1]
	v_pk_mul_f32 v[84:85], v[88:89], v[84:85]
	v_rcp_f32_e32 v91, v82
	v_mul_f32_e32 v82, 0xbfb8aa3b, v85
	v_exp_f32_e32 v88, v82
	v_pk_mul_f32 v[82:83], v[150:151], v[112:113] op_sel_hi:[0,1]
	v_pk_mul_f32 v[82:83], v[82:83], v[86:87]
	v_mul_f32_e32 v81, v81, v91
	v_mul_f32_e32 v86, 0xbfb8aa3b, v83
	v_exp_f32_e32 v86, v86
	v_add_f32_e32 v87, 1.0, v88
	v_rcp_f32_e32 v87, v87
	v_mul_f32_e32 v88, v80, v81
	v_add_f32_e32 v86, 1.0, v86
	v_rcp_f32_e32 v86, v86
	v_mul_f32_e32 v80, v85, v87
	v_mul_f32_e32 v87, v84, v80
	v_cvt_f32_i32_e32 v85, v76
	v_cvt_f32_i32_e32 v84, v72
	v_mul_f32_e32 v80, v83, v86
	v_mul_f32_e32 v83, v82, v80
	v_cvt_pk_bf16_f32 v80, v98, v96
	v_cvt_pk_bf16_f32 v81, v92, v93
	v_cvt_pk_bf16_f32 v82, v90, v88
	v_cvt_pk_bf16_f32 v83, v87, v83
	v_pk_mul_f32 v[86:87], v[152:153], v[166:167] op_sel_hi:[0,1]
; __device__ __forceinline__ unsigned pack4_fp8(const f32x4 v) { int w = __builtin_amdgcn_cvt_pk_fp8_f32(clamp448(v[0]), clamp448(v[1]), 0, false); w = __builtin_amdgcn_cvt_pk_fp8_f32(clamp448(v[2]), clamp448(v[3]), w, true); return (unsigned)w; }
; __device__ __forceinline__ float silu_f(float g) { return g * fast_rcp(1.0f + fast_exp(-g)); }
; __device__ __forceinline__ u32x4 pack8(const f32x4 a, const f32x4 b) { u32x4 w; w.x = cvt_pk_bf16(a[0], a[1]); w.y = cvt_pk_bf16(a[2], a[3]); w.z = cvt_pk_bf16(b[0], b[1]); w.w = cvt_pk_bf16(b[2], b[3]); return w; }
;     __device__ __forceinline__ void operator()(const f32x4 (&acc)[2][2][4][2], const Unit& u, int wr, int wc, int fr, int fq, const float (&pr)[8]) const {
;     ...
; #pragma unroll
;         for (int ai = 0; ai < 2; ++ai)
; #pragma unroll
;             for (int m = 0; m < 4; ++m) { const int row = row0 + ai * HALF + m * 16; const float s = pr[ai * 4 + m];
;                 f32x4 h[2];
; #pragma unroll
;                 for (int n = 0; n < 2; ++n) { f32x4 g, uu;
;                     if constexpr (I8IN) { const i32x4 gi = __builtin_bit_cast(i32x4, acc[ai][0][m][n]), ui = __builtin_bit_cast(i32x4, acc[ai][1][m][n]);
;                         g = (f32x4){(float)gi[0], (float)gi[1], (float)gi[2], (float)gi[3]} * (csg[n] * s); uu = (f32x4){(float)ui[0], (float)ui[1], (float)ui[2], (float)ui[3]} * (csu[n] * s); }
;                     else { g = acc[ai][0][m][n] * s; uu = acc[ai][1][m][n] * s; }
; #pragma unroll
;                     for (int j = 0; j < 4; ++j) h[n][j] = silu_f(g[j]) * uu[j]; }
;                 if constexpr (F8OUT) { u32x2 w; w.x = pack4_fp8(h[0] * hscale); w.y = pack4_fp8(h[1] * hscale); *(u32x2*)((unsigned char*)H + (size_t)row * ldh + col0) = w; }
;                 else *(u32x4*)(H + (size_t)row * ldh + col0) = pack8(h[0], h[1]); }
	v_pk_mul_f32 v[84:85], v[86:87], v[84:85]
	v_cvt_f32_i32_e32 v76, v73
	v_mul_f32_e32 v72, 0xbfb8aa3b, v85
	v_exp_f32_e32 v72, v72
	v_or_b32_e32 v89, 32, v162
	v_mad_i64_i32 v[86:87], s[34:35], v89, s70, v[122:123]
	v_add_f32_e32 v72, 1.0, v72
	v_rcp_f32_e32 v88, v72
	v_pk_mul_f32 v[72:73], v[152:153], v[164:165] op_sel_hi:[0,1]
	v_pk_mul_f32 v[72:73], v[72:73], v[76:77]
	s_nop 0
	v_mul_f32_e32 v76, 0xbfb8aa3b, v73
	v_exp_f32_e32 v89, v76
	v_lshl_add_u64 v[76:77], v[86:87], 0, v[126:127]
	global_store_dwordx4 v[76:77], v[80:83], off
	v_cvt_f32_i32_e32 v77, v78
	v_add_f32_e32 v76, 1.0, v89
	v_rcp_f32_e32 v81, v76
	v_cvt_f32_i32_e32 v76, v74
	v_mul_f32_e32 v80, v85, v88
	v_mul_f32_e32 v82, v84, v80
	v_mul_f32_e32 v73, v73, v81
	v_pk_mul_f32 v[80:81], v[152:153], v[124:125] op_sel_hi:[0,1]
	v_pk_mul_f32 v[76:77], v[80:81], v[76:77]
	v_cvt_f32_i32_e32 v78, v75
	v_mul_f32_e32 v74, 0xbfb8aa3b, v77
	v_exp_f32_e32 v74, v74
	v_mul_f32_e32 v80, v72, v73
	v_pk_mul_f32 v[72:73], v[152:153], v[120:121] op_sel_hi:[0,1]
	v_pk_mul_f32 v[72:73], v[72:73], v[78:79]
	v_add_f32_e32 v74, 1.0, v74
	v_mul_f32_e32 v75, 0xbfb8aa3b, v73
	v_exp_f32_e32 v78, v75
	v_rcp_f32_e32 v81, v74
	v_cvt_f32_i32_e32 v75, v68
	v_cvt_f32_i32_e32 v74, v64
	v_add_f32_e32 v64, 1.0, v78
	v_pk_mul_f32 v[78:79], v[152:153], v[118:119] op_sel_hi:[0,1]
	v_rcp_f32_e32 v64, v64
	v_pk_mul_f32 v[74:75], v[78:79], v[74:75]
	v_mul_f32_e32 v77, v77, v81
	v_mul_f32_e32 v68, 0xbfb8aa3b, v75
	v_exp_f32_e32 v68, v68
	v_mul_f32_e32 v64, v73, v64
	v_mul_f32_e32 v76, v76, v77
	v_mul_f32_e32 v77, v72, v64
	v_add_f32_e32 v68, 1.0, v68
	v_rcp_f32_e32 v73, v68
	v_cvt_f32_i32_e32 v68, v65
	v_pk_mul_f32 v[64:65], v[152:153], v[116:117] op_sel_hi:[0,1]
	v_mul_f32_e32 v72, v75, v73
	v_pk_mul_f32 v[64:65], v[64:65], v[68:69]
	v_cvt_f32_i32_e32 v69, v70
	v_mul_f32_e32 v68, 0xbfb8aa3b, v65
	v_exp_f32_e32 v73, v68
	v_cvt_f32_i32_e32 v68, v66
	v_mul_f32_e32 v74, v74, v72
	v_cvt_f32_i32_e32 v70, v67
	v_add_f32_e32 v66, 1.0, v73
	v_pk_mul_f32 v[72:73], v[152:153], v[114:115] op_sel_hi:[0,1]
	v_pk_mul_f32 v[68:69], v[72:73], v[68:69]
	v_rcp_f32_e32 v75, v66
	v_mul_f32_e32 v66, 0xbfb8aa3b, v69
	v_exp_f32_e32 v72, v66
	v_pk_mul_f32 v[66:67], v[152:153], v[112:113] op_sel_hi:[0,1]
	v_pk_mul_f32 v[66:67], v[66:67], v[70:71]
	v_mul_f32_e32 v65, v65, v75
	v_mul_f32_e32 v70, 0xbfb8aa3b, v67
	v_exp_f32_e32 v70, v70
	v_add_f32_e32 v71, 1.0, v72
	v_rcp_f32_e32 v71, v71
	v_mul_f32_e32 v72, v64, v65
	v_add_f32_e32 v70, 1.0, v70
	v_rcp_f32_e32 v70, v70
	v_mul_f32_e32 v64, v69, v71
	v_mul_f32_e32 v68, v68, v64
	v_cvt_f32_i32_e32 v69, v60
	v_mul_f32_e32 v64, v67, v70
	v_mul_f32_e32 v67, v66, v64
	v_cvt_pk_bf16_f32 v64, v82, v80
	v_cvt_pk_bf16_f32 v65, v76, v77
	v_cvt_pk_bf16_f32 v66, v74, v72
	v_cvt_pk_bf16_f32 v67, v68, v67
	v_cvt_f32_i32_e32 v68, v56
	v_pk_mul_f32 v[72:73], v[154:155], v[166:167] op_sel_hi:[0,1]
	v_cvt_f32_i32_e32 v60, v57
	v_or_b32_e32 v70, 48, v162
	v_pk_mul_f32 v[68:69], v[72:73], v[68:69]
	v_mad_i64_i32 v[70:71], s[34:35], v70, s70, v[122:123]
	v_mul_f32_e32 v56, 0xbfb8aa3b, v69
	v_exp_f32_e32 v56, v56
	v_lshl_add_u64 v[70:71], v[70:71], 0, v[126:127]
	global_store_dwordx4 v[70:71], v[64:67], off
	v_add_f32_e32 v56, 1.0, v56
	v_rcp_f32_e32 v72, v56
	v_pk_mul_f32 v[56:57], v[154:155], v[164:165] op_sel_hi:[0,1]
	v_pk_mul_f32 v[56:57], v[56:57], v[60:61]
	v_cvt_f32_i32_e32 v61, v62
	v_mul_f32_e32 v60, 0xbfb8aa3b, v57
	v_exp_f32_e32 v60, v60
	v_mul_f32_e32 v64, v69, v72
	v_mul_f32_e32 v67, v68, v64
	v_cvt_f32_i32_e32 v62, v59
	v_add_f32_e32 v60, 1.0, v60
	v_rcp_f32_e32 v65, v60
	v_cvt_f32_i32_e32 v60, v58
	v_add_u32_e32 v66, 0x80, v162
	v_mul_f32_e32 v57, v57, v65
	v_pk_mul_f32 v[64:65], v[154:155], v[124:125] op_sel_hi:[0,1]
	v_pk_mul_f32 v[60:61], v[64:65], v[60:61]
	v_mul_f32_e32 v64, v56, v57
	v_mul_f32_e32 v58, 0xbfb8aa3b, v61
	v_exp_f32_e32 v58, v58
	v_pk_mul_f32 v[56:57], v[154:155], v[120:121] op_sel_hi:[0,1]
	v_pk_mul_f32 v[56:57], v[56:57], v[62:63]
	v_add_f32_e32 v58, 1.0, v58
	v_mul_f32_e32 v59, 0xbfb8aa3b, v57
	v_exp_f32_e32 v62, v59
	v_rcp_f32_e32 v65, v58
	v_cvt_f32_i32_e32 v59, v52
	v_cvt_f32_i32_e32 v58, v48
	v_add_f32_e32 v48, 1.0, v62
	v_pk_mul_f32 v[62:63], v[154:155], v[118:119] op_sel_hi:[0,1]
	v_rcp_f32_e32 v48, v48
	v_pk_mul_f32 v[58:59], v[62:63], v[58:59]
	v_mul_f32_e32 v61, v61, v65
	v_mul_f32_e32 v52, 0xbfb8aa3b, v59
	v_exp_f32_e32 v52, v52
	v_mul_f32_e32 v48, v57, v48
	v_mul_f32_e32 v60, v60, v61
	v_mul_f32_e32 v61, v56, v48
	v_add_f32_e32 v52, 1.0, v52
	v_rcp_f32_e32 v57, v52
	v_cvt_f32_i32_e32 v52, v49
	v_pk_mul_f32 v[48:49], v[154:155], v[116:117] op_sel_hi:[0,1]
	v_mul_f32_e32 v56, v59, v57
	v_pk_mul_f32 v[48:49], v[48:49], v[52:53]
	v_cvt_f32_i32_e32 v53, v54
	v_mul_f32_e32 v52, 0xbfb8aa3b, v49
	v_exp_f32_e32 v57, v52
	v_cvt_f32_i32_e32 v52, v50
	v_mul_f32_e32 v58, v58, v56
	v_cvt_f32_i32_e32 v54, v51
	v_add_f32_e32 v50, 1.0, v57
	v_pk_mul_f32 v[56:57], v[154:155], v[114:115] op_sel_hi:[0,1]
	v_pk_mul_f32 v[52:53], v[56:57], v[52:53]
	v_rcp_f32_e32 v59, v50
	v_mul_f32_e32 v50, 0xbfb8aa3b, v53
	v_exp_f32_e32 v56, v50
	v_pk_mul_f32 v[50:51], v[154:155], v[112:113] op_sel_hi:[0,1]
	v_pk_mul_f32 v[50:51], v[50:51], v[54:55]
	v_mul_f32_e32 v49, v49, v59
	v_mul_f32_e32 v54, 0xbfb8aa3b, v51
	v_exp_f32_e32 v54, v54
	v_add_f32_e32 v55, 1.0, v56
	v_rcp_f32_e32 v55, v55
	v_mul_f32_e32 v56, v48, v49
	v_add_f32_e32 v54, 1.0, v54
	v_rcp_f32_e32 v54, v54
	v_mul_f32_e32 v48, v53, v55
	v_mul_f32_e32 v55, v52, v48
	v_cvt_f32_i32_e32 v53, v44
	v_cvt_f32_i32_e32 v52, v40
	v_mul_f32_e32 v48, v51, v54
	v_mul_f32_e32 v51, v50, v48
	v_cvt_pk_bf16_f32 v48, v67, v64
	v_cvt_pk_bf16_f32 v49, v60, v61
; __device__ __forceinline__ unsigned pack4_fp8(const f32x4 v) { int w = __builtin_amdgcn_cvt_pk_fp8_f32(clamp448(v[0]), clamp448(v[1]), 0, false); w = __builtin_amdgcn_cvt_pk_fp8_f32(clamp448(v[2]), clamp448(v[3]), w, true); return (unsigned)w; }
; __device__ __forceinline__ float silu_f(float g) { return g * fast_rcp(1.0f + fast_exp(-g)); }
; __device__ __forceinline__ u32x4 pack8(const f32x4 a, const f32x4 b) { u32x4 w; w.x = cvt_pk_bf16(a[0], a[1]); w.y = cvt_pk_bf16(a[2], a[3]); w.z = cvt_pk_bf16(b[0], b[1]); w.w = cvt_pk_bf16(b[2], b[3]); return w; }
;     __device__ __forceinline__ void operator()(const f32x4 (&acc)[2][2][4][2], const Unit& u, int wr, int wc, int fr, int fq, const float (&pr)[8]) const {
;     ...
; #pragma unroll
;         for (int ai = 0; ai < 2; ++ai)
; #pragma unroll
;             for (int m = 0; m < 4; ++m) { const int row = row0 + ai * HALF + m * 16; const float s = pr[ai * 4 + m];
;                 f32x4 h[2];
; #pragma unroll
;                 for (int n = 0; n < 2; ++n) { f32x4 g, uu;
;                     if constexpr (I8IN) { const i32x4 gi = __builtin_bit_cast(i32x4, acc[ai][0][m][n]), ui = __builtin_bit_cast(i32x4, acc[ai][1][m][n]);
;                         g = (f32x4){(float)gi[0], (float)gi[1], (float)gi[2], (float)gi[3]} * (csg[n] * s); uu = (f32x4){(float)ui[0], (float)ui[1], (float)ui[2], (float)ui[3]} * (csu[n] * s); }
;                     else { g = acc[ai][0][m][n] * s; uu = acc[ai][1][m][n] * s; }
; #pragma unroll
;                     for (int j = 0; j < 4; ++j) h[n][j] = silu_f(g[j]) * uu[j]; }
;                 if constexpr (F8OUT) { u32x2 w; w.x = pack4_fp8(h[0] * hscale); w.y = pack4_fp8(h[1] * hscale); *(u32x2*)((unsigned char*)H + (size_t)row * ldh + col0) = w; }
;                 else *(u32x4*)(H + (size_t)row * ldh + col0) = pack8(h[0], h[1]); }
	v_cvt_pk_bf16_f32 v50, v58, v56
	v_cvt_pk_bf16_f32 v51, v55, v51
	v_pk_mul_f32 v[54:55], v[156:157], v[166:167] op_sel_hi:[0,1]
	v_pk_mul_f32 v[52:53], v[54:55], v[52:53]
	v_cvt_f32_i32_e32 v44, v41
	v_mul_f32_e32 v40, 0xbfb8aa3b, v53
	v_exp_f32_e32 v40, v40
	v_mad_i64_i32 v[54:55], s[34:35], v66, s70, v[122:123]
	v_add_f32_e32 v40, 1.0, v40
	v_rcp_f32_e32 v56, v40
	v_pk_mul_f32 v[40:41], v[156:157], v[164:165] op_sel_hi:[0,1]
	v_pk_mul_f32 v[40:41], v[40:41], v[44:45]
	s_nop 0
	v_mul_f32_e32 v44, 0xbfb8aa3b, v41
	v_exp_f32_e32 v57, v44
	v_lshl_add_u64 v[44:45], v[54:55], 0, v[126:127]
	global_store_dwordx4 v[44:45], v[48:51], off
	v_cvt_f32_i32_e32 v45, v46
	v_add_f32_e32 v44, 1.0, v57
	v_rcp_f32_e32 v49, v44
	v_cvt_f32_i32_e32 v44, v42
	v_mul_f32_e32 v48, v53, v56
	v_mul_f32_e32 v50, v52, v48
	v_mul_f32_e32 v41, v41, v49
	v_pk_mul_f32 v[48:49], v[156:157], v[124:125] op_sel_hi:[0,1]
	v_pk_mul_f32 v[44:45], v[48:49], v[44:45]
	v_cvt_f32_i32_e32 v46, v43
	v_mul_f32_e32 v42, 0xbfb8aa3b, v45
	v_exp_f32_e32 v42, v42
	v_mul_f32_e32 v48, v40, v41
	v_pk_mul_f32 v[40:41], v[156:157], v[120:121] op_sel_hi:[0,1]
	v_pk_mul_f32 v[40:41], v[40:41], v[46:47]
	v_add_f32_e32 v42, 1.0, v42
	v_mul_f32_e32 v43, 0xbfb8aa3b, v41
	v_exp_f32_e32 v46, v43
	v_rcp_f32_e32 v49, v42
	v_cvt_f32_i32_e32 v43, v36
	v_cvt_f32_i32_e32 v42, v32
	v_add_f32_e32 v32, 1.0, v46
	v_pk_mul_f32 v[46:47], v[156:157], v[118:119] op_sel_hi:[0,1]
	v_rcp_f32_e32 v32, v32
	v_pk_mul_f32 v[42:43], v[46:47], v[42:43]
	v_mul_f32_e32 v45, v45, v49
	v_mul_f32_e32 v36, 0xbfb8aa3b, v43
	v_exp_f32_e32 v36, v36
	v_mul_f32_e32 v32, v41, v32
	v_mul_f32_e32 v44, v44, v45
	v_mul_f32_e32 v45, v40, v32
	v_add_f32_e32 v36, 1.0, v36
	v_rcp_f32_e32 v41, v36
	v_cvt_f32_i32_e32 v36, v33
	v_pk_mul_f32 v[32:33], v[156:157], v[116:117] op_sel_hi:[0,1]
	v_mul_f32_e32 v40, v43, v41
	v_pk_mul_f32 v[32:33], v[32:33], v[36:37]
	v_cvt_f32_i32_e32 v37, v38
	v_mul_f32_e32 v36, 0xbfb8aa3b, v33
	v_exp_f32_e32 v41, v36
	v_cvt_f32_i32_e32 v36, v34
	v_mul_f32_e32 v42, v42, v40
	v_cvt_f32_i32_e32 v38, v35
	v_add_f32_e32 v34, 1.0, v41
	v_pk_mul_f32 v[40:41], v[156:157], v[114:115] op_sel_hi:[0,1]
	v_pk_mul_f32 v[36:37], v[40:41], v[36:37]
	v_rcp_f32_e32 v43, v34
	v_mul_f32_e32 v34, 0xbfb8aa3b, v37
	v_exp_f32_e32 v40, v34
	v_pk_mul_f32 v[34:35], v[156:157], v[112:113] op_sel_hi:[0,1]
	v_pk_mul_f32 v[34:35], v[34:35], v[38:39]
	v_mul_f32_e32 v33, v33, v43
	v_mul_f32_e32 v38, 0xbfb8aa3b, v35
	v_exp_f32_e32 v38, v38
	v_add_f32_e32 v39, 1.0, v40
	v_rcp_f32_e32 v39, v39
	v_mul_f32_e32 v40, v32, v33
	v_add_f32_e32 v38, 1.0, v38
	v_rcp_f32_e32 v38, v38
	v_mul_f32_e32 v32, v37, v39
	v_mul_f32_e32 v39, v36, v32
	v_cvt_f32_i32_e32 v37, v28
	v_cvt_f32_i32_e32 v36, v24
	v_mul_f32_e32 v32, v35, v38
	v_mul_f32_e32 v35, v34, v32
	v_cvt_pk_bf16_f32 v32, v50, v48
	v_cvt_pk_bf16_f32 v33, v44, v45
	v_cvt_pk_bf16_f32 v34, v42, v40
	v_cvt_pk_bf16_f32 v35, v39, v35
	v_pk_mul_f32 v[38:39], v[158:159], v[166:167] op_sel_hi:[0,1]
	v_pk_mul_f32 v[36:37], v[38:39], v[36:37]
	v_cvt_f32_i32_e32 v28, v25
	v_mul_f32_e32 v24, 0xbfb8aa3b, v37
	v_exp_f32_e32 v24, v24
	v_add_u32_e32 v41, 0x90, v162
	v_mad_i64_i32 v[38:39], s[34:35], v41, s70, v[122:123]
	v_add_f32_e32 v24, 1.0, v24
	v_rcp_f32_e32 v40, v24
	v_pk_mul_f32 v[24:25], v[158:159], v[164:165] op_sel_hi:[0,1]
	v_pk_mul_f32 v[24:25], v[24:25], v[28:29]
	s_nop 0
	v_mul_f32_e32 v28, 0xbfb8aa3b, v25
	v_exp_f32_e32 v41, v28
	v_lshl_add_u64 v[28:29], v[38:39], 0, v[126:127]
	global_store_dwordx4 v[28:29], v[32:35], off
	v_cvt_f32_i32_e32 v29, v30
	v_add_f32_e32 v28, 1.0, v41
	v_rcp_f32_e32 v33, v28
	v_cvt_f32_i32_e32 v28, v26
	v_mul_f32_e32 v32, v37, v40
	v_mul_f32_e32 v34, v36, v32
	v_mul_f32_e32 v25, v25, v33
	v_pk_mul_f32 v[32:33], v[158:159], v[124:125] op_sel_hi:[0,1]
	v_pk_mul_f32 v[28:29], v[32:33], v[28:29]
	v_cvt_f32_i32_e32 v30, v27
	v_mul_f32_e32 v26, 0xbfb8aa3b, v29
	v_exp_f32_e32 v26, v26
	v_mul_f32_e32 v32, v24, v25
	v_pk_mul_f32 v[24:25], v[158:159], v[120:121] op_sel_hi:[0,1]
	v_pk_mul_f32 v[24:25], v[24:25], v[30:31]
	v_add_f32_e32 v26, 1.0, v26
	v_mul_f32_e32 v27, 0xbfb8aa3b, v25
	v_exp_f32_e32 v30, v27
	v_rcp_f32_e32 v33, v26
	v_cvt_f32_i32_e32 v27, v20
	v_cvt_f32_i32_e32 v26, v16
	v_add_f32_e32 v16, 1.0, v30
	v_pk_mul_f32 v[30:31], v[158:159], v[118:119] op_sel_hi:[0,1]
	v_rcp_f32_e32 v16, v16
	v_pk_mul_f32 v[26:27], v[30:31], v[26:27]
	v_mul_f32_e32 v29, v29, v33
; __device__ __forceinline__ unsigned pack4_fp8(const f32x4 v) { int w = __builtin_amdgcn_cvt_pk_fp8_f32(clamp448(v[0]), clamp448(v[1]), 0, false); w = __builtin_amdgcn_cvt_pk_fp8_f32(clamp448(v[2]), clamp448(v[3]), w, true); return (unsigned)w; }
; __device__ __forceinline__ float silu_f(float g) { return g * fast_rcp(1.0f + fast_exp(-g)); }
; __device__ __forceinline__ u32x4 pack8(const f32x4 a, const f32x4 b) { u32x4 w; w.x = cvt_pk_bf16(a[0], a[1]); w.y = cvt_pk_bf16(a[2], a[3]); w.z = cvt_pk_bf16(b[0], b[1]); w.w = cvt_pk_bf16(b[2], b[3]); return w; }
; #define PG8_BAR __builtin_amdgcn_s_barrier()
;     __device__ __forceinline__ void operator()(const f32x4 (&acc)[2][2][4][2], const Unit& u, int wr, int wc, int fr, int fq, const float (&pr)[8]) const {
;     ...
; #pragma unroll
;         for (int ai = 0; ai < 2; ++ai)
; #pragma unroll
;             for (int m = 0; m < 4; ++m) { const int row = row0 + ai * HALF + m * 16; const float s = pr[ai * 4 + m];
;                 f32x4 h[2];
; #pragma unroll
;                 for (int n = 0; n < 2; ++n) { f32x4 g, uu;
;                     if constexpr (I8IN) { const i32x4 gi = __builtin_bit_cast(i32x4, acc[ai][0][m][n]), ui = __builtin_bit_cast(i32x4, acc[ai][1][m][n]);
;                         g = (f32x4){(float)gi[0], (float)gi[1], (float)gi[2], (float)gi[3]} * (csg[n] * s); uu = (f32x4){(float)ui[0], (float)ui[1], (float)ui[2], (float)ui[3]} * (csu[n] * s); }
;                     else { g = acc[ai][0][m][n] * s; uu = acc[ai][1][m][n] * s; }
; #pragma unroll
;                     for (int j = 0; j < 4; ++j) h[n][j] = silu_f(g[j]) * uu[j]; }
;                 if constexpr (F8OUT) { u32x2 w; w.x = pack4_fp8(h[0] * hscale); w.y = pack4_fp8(h[1] * hscale); *(u32x2*)((unsigned char*)H + (size_t)row * ldh + col0) = w; }
;                 else *(u32x4*)(H + (size_t)row * ldh + col0) = pack8(h[0], h[1]); }
;     ...
;         if (!has_next) break;
; #pragma unroll
;         for (int a = 0; a < 2; ++a)
; #pragma unroll
;             for (int b = 0; b < 2; ++b)
; #pragma unroll
;                 for (int m = 0; m < 4; ++m)
; #pragma unroll
;                     for (int n = 0; n < 2; ++n) acc[a][b][m][n] = (f32x4){0.f, 0.f, 0.f, 0.f};
;         cur = nxt; cA = nA; cB = nB; ++ui;
;         if constexpr (ALIGN_EPI) { if (wr == 1) PG8_BAR; }
	v_mul_f32_e32 v20, 0xbfb8aa3b, v27
	v_exp_f32_e32 v20, v20
	v_mul_f32_e32 v16, v25, v16
	v_mul_f32_e32 v28, v28, v29
	v_mul_f32_e32 v29, v24, v16
	v_add_f32_e32 v20, 1.0, v20
	v_rcp_f32_e32 v25, v20
	v_cvt_f32_i32_e32 v20, v17
	v_pk_mul_f32 v[16:17], v[158:159], v[116:117] op_sel_hi:[0,1]
	v_mul_f32_e32 v24, v27, v25
	v_pk_mul_f32 v[16:17], v[16:17], v[20:21]
	v_cvt_f32_i32_e32 v21, v22
	v_mul_f32_e32 v20, 0xbfb8aa3b, v17
	v_exp_f32_e32 v25, v20
	v_cvt_f32_i32_e32 v20, v18
	v_mul_f32_e32 v26, v26, v24
	v_cvt_f32_i32_e32 v22, v19
	v_add_f32_e32 v18, 1.0, v25
	v_pk_mul_f32 v[24:25], v[158:159], v[114:115] op_sel_hi:[0,1]
	v_pk_mul_f32 v[20:21], v[24:25], v[20:21]
	v_rcp_f32_e32 v27, v18
	v_mul_f32_e32 v18, 0xbfb8aa3b, v21
	v_exp_f32_e32 v24, v18
	v_pk_mul_f32 v[18:19], v[158:159], v[112:113] op_sel_hi:[0,1]
	v_pk_mul_f32 v[18:19], v[18:19], v[22:23]
	v_mul_f32_e32 v17, v17, v27
	v_mul_f32_e32 v22, 0xbfb8aa3b, v19
	v_exp_f32_e32 v22, v22
	v_add_f32_e32 v23, 1.0, v24
	v_rcp_f32_e32 v23, v23
	v_mul_f32_e32 v24, v16, v17
	v_add_f32_e32 v22, 1.0, v22
	v_rcp_f32_e32 v22, v22
	v_mul_f32_e32 v16, v21, v23
	v_mul_f32_e32 v23, v20, v16
	v_cvt_f32_i32_e32 v21, v12
	v_cvt_f32_i32_e32 v20, v8
	v_mul_f32_e32 v16, v19, v22
	v_mul_f32_e32 v19, v18, v16
	v_cvt_pk_bf16_f32 v16, v34, v32
	v_cvt_pk_bf16_f32 v17, v28, v29
	v_cvt_pk_bf16_f32 v18, v26, v24
	v_cvt_pk_bf16_f32 v19, v23, v19
	v_pk_mul_f32 v[22:23], v[160:161], v[166:167] op_sel_hi:[0,1]
	v_pk_mul_f32 v[20:21], v[22:23], v[20:21]
	v_cvt_f32_i32_e32 v12, v9
	v_mul_f32_e32 v8, 0xbfb8aa3b, v21
	v_exp_f32_e32 v8, v8
	v_add_u32_e32 v25, 0xa0, v162
	v_mad_i64_i32 v[22:23], s[34:35], v25, s70, v[122:123]
	v_add_f32_e32 v8, 1.0, v8
	v_rcp_f32_e32 v24, v8
	v_pk_mul_f32 v[8:9], v[160:161], v[164:165] op_sel_hi:[0,1]
	v_pk_mul_f32 v[8:9], v[8:9], v[12:13]
	s_nop 0
	v_mul_f32_e32 v12, 0xbfb8aa3b, v9
	v_exp_f32_e32 v25, v12
	v_lshl_add_u64 v[12:13], v[22:23], 0, v[126:127]
	global_store_dwordx4 v[12:13], v[16:19], off
	v_cvt_f32_i32_e32 v13, v14
	v_add_f32_e32 v12, 1.0, v25
	v_rcp_f32_e32 v17, v12
	v_cvt_f32_i32_e32 v12, v10
	v_mul_f32_e32 v16, v21, v24
	v_mul_f32_e32 v18, v20, v16
	v_mul_f32_e32 v9, v9, v17
	v_pk_mul_f32 v[16:17], v[160:161], v[124:125] op_sel_hi:[0,1]
	v_pk_mul_f32 v[12:13], v[16:17], v[12:13]
	v_cvt_f32_i32_e32 v14, v11
	v_mul_f32_e32 v10, 0xbfb8aa3b, v13
	v_exp_f32_e32 v10, v10
	v_mul_f32_e32 v16, v8, v9
	v_pk_mul_f32 v[8:9], v[160:161], v[120:121] op_sel_hi:[0,1]
	v_pk_mul_f32 v[8:9], v[8:9], v[14:15]
	v_add_f32_e32 v10, 1.0, v10
	v_mul_f32_e32 v11, 0xbfb8aa3b, v9
	v_exp_f32_e32 v14, v11
	v_rcp_f32_e32 v17, v10
	v_cvt_f32_i32_e32 v11, v4
	v_cvt_f32_i32_e32 v10, v0
	v_add_f32_e32 v0, 1.0, v14
	v_pk_mul_f32 v[14:15], v[160:161], v[118:119] op_sel_hi:[0,1]
	v_rcp_f32_e32 v0, v0
	v_pk_mul_f32 v[10:11], v[14:15], v[10:11]
	v_mul_f32_e32 v13, v13, v17
	v_mul_f32_e32 v4, 0xbfb8aa3b, v11
	v_exp_f32_e32 v4, v4
	v_mul_f32_e32 v0, v9, v0
	v_mul_f32_e32 v12, v12, v13
	v_mul_f32_e32 v13, v8, v0
	v_add_f32_e32 v4, 1.0, v4
	v_rcp_f32_e32 v9, v4
	v_cvt_f32_i32_e32 v4, v1
	v_pk_mul_f32 v[0:1], v[160:161], v[116:117] op_sel_hi:[0,1]
	v_mul_f32_e32 v8, v11, v9
	v_pk_mul_f32 v[0:1], v[0:1], v[4:5]
	v_cvt_f32_i32_e32 v5, v6
	v_mul_f32_e32 v4, 0xbfb8aa3b, v1
	v_exp_f32_e32 v9, v4
	v_cvt_f32_i32_e32 v4, v2
	v_mul_f32_e32 v10, v10, v8
	v_cvt_f32_i32_e32 v6, v3
	v_add_f32_e32 v2, 1.0, v9
	v_pk_mul_f32 v[8:9], v[160:161], v[114:115] op_sel_hi:[0,1]
	v_pk_mul_f32 v[4:5], v[8:9], v[4:5]
	v_rcp_f32_e32 v11, v2
	v_mul_f32_e32 v2, 0xbfb8aa3b, v5
	v_exp_f32_e32 v8, v2
	v_pk_mul_f32 v[2:3], v[160:161], v[112:113] op_sel_hi:[0,1]
	v_pk_mul_f32 v[2:3], v[2:3], v[6:7]
	v_mul_f32_e32 v1, v1, v11
	v_mul_f32_e32 v6, 0xbfb8aa3b, v3
	v_exp_f32_e32 v6, v6
	v_add_f32_e32 v7, 1.0, v8
	v_rcp_f32_e32 v7, v7
	v_mul_f32_e32 v8, v0, v1
	v_add_f32_e32 v6, 1.0, v6
	v_rcp_f32_e32 v6, v6
	v_mul_f32_e32 v0, v5, v7
	v_mul_f32_e32 v4, v4, v0
	v_add_u32_e32 v5, 0xb0, v162
	v_mul_f32_e32 v0, v3, v6
	v_mul_f32_e32 v3, v2, v0
	v_cvt_pk_bf16_f32 v0, v18, v16
	v_cvt_pk_bf16_f32 v1, v12, v13
	v_cvt_pk_bf16_f32 v2, v10, v8
	v_cvt_pk_bf16_f32 v3, v4, v3
	v_mad_i64_i32 v[4:5], s[34:35], v5, s70, v[122:123]
	v_lshl_add_u64 v[4:5], v[4:5], 0, v[126:127]
	global_store_dwordx4 v[4:5], v[0:3], off
	s_cbranch_vccnz .LBB0_244
	s_andn2_b64 vcc, exec, s[6:7]
	s_cbranch_vccnz .LBB0_243
	s_barrier
	s_branch .LBB0_243

;     ...
; #pragma unroll
;         for (int a = 0; a < 2; ++a)
; #pragma unroll
;             for (int b = 0; b < 2; ++b)
; #pragma unroll
;                 for (int m = 0; m < 4; ++m)
; #pragma unroll
;                     for (int n = 0; n < 2; ++n) acc[a][b][m][n] = (f32x4){0.f, 0.f, 0.f, 0.f};
;         cur = nxt; cA = nA; cB = nB; ++ui;
.LBB0_334:
	s_add_u32 s50, s50, 0x160080
	s_addc_u32 s51, s51, 0
	s_add_u32 s34, s52, 0x100
	v_mov_b32_e32 v0, 0
	s_addc_u32 s35, s53, 0
	s_mov_b32 s72, -2
	s_waitcnt lgkmcnt(0)
	v_mov_b32_e32 v1, v0
	v_mov_b32_e32 v2, v0
	v_mov_b32_e32 v3, v0
	v_mov_b32_e32 v4, v0
	v_mov_b32_e32 v5, v0
	v_mov_b32_e32 v6, v0
	v_mov_b32_e32 v7, v0
	v_mov_b32_e32 v16, v0
	v_mov_b32_e32 v17, v0
	v_mov_b32_e32 v18, v0
	v_mov_b32_e32 v19, v0
	v_mov_b32_e32 v20, v0
	v_mov_b32_e32 v21, v0
	v_mov_b32_e32 v22, v0
	v_mov_b32_e32 v23, v0
	v_mov_b32_e32 v32, v0
	v_mov_b32_e32 v33, v0
	v_mov_b32_e32 v34, v0
	v_mov_b32_e32 v35, v0
	v_mov_b32_e32 v36, v0
	v_mov_b32_e32 v37, v0
	v_mov_b32_e32 v38, v0
	v_mov_b32_e32 v39, v0
	v_mov_b32_e32 v48, v0
	v_mov_b32_e32 v49, v0
	v_mov_b32_e32 v50, v0
	v_mov_b32_e32 v51, v0
	v_mov_b32_e32 v52, v0
	v_mov_b32_e32 v53, v0
	v_mov_b32_e32 v54, v0
	v_mov_b32_e32 v55, v0
	v_mov_b32_e32 v8, v0
	v_mov_b32_e32 v9, v0
	v_mov_b32_e32 v10, v0
	v_mov_b32_e32 v11, v0
	v_mov_b32_e32 v12, v0
	v_mov_b32_e32 v13, v0
	v_mov_b32_e32 v14, v0
	v_mov_b32_e32 v15, v0
	v_mov_b32_e32 v24, v0
	v_mov_b32_e32 v25, v0
	v_mov_b32_e32 v26, v0
	v_mov_b32_e32 v27, v0
	v_mov_b32_e32 v28, v0
	v_mov_b32_e32 v29, v0
	v_mov_b32_e32 v30, v0
	v_mov_b32_e32 v31, v0
	v_mov_b32_e32 v40, v0
	v_mov_b32_e32 v41, v0
	v_mov_b32_e32 v42, v0
	v_mov_b32_e32 v43, v0
	v_mov_b32_e32 v44, v0
	v_mov_b32_e32 v45, v0
	v_mov_b32_e32 v46, v0
	v_mov_b32_e32 v47, v0
	v_mov_b32_e32 v56, v0
	v_mov_b32_e32 v57, v0
	v_mov_b32_e32 v58, v0
	v_mov_b32_e32 v59, v0
	v_mov_b32_e32 v60, v0
	v_mov_b32_e32 v61, v0
	v_mov_b32_e32 v62, v0
	v_mov_b32_e32 v63, v0
	v_mov_b32_e32 v64, v0
	v_mov_b32_e32 v65, v0
	v_mov_b32_e32 v66, v0
	v_mov_b32_e32 v67, v0
	v_mov_b32_e32 v68, v0
	v_mov_b32_e32 v69, v0
	v_mov_b32_e32 v70, v0
	v_mov_b32_e32 v71, v0
	v_mov_b32_e32 v80, v0
	v_mov_b32_e32 v81, v0
	v_mov_b32_e32 v82, v0
	v_mov_b32_e32 v83, v0
	v_mov_b32_e32 v84, v0
	v_mov_b32_e32 v85, v0
	v_mov_b32_e32 v86, v0
	v_mov_b32_e32 v87, v0
	v_mov_b32_e32 v96, v0
	v_mov_b32_e32 v97, v0
	v_mov_b32_e32 v98, v0
	v_mov_b32_e32 v99, v0
	v_mov_b32_e32 v100, v0
	v_mov_b32_e32 v101, v0
	v_mov_b32_e32 v102, v0
	v_mov_b32_e32 v103, v0
	v_mov_b32_e32 v112, v0
	v_mov_b32_e32 v113, v0
	v_mov_b32_e32 v114, v0
	v_mov_b32_e32 v115, v0
	v_mov_b32_e32 v116, v0
	v_mov_b32_e32 v117, v0
	v_mov_b32_e32 v118, v0
	v_mov_b32_e32 v119, v0
	v_mov_b32_e32 v72, v0
	v_mov_b32_e32 v73, v0
	v_mov_b32_e32 v74, v0
	v_mov_b32_e32 v75, v0
	v_mov_b32_e32 v76, v0
	v_mov_b32_e32 v77, v0
	v_mov_b32_e32 v78, v0
	v_mov_b32_e32 v79, v0
	v_mov_b32_e32 v88, v0
	v_mov_b32_e32 v89, v0
	v_mov_b32_e32 v90, v0
	v_mov_b32_e32 v91, v0
	v_mov_b32_e32 v92, v0
	v_mov_b32_e32 v93, v0
	v_mov_b32_e32 v94, v0
	v_mov_b32_e32 v95, v0
	v_mov_b32_e32 v104, v0
	v_mov_b32_e32 v105, v0
	v_mov_b32_e32 v106, v0
	v_mov_b32_e32 v107, v0
	v_mov_b32_e32 v108, v0
	v_mov_b32_e32 v109, v0
	v_mov_b32_e32 v110, v0
	v_mov_b32_e32 v111, v0
	v_mov_b32_e32 v120, v0
	v_mov_b32_e32 v121, v0
	v_mov_b32_e32 v122, v0
	v_mov_b32_e32 v123, v0
	v_mov_b32_e32 v124, v0
	v_mov_b32_e32 v125, v0
	v_mov_b32_e32 v126, v0
	v_mov_b32_e32 v127, v0

;     ...
;     for (;;) {
;         const bool has_next = S.next(ui + 1, nxt);
;         const char* nA = has_next ? (const char*)g.A + (size_t)nxt.pm * tstep : cA; const char* nB = has_next ? (const char*)g.Bt + (size_t)nxt.pn * tstep : cB;
;     ...
; #pragma unroll
;         for (int a = 0; a < 2; ++a)
; #pragma unroll
;             for (int b = 0; b < 2; ++b)
; #pragma unroll
;                 for (int m = 0; m < 4; ++m)
; #pragma unroll
;                     for (int n = 0; n < 2; ++n) acc[a][b][m][n] = (f32x4){0.f, 0.f, 0.f, 0.f};
;         cur = nxt; cA = nA; cB = nB; ++ui;
.LBB0_431:
	s_ashr_i32 s63, s62, 31
	s_lshl_b64 s[18:19], s[62:63], 20
	s_add_u32 s64, s16, s18
	s_addc_u32 s65, s17, s19
	s_and_b64 s[18:19], s[6:7], exec
	s_cselect_b32 s18, s65, s71
	s_cselect_b32 s19, s64, s70
	s_ashr_i32 s61, s60, 31
	s_lshl_b64 s[34:35], s[60:61], 20
	s_add_u32 s66, s80, s34
	s_addc_u32 s67, s81, s35
	s_and_b64 s[34:35], s[6:7], exec
	s_cselect_b32 s34, s67, s73
	s_cselect_b32 s35, s66, s72
	s_add_u32 s70, s70, 0x80080
	v_lshl_add_u32 v186, s10, 8, v204
	s_addc_u32 s71, s71, 0
	v_ashrrev_i32_e32 v187, 31, v186
	s_add_u32 s10, s72, 0x100
	v_mov_b32_e32 v0, 0
	v_lshl_add_u64 v[128:129], v[186:187], 2, s[8:9]
	s_addc_u32 s61, s73, 0
	s_mov_b32 s63, -2
	v_mov_b32_e32 v1, v0
	v_mov_b32_e32 v2, v0
	v_mov_b32_e32 v3, v0
	v_mov_b32_e32 v4, v0
	v_mov_b32_e32 v5, v0
	v_mov_b32_e32 v6, v0
	v_mov_b32_e32 v7, v0
	v_mov_b32_e32 v16, v0
	v_mov_b32_e32 v17, v0
	v_mov_b32_e32 v18, v0
	v_mov_b32_e32 v19, v0
	v_mov_b32_e32 v20, v0
	v_mov_b32_e32 v21, v0
	v_mov_b32_e32 v22, v0
	v_mov_b32_e32 v23, v0
	v_mov_b32_e32 v32, v0
	v_mov_b32_e32 v33, v0
	v_mov_b32_e32 v34, v0
	v_mov_b32_e32 v35, v0
	v_mov_b32_e32 v36, v0
	v_mov_b32_e32 v37, v0
	v_mov_b32_e32 v38, v0
	v_mov_b32_e32 v39, v0
	v_mov_b32_e32 v48, v0
	v_mov_b32_e32 v49, v0
	v_mov_b32_e32 v50, v0
	v_mov_b32_e32 v51, v0
	v_mov_b32_e32 v52, v0
	v_mov_b32_e32 v53, v0
	v_mov_b32_e32 v54, v0
	v_mov_b32_e32 v55, v0
	v_mov_b32_e32 v8, v0
	v_mov_b32_e32 v9, v0
	v_mov_b32_e32 v10, v0
	v_mov_b32_e32 v11, v0
	v_mov_b32_e32 v12, v0
	v_mov_b32_e32 v13, v0
	v_mov_b32_e32 v14, v0
	v_mov_b32_e32 v15, v0
	v_mov_b32_e32 v24, v0
	v_mov_b32_e32 v25, v0
	v_mov_b32_e32 v26, v0
	v_mov_b32_e32 v27, v0
	v_mov_b32_e32 v28, v0
	v_mov_b32_e32 v29, v0
	v_mov_b32_e32 v30, v0
	v_mov_b32_e32 v31, v0
	v_mov_b32_e32 v40, v0
	v_mov_b32_e32 v41, v0
	v_mov_b32_e32 v42, v0
	v_mov_b32_e32 v43, v0
	v_mov_b32_e32 v44, v0
	v_mov_b32_e32 v45, v0
	v_mov_b32_e32 v46, v0
	v_mov_b32_e32 v47, v0
	v_mov_b32_e32 v56, v0
	v_mov_b32_e32 v57, v0
	v_mov_b32_e32 v58, v0
	v_mov_b32_e32 v59, v0
	v_mov_b32_e32 v60, v0
	v_mov_b32_e32 v61, v0
	v_mov_b32_e32 v62, v0
	v_mov_b32_e32 v63, v0
	v_mov_b32_e32 v64, v0
	v_mov_b32_e32 v65, v0
	v_mov_b32_e32 v66, v0
	v_mov_b32_e32 v67, v0
	v_mov_b32_e32 v68, v0
	v_mov_b32_e32 v69, v0
	v_mov_b32_e32 v70, v0
	v_mov_b32_e32 v71, v0
	v_mov_b32_e32 v80, v0
	v_mov_b32_e32 v81, v0
	v_mov_b32_e32 v82, v0
	v_mov_b32_e32 v83, v0
	v_mov_b32_e32 v84, v0
	v_mov_b32_e32 v85, v0
	v_mov_b32_e32 v86, v0
	v_mov_b32_e32 v87, v0
	v_mov_b32_e32 v96, v0
	v_mov_b32_e32 v97, v0
	v_mov_b32_e32 v98, v0
	v_mov_b32_e32 v99, v0
	v_mov_b32_e32 v100, v0
	v_mov_b32_e32 v101, v0
	v_mov_b32_e32 v102, v0
	v_mov_b32_e32 v103, v0
	v_mov_b32_e32 v112, v0
	v_mov_b32_e32 v113, v0
	v_mov_b32_e32 v114, v0
	v_mov_b32_e32 v115, v0
	v_mov_b32_e32 v116, v0
	v_mov_b32_e32 v117, v0
	v_mov_b32_e32 v118, v0
	v_mov_b32_e32 v119, v0
	v_mov_b32_e32 v72, v0
	v_mov_b32_e32 v73, v0
	v_mov_b32_e32 v74, v0
	v_mov_b32_e32 v75, v0
	v_mov_b32_e32 v76, v0
	v_mov_b32_e32 v77, v0
	v_mov_b32_e32 v78, v0
	v_mov_b32_e32 v79, v0
	v_mov_b32_e32 v88, v0
	v_mov_b32_e32 v89, v0
	v_mov_b32_e32 v90, v0
	v_mov_b32_e32 v91, v0
	v_mov_b32_e32 v92, v0
	v_mov_b32_e32 v93, v0
	v_mov_b32_e32 v94, v0
	v_mov_b32_e32 v95, v0
	v_mov_b32_e32 v104, v0
	v_mov_b32_e32 v105, v0
	v_mov_b32_e32 v106, v0
	v_mov_b32_e32 v107, v0
	v_mov_b32_e32 v108, v0
	v_mov_b32_e32 v109, v0
	v_mov_b32_e32 v110, v0
	v_mov_b32_e32 v111, v0
	v_mov_b32_e32 v120, v0
	v_mov_b32_e32 v121, v0
	v_mov_b32_e32 v122, v0
	v_mov_b32_e32 v123, v0
	v_mov_b32_e32 v124, v0
	v_mov_b32_e32 v125, v0
	v_mov_b32_e32 v126, v0
	v_mov_b32_e32 v127, v0
	s_branch .LBB0_433

; #define PG8_STAGE(bufoff, gbase, voff) do { _Pragma("unroll") for (int _i = 0; _i < 2; ++_i) \
;         __builtin_amdgcn_global_load_lds((const unsigned*)((const char*)(gbase) + (voff)[_i]), (PG8_LAS unsigned*)(lds + (bufoff) + ldsw + _i * 8192), 16, 0, 0); } while (0)
; #define PG8_WAIT_V(n) asm volatile("s_waitcnt vmcnt(" #n ")" ::: "memory")
; #define PG8_WAIT_L(n) asm volatile("s_waitcnt lgkmcnt(" #n ")" ::: "memory")
; #define PG8_BAR __builtin_amdgcn_s_barrier()
; #define PG8_SCHED __builtin_amdgcn_sched_barrier(0)
;     ...
;             PG8_LDB(B0, 0, 0); PG8_LDB(B1, 0, 1); PG8_SCHED; PG8_LDA(At, 0, 0); PG8_STAGE(PG8_SA(1, 1), a1 + hstep, voffA);
;             PG8_WAIT_V(8); PG8_WAIT_L(0); PG8_BAR; PG8_MMA(0, 0, At, B0); PG8_MMA(0, 1, At, B1); PG8_BAR; PG8_SCHED;
;             PG8_LDA(At, 0, 1); PG8_STAGE(PG8_SB(0, 0), b2, voffB); PG8_STAGE(PG8_SB(0, 1), b2 + hstep, voffB); PG8_STAGE(PG8_SA(0, 0), a2, voffA);
;             PG8_WAIT_V(8); PG8_WAIT_L(0); PG8_BAR; PG8_MMA(1, 0, At, B0); PG8_MMA(1, 1, At, B1); PG8_BAR; PG8_SCHED;
.LBB0_851:
	v_add_u32_e32 v157, s60, v149
	ds_read_b128 v[166:169], v157
	ds_read_b128 v[170:173], v157 offset:1024
	ds_read_b128 v[174:177], v157 offset:2048
	ds_read_b128 v[178:181], v157 offset:3072
	v_add_u32_e32 v157, s61, v149
	ds_read_b128 v[182:185], v157
	ds_read_b128 v[186:189], v157 offset:1024
	ds_read_b128 v[190:193], v157 offset:2048
	ds_read_b128 v[194:197], v157 offset:3072
	s_add_u32 s33, s42, 0xfffc0080
	s_addc_u32 s46, s43, -1
	s_and_b64 s[44:45], s[44:45], exec
	s_cselect_b32 s47, s34, s46
	s_cselect_b32 s46, s35, s33
	s_cselect_b32 s45, s25, s66
	s_cselect_b32 s44, s37, s65
	v_lshl_add_u64 v[210:211], s[42:43], 0, v[138:139]
	s_add_i32 m0, s51, 0xc000
	ds_read_b128 v[198:201], v153
	ds_read_b128 v[202:205], v153 offset:1024
	ds_read_b128 v[206:209], v153 offset:2048
	ds_read_b128 v[214:217], v153 offset:3072
	ds_read_b128 v[218:221], v153 offset:4096
	ds_read_b128 v[222:225], v153 offset:5120
	ds_read_b128 v[226:229], v153 offset:6144
	ds_read_b128 v[230:233], v153 offset:7168
	global_load_lds_dwordx4 v[210:211], off
	v_lshl_add_u64 v[210:211], s[42:43], 0, v[140:141]
	s_add_i32 m0, s51, 0xe000
	s_nop 0
	global_load_lds_dwordx4 v[210:211], off
	s_waitcnt vmcnt(8)
	s_waitcnt lgkmcnt(0)
	s_barrier
	s_setprio 1
	s_waitcnt lgkmcnt(0)
	v_mfma_i32_16x16x64_i8 v[124:127], v[166:169], v[198:201], v[124:127]
	v_mfma_i32_16x16x64_i8 v[120:123], v[174:177], v[198:201], v[120:123]
	v_mfma_i32_16x16x64_i8 v[108:111], v[166:169], v[206:209], v[108:111]
	v_mfma_i32_16x16x64_i8 v[100:103], v[174:177], v[206:209], v[100:103]
	v_mfma_i32_16x16x64_i8 v[92:95], v[166:169], v[218:221], v[92:95]
	v_mfma_i32_16x16x64_i8 v[84:87], v[174:177], v[218:221], v[84:87]
	v_mfma_i32_16x16x64_i8 v[76:79], v[166:169], v[226:229], v[76:79]
	v_mfma_i32_16x16x64_i8 v[68:71], v[174:177], v[226:229], v[68:71]
	v_mfma_i32_16x16x64_i8 v[124:127], v[170:173], v[202:205], v[124:127]
	v_mfma_i32_16x16x64_i8 v[120:123], v[178:181], v[202:205], v[120:123]
	v_mfma_i32_16x16x64_i8 v[108:111], v[170:173], v[214:217], v[108:111]
	v_mfma_i32_16x16x64_i8 v[100:103], v[178:181], v[214:217], v[100:103]
	v_mfma_i32_16x16x64_i8 v[92:95], v[170:173], v[222:225], v[92:95]
	v_mfma_i32_16x16x64_i8 v[84:87], v[178:181], v[222:225], v[84:87]
	v_mfma_i32_16x16x64_i8 v[76:79], v[170:173], v[230:233], v[76:79]
	v_mfma_i32_16x16x64_i8 v[68:71], v[178:181], v[230:233], v[68:71]
	s_setprio 0
	s_setprio 1
	v_mfma_i32_16x16x64_i8 v[116:119], v[182:185], v[198:201], v[116:119]
	v_mfma_i32_16x16x64_i8 v[112:115], v[190:193], v[198:201], v[112:115]
	v_mfma_i32_16x16x64_i8 v[104:107], v[182:185], v[206:209], v[104:107]
	v_mfma_i32_16x16x64_i8 v[96:99], v[190:193], v[206:209], v[96:99]
	v_mfma_i32_16x16x64_i8 v[88:91], v[182:185], v[218:221], v[88:91]
	v_mfma_i32_16x16x64_i8 v[80:83], v[190:193], v[218:221], v[80:83]
	v_mfma_i32_16x16x64_i8 v[72:75], v[182:185], v[226:229], v[72:75]
	v_mfma_i32_16x16x64_i8 v[64:67], v[190:193], v[226:229], v[64:67]
	v_mfma_i32_16x16x64_i8 v[116:119], v[186:189], v[202:205], v[116:119]
	v_mfma_i32_16x16x64_i8 v[112:115], v[194:197], v[202:205], v[112:115]
	v_mfma_i32_16x16x64_i8 v[104:107], v[186:189], v[214:217], v[104:107]
	v_mfma_i32_16x16x64_i8 v[96:99], v[194:197], v[214:217], v[96:99]
	v_mfma_i32_16x16x64_i8 v[88:91], v[186:189], v[222:225], v[88:91]
	v_mfma_i32_16x16x64_i8 v[80:83], v[194:197], v[222:225], v[80:83]
	v_mfma_i32_16x16x64_i8 v[72:75], v[186:189], v[230:233], v[72:75]
	v_mfma_i32_16x16x64_i8 v[64:67], v[194:197], v[230:233], v[64:67]
	s_setprio 0
	s_barrier
	s_add_i32 s33, s60, s48
	v_lshl_add_u64 v[210:211], s[44:45], 0, v[132:133]
	s_mov_b32 m0, s33
	ds_read_b128 v[198:201], v153 offset:16384
	ds_read_b128 v[202:205], v153 offset:17408
	ds_read_b128 v[206:209], v153 offset:18432
	ds_read_b128 v[214:217], v153 offset:19456
	ds_read_b128 v[218:221], v153 offset:20480
	ds_read_b128 v[222:225], v153 offset:21504
	ds_read_b128 v[226:229], v153 offset:22528
	ds_read_b128 v[230:233], v153 offset:23552
	global_load_lds_dwordx4 v[210:211], off
	s_add_i32 m0, s33, 0x2000
	s_add_u32 s68, s44, 0x40000
	v_lshl_add_u64 v[234:235], s[44:45], 0, v[128:129]
	s_addc_u32 s69, s45, 0
	s_add_i32 s33, s61, s48
	global_load_lds_dwordx4 v[234:235], off
	v_lshl_add_u64 v[236:237], s[68:69], 0, v[132:133]
	s_mov_b32 m0, s33
	v_lshl_add_u64 v[238:239], s[46:47], 0, v[130:131]
	global_load_lds_dwordx4 v[236:237], off
	v_lshl_add_u64 v[236:237], s[68:69], 0, v[128:129]
	s_add_i32 m0, s33, 0x2000
	s_nop 0
	global_load_lds_dwordx4 v[236:237], off
	v_lshl_add_u64 v[236:237], s[46:47], 0, v[134:135]
	s_mov_b32 m0, s51
	s_nop 0
	global_load_lds_dwordx4 v[236:237], off
	s_mov_b32 m0, s52
	s_nop 0
	global_load_lds_dwordx4 v[238:239], off
	s_waitcnt vmcnt(8)
	s_waitcnt lgkmcnt(0)
	s_barrier
; #define PG8_STAGE(bufoff, gbase, voff) do { _Pragma("unroll") for (int _i = 0; _i < 2; ++_i) \
;         __builtin_amdgcn_global_load_lds((const unsigned*)((const char*)(gbase) + (voff)[_i]), (PG8_LAS unsigned*)(lds + (bufoff) + ldsw + _i * 8192), 16, 0, 0); } while (0)
; #define PG8_WAIT_V(n) asm volatile("s_waitcnt vmcnt(" #n ")" ::: "memory")
; #define PG8_WAIT_L(n) asm volatile("s_waitcnt lgkmcnt(" #n ")" ::: "memory")
; #define PG8_BAR __builtin_amdgcn_s_barrier()
; #define PG8_SCHED __builtin_amdgcn_sched_barrier(0)
;     __device__ __forceinline__ void operator()(const f32x4 (&acc)[2][2][4][2], const Unit& u, int wr, int wc, int fr, int fq, const float (&pr)[8]) const {
;     ...
;             for (int n = 0; n < 2; ++n) { const u32x4 a = *(const u32x4*)(colmax + u.pn * BM + wc * 32 + 8 * fq + 4 * n), b = *(const u32x4*)(colmax + u.pn * BM + HALF + wc * 32 + 8 * fq + 4 * n);
;                 csg[n] = (f32x4){__uint_as_float(a.x), __uint_as_float(a.y), __uint_as_float(a.z), __uint_as_float(a.w)} * (1.0f / 127.0f);
;                 csu[n] = (f32x4){__uint_as_float(b.x), __uint_as_float(b.y), __uint_as_float(b.z), __uint_as_float(b.w)} * (1.0f / 127.0f); }
;     ...
;             PG8_WAIT_V(8); PG8_WAIT_L(0); PG8_BAR; PG8_MMA(0, 0, At, B0); PG8_MMA(0, 1, At, B1); PG8_BAR; PG8_SCHED;
;             PG8_LDA(At, 0, 1); PG8_STAGE(PG8_SB(0, 0), b2, voffB); PG8_STAGE(PG8_SB(0, 1), b2 + hstep, voffB); PG8_STAGE(PG8_SA(0, 0), a2, voffA);
;             PG8_WAIT_V(8); PG8_WAIT_L(0); PG8_BAR; PG8_MMA(1, 0, At, B0); PG8_MMA(1, 1, At, B1); PG8_BAR; PG8_SCHED;
;             PG8_LDB(B0, 1, 0); PG8_LDB(B1, 1, 1); PG8_SCHED; PG8_LDA(At, 1, 0); PG8_STAGE(PG8_SA(0, 1), a2 + hstep, voffA);
;             PG8_WAIT_V(8); PG8_WAIT_L(0); PG8_BAR; PG8_MMA(0, 0, At, B0); PG8_MMA(0, 1, At, B1); PG8_BAR; PG8_SCHED;
;             PG8_LDA(At, 1, 1); PG8_STAGE(PG8_SB(1, 0), b3, voffB); PG8_STAGE(PG8_SB(1, 1), b3 + hstep, voffB); PG8_STAGE(PG8_SA(1, 0), a3, voffA);
;             PG8_WAIT_V(8); PG8_WAIT_L(0); PG8_BAR; PG8_MMA(1, 0, At, B0); PG8_MMA(1, 1, At, B1); PG8_BAR; PG8_SCHED;
	s_setprio 1
	s_waitcnt lgkmcnt(0)
	v_mfma_i32_16x16x64_i8 v[60:63], v[166:169], v[198:201], v[60:63]
	v_mfma_i32_16x16x64_i8 v[52:55], v[174:177], v[198:201], v[52:55]
	v_mfma_i32_16x16x64_i8 v[44:47], v[166:169], v[206:209], v[44:47]
	v_mfma_i32_16x16x64_i8 v[36:39], v[174:177], v[206:209], v[36:39]
	v_mfma_i32_16x16x64_i8 v[28:31], v[166:169], v[218:221], v[28:31]
	v_mfma_i32_16x16x64_i8 v[20:23], v[174:177], v[218:221], v[20:23]
	v_mfma_i32_16x16x64_i8 v[12:15], v[166:169], v[226:229], v[12:15]
	v_mfma_i32_16x16x64_i8 v[4:7], v[174:177], v[226:229], v[4:7]
	v_mfma_i32_16x16x64_i8 v[60:63], v[170:173], v[202:205], v[60:63]
	v_mfma_i32_16x16x64_i8 v[52:55], v[178:181], v[202:205], v[52:55]
	v_mfma_i32_16x16x64_i8 v[44:47], v[170:173], v[214:217], v[44:47]
	v_mfma_i32_16x16x64_i8 v[36:39], v[178:181], v[214:217], v[36:39]
	v_mfma_i32_16x16x64_i8 v[28:31], v[170:173], v[222:225], v[28:31]
	v_mfma_i32_16x16x64_i8 v[20:23], v[178:181], v[222:225], v[20:23]
	v_mfma_i32_16x16x64_i8 v[12:15], v[170:173], v[230:233], v[12:15]
	v_mfma_i32_16x16x64_i8 v[4:7], v[178:181], v[230:233], v[4:7]
	s_setprio 0
	s_setprio 1
	v_mfma_i32_16x16x64_i8 v[56:59], v[182:185], v[198:201], v[56:59]
	v_mfma_i32_16x16x64_i8 v[48:51], v[190:193], v[198:201], v[48:51]
	v_mfma_i32_16x16x64_i8 v[40:43], v[182:185], v[206:209], v[40:43]
	v_mfma_i32_16x16x64_i8 v[32:35], v[190:193], v[206:209], v[32:35]
	v_mfma_i32_16x16x64_i8 v[24:27], v[182:185], v[218:221], v[24:27]
	v_mfma_i32_16x16x64_i8 v[16:19], v[190:193], v[218:221], v[16:19]
	v_mfma_i32_16x16x64_i8 v[8:11], v[182:185], v[226:229], v[8:11]
	v_mfma_i32_16x16x64_i8 v[0:3], v[190:193], v[226:229], v[0:3]
	v_mfma_i32_16x16x64_i8 v[56:59], v[186:189], v[202:205], v[56:59]
	v_mfma_i32_16x16x64_i8 v[48:51], v[194:197], v[202:205], v[48:51]
	v_mfma_i32_16x16x64_i8 v[40:43], v[186:189], v[214:217], v[40:43]
	v_mfma_i32_16x16x64_i8 v[32:35], v[194:197], v[214:217], v[32:35]
	v_mfma_i32_16x16x64_i8 v[24:27], v[186:189], v[222:225], v[24:27]
	v_mfma_i32_16x16x64_i8 v[16:19], v[194:197], v[222:225], v[16:19]
	v_mfma_i32_16x16x64_i8 v[8:11], v[186:189], v[230:233], v[8:11]
	v_mfma_i32_16x16x64_i8 v[0:3], v[194:197], v[230:233], v[0:3]
	s_setprio 0
	s_barrier
	s_add_i32 s33, 0, 0x18000
	v_add_u32_e32 v157, s33, v149
	s_add_i32 s68, 0, 0x1c000
	ds_read_b128 v[166:169], v157
	ds_read_b128 v[170:173], v157 offset:1024
	ds_read_b128 v[174:177], v157 offset:2048
	ds_read_b128 v[178:181], v157 offset:3072
	v_add_u32_e32 v157, s68, v149
	ds_read_b128 v[182:185], v157
	ds_read_b128 v[186:189], v157 offset:1024
	ds_read_b128 v[190:193], v157 offset:2048
	ds_read_b128 v[194:197], v157 offset:3072
	s_add_u32 s46, s46, 0x40000
	s_addc_u32 s47, s47, 0
	s_mov_b32 m0, s53
	v_lshl_add_u64 v[240:241], s[46:47], 0, v[134:135]
	ds_read_b128 v[198:201], v153 offset:32768
	ds_read_b128 v[202:205], v153 offset:33792
	ds_read_b128 v[206:209], v153 offset:34816
	ds_read_b128 v[214:217], v153 offset:35840
	ds_read_b128 v[218:221], v153 offset:36864
	ds_read_b128 v[222:225], v153 offset:37888
	ds_read_b128 v[226:229], v153 offset:38912
	ds_read_b128 v[230:233], v153 offset:39936
	global_load_lds_dwordx4 v[240:241], off
	v_lshl_add_u64 v[240:241], s[46:47], 0, v[130:131]
	s_mov_b32 m0, s54
	s_nop 0
	global_load_lds_dwordx4 v[240:241], off
	s_waitcnt vmcnt(8)
	s_waitcnt lgkmcnt(0)
	s_barrier
	s_setprio 1
	s_waitcnt lgkmcnt(0)
	v_mfma_i32_16x16x64_i8 v[124:127], v[166:169], v[198:201], v[124:127]
	v_mfma_i32_16x16x64_i8 v[120:123], v[174:177], v[198:201], v[120:123]
	v_mfma_i32_16x16x64_i8 v[108:111], v[166:169], v[206:209], v[108:111]
	v_mfma_i32_16x16x64_i8 v[100:103], v[174:177], v[206:209], v[100:103]
	v_mfma_i32_16x16x64_i8 v[92:95], v[166:169], v[218:221], v[92:95]
	v_mfma_i32_16x16x64_i8 v[84:87], v[174:177], v[218:221], v[84:87]
	v_mfma_i32_16x16x64_i8 v[76:79], v[166:169], v[226:229], v[76:79]
	v_mfma_i32_16x16x64_i8 v[68:71], v[174:177], v[226:229], v[68:71]
	v_mfma_i32_16x16x64_i8 v[124:127], v[170:173], v[202:205], v[124:127]
	v_mfma_i32_16x16x64_i8 v[120:123], v[178:181], v[202:205], v[120:123]
	v_mfma_i32_16x16x64_i8 v[108:111], v[170:173], v[214:217], v[108:111]
	v_mfma_i32_16x16x64_i8 v[100:103], v[178:181], v[214:217], v[100:103]
	v_mfma_i32_16x16x64_i8 v[92:95], v[170:173], v[222:225], v[92:95]
	v_mfma_i32_16x16x64_i8 v[84:87], v[178:181], v[222:225], v[84:87]
	v_mfma_i32_16x16x64_i8 v[76:79], v[170:173], v[230:233], v[76:79]
	v_mfma_i32_16x16x64_i8 v[68:71], v[178:181], v[230:233], v[68:71]
	s_setprio 0
	s_setprio 1
	v_mfma_i32_16x16x64_i8 v[116:119], v[182:185], v[198:201], v[116:119]
	v_mfma_i32_16x16x64_i8 v[112:115], v[190:193], v[198:201], v[112:115]
	v_mfma_i32_16x16x64_i8 v[104:107], v[182:185], v[206:209], v[104:107]
	v_mfma_i32_16x16x64_i8 v[96:99], v[190:193], v[206:209], v[96:99]
	v_mfma_i32_16x16x64_i8 v[88:91], v[182:185], v[218:221], v[88:91]
	v_mfma_i32_16x16x64_i8 v[80:83], v[190:193], v[218:221], v[80:83]
	v_mfma_i32_16x16x64_i8 v[72:75], v[182:185], v[226:229], v[72:75]
	v_mfma_i32_16x16x64_i8 v[64:67], v[190:193], v[226:229], v[64:67]
	v_mfma_i32_16x16x64_i8 v[116:119], v[186:189], v[202:205], v[116:119]
	v_mfma_i32_16x16x64_i8 v[112:115], v[194:197], v[202:205], v[112:115]
	v_mfma_i32_16x16x64_i8 v[104:107], v[186:189], v[214:217], v[104:107]
	v_mfma_i32_16x16x64_i8 v[96:99], v[194:197], v[214:217], v[96:99]
	v_mfma_i32_16x16x64_i8 v[88:91], v[186:189], v[222:225], v[88:91]
	v_mfma_i32_16x16x64_i8 v[80:83], v[194:197], v[222:225], v[80:83]
	v_mfma_i32_16x16x64_i8 v[72:75], v[186:189], v[230:233], v[72:75]
	v_mfma_i32_16x16x64_i8 v[64:67], v[194:197], v[230:233], v[64:67]
	s_setprio 0
	s_barrier
	s_add_i32 s33, s33, s48
	v_lshl_add_u64 v[210:211], v[210:211], 0, s[10:11]
	s_mov_b32 m0, s33
	ds_read_b128 v[198:201], v153 offset:49152
	ds_read_b128 v[202:205], v153 offset:50176
	ds_read_b128 v[206:209], v153 offset:51200
	ds_read_b128 v[214:217], v153 offset:52224
	ds_read_b128 v[218:221], v153 offset:53248
	ds_read_b128 v[222:225], v153 offset:54272
	ds_read_b128 v[226:229], v153 offset:55296
	ds_read_b128 v[230:233], v153 offset:56320
	global_load_lds_dwordx4 v[210:211], off
	s_add_i32 m0, s33, 0x2000
	s_add_u32 s44, s44, 0x40080
	v_lshl_add_u64 v[210:211], v[234:235], 0, s[10:11]
	s_addc_u32 s45, s45, 0
	s_add_i32 s33, s68, s48
	global_load_lds_dwordx4 v[210:211], off
	v_lshl_add_u64 v[210:211], s[44:45], 0, v[132:133]
	s_mov_b32 m0, s33
	s_nop 0
	global_load_lds_dwordx4 v[210:211], off
	v_lshl_add_u64 v[210:211], s[44:45], 0, v[128:129]
	s_add_i32 m0, s33, 0x2000
	s_nop 0
	global_load_lds_dwordx4 v[210:211], off
	v_lshl_add_u64 v[210:211], v[236:237], 0, s[10:11]
	s_mov_b32 m0, s56
	s_nop 0
	global_load_lds_dwordx4 v[210:211], off
	v_lshl_add_u64 v[210:211], v[238:239], 0, s[10:11]
	s_mov_b32 m0, s57
	s_nop 0
	global_load_lds_dwordx4 v[210:211], off
	s_waitcnt vmcnt(8)
	s_waitcnt lgkmcnt(0)
	s_barrier
	s_cmp_eq_u32 s67, 12
	s_cbranch_scc1 .Lp9_cm_load
; #define PG8_STAGE(bufoff, gbase, voff) do { _Pragma("unroll") for (int _i = 0; _i < 2; ++_i) \
;         __builtin_amdgcn_global_load_lds((const unsigned*)((const char*)(gbase) + (voff)[_i]), (PG8_LAS unsigned*)(lds + (bufoff) + ldsw + _i * 8192), 16, 0, 0); } while (0)
; #define PG8_WAIT_V(n) asm volatile("s_waitcnt vmcnt(" #n ")" ::: "memory")
; #define PG8_WAIT_L(n) asm volatile("s_waitcnt lgkmcnt(" #n ")" ::: "memory")
; #define PG8_BAR __builtin_amdgcn_s_barrier()
; #define PG8_SCHED __builtin_amdgcn_sched_barrier(0)
;     ...
;         for (int t = 0; t < nt; t += 2) {
;             const bool last = (t == nt - 2);
;             const char* a1 = cA + (size_t)(t + 1) * kstep;
;             const char* a2 = last ? nA : cA + (size_t)(t + 2) * kstep; const char* b2 = last ? nB : cB + (size_t)(t + 2) * kstep;
;             const char* a3 = a2 + kstep; const char* b3 = b2 + kstep;
;             if (last && has_next) S.a_ready(nxt);
;             if (last) E.pre(pre, cur, wr, fr);
;             if constexpr (MIDK > 0) { if (t == MIDK / BK) E.mid(acc, cur, wr, wc, fr, fq); }
;             if constexpr (SP2) {
;             PG8_LDB(B0, 0, 0); PG8_LDB(B1, 0, 1); PG8_SCHED; PG8_LDA(At, 0, 0); PG8_STAGE(PG8_SA(1, 1), a1 + hstep, voffA);
;             PG8_WAIT_V(8); PG8_WAIT_L(0); PG8_BAR; PG8_MMA(0, 0, At, B0); PG8_MMA(0, 1, At, B1); PG8_BAR; PG8_SCHED;
;             PG8_LDA(At, 0, 1); PG8_STAGE(PG8_SB(0, 0), b2, voffB); PG8_STAGE(PG8_SB(0, 1), b2 + hstep, voffB); PG8_STAGE(PG8_SA(0, 0), a2, voffA);
;             PG8_WAIT_V(8); PG8_WAIT_L(0); PG8_BAR; PG8_MMA(1, 0, At, B0); PG8_MMA(1, 1, At, B1); PG8_BAR; PG8_SCHED;
;             PG8_LDB(B0, 1, 0); PG8_LDB(B1, 1, 1); PG8_SCHED; PG8_LDA(At, 1, 0); PG8_STAGE(PG8_SA(0, 1), a2 + hstep, voffA);
;             PG8_WAIT_V(8); PG8_WAIT_L(0); PG8_BAR; PG8_MMA(0, 0, At, B0); PG8_MMA(0, 1, At, B1); PG8_BAR; PG8_SCHED;
;             PG8_LDA(At, 1, 1); PG8_STAGE(PG8_SB(1, 0), b3, voffB); PG8_STAGE(PG8_SB(1, 1), b3 + hstep, voffB); PG8_STAGE(PG8_SA(1, 0), a3, voffA);
;             PG8_WAIT_V(8); PG8_WAIT_L(0); PG8_BAR; PG8_MMA(1, 0, At, B0); PG8_MMA(1, 1, At, B1); PG8_BAR; PG8_SCHED;
.Lp9_cm_back:
	s_setprio 1
	s_waitcnt lgkmcnt(0)
	v_mfma_i32_16x16x64_i8 v[60:63], v[166:169], v[198:201], v[60:63]
	v_mfma_i32_16x16x64_i8 v[52:55], v[174:177], v[198:201], v[52:55]
	v_mfma_i32_16x16x64_i8 v[44:47], v[166:169], v[206:209], v[44:47]
	v_mfma_i32_16x16x64_i8 v[36:39], v[174:177], v[206:209], v[36:39]
	v_mfma_i32_16x16x64_i8 v[28:31], v[166:169], v[218:221], v[28:31]
	v_mfma_i32_16x16x64_i8 v[20:23], v[174:177], v[218:221], v[20:23]
	v_mfma_i32_16x16x64_i8 v[12:15], v[166:169], v[226:229], v[12:15]
	v_mfma_i32_16x16x64_i8 v[4:7], v[174:177], v[226:229], v[4:7]
	v_mfma_i32_16x16x64_i8 v[60:63], v[170:173], v[202:205], v[60:63]
	v_mfma_i32_16x16x64_i8 v[52:55], v[178:181], v[202:205], v[52:55]
	v_mfma_i32_16x16x64_i8 v[44:47], v[170:173], v[214:217], v[44:47]
	v_mfma_i32_16x16x64_i8 v[36:39], v[178:181], v[214:217], v[36:39]
	v_mfma_i32_16x16x64_i8 v[28:31], v[170:173], v[222:225], v[28:31]
	v_mfma_i32_16x16x64_i8 v[20:23], v[178:181], v[222:225], v[20:23]
	v_mfma_i32_16x16x64_i8 v[12:15], v[170:173], v[230:233], v[12:15]
	v_mfma_i32_16x16x64_i8 v[4:7], v[178:181], v[230:233], v[4:7]
	s_setprio 0
	s_setprio 1
	v_mfma_i32_16x16x64_i8 v[56:59], v[182:185], v[198:201], v[56:59]
	v_mfma_i32_16x16x64_i8 v[48:51], v[190:193], v[198:201], v[48:51]
	v_mfma_i32_16x16x64_i8 v[40:43], v[182:185], v[206:209], v[40:43]
	v_mfma_i32_16x16x64_i8 v[32:35], v[190:193], v[206:209], v[32:35]
	v_mfma_i32_16x16x64_i8 v[24:27], v[182:185], v[218:221], v[24:27]
	v_mfma_i32_16x16x64_i8 v[16:19], v[190:193], v[218:221], v[16:19]
	v_mfma_i32_16x16x64_i8 v[8:11], v[182:185], v[226:229], v[8:11]
	v_mfma_i32_16x16x64_i8 v[0:3], v[190:193], v[226:229], v[0:3]
	v_mfma_i32_16x16x64_i8 v[56:59], v[186:189], v[202:205], v[56:59]
	v_mfma_i32_16x16x64_i8 v[48:51], v[194:197], v[202:205], v[48:51]
	v_mfma_i32_16x16x64_i8 v[40:43], v[186:189], v[214:217], v[40:43]
	v_mfma_i32_16x16x64_i8 v[32:35], v[194:197], v[214:217], v[32:35]
	v_mfma_i32_16x16x64_i8 v[24:27], v[186:189], v[222:225], v[24:27]
	v_mfma_i32_16x16x64_i8 v[16:19], v[194:197], v[222:225], v[16:19]
	v_mfma_i32_16x16x64_i8 v[8:11], v[186:189], v[230:233], v[8:11]
	v_mfma_i32_16x16x64_i8 v[0:3], v[194:197], v[230:233], v[0:3]
	s_setprio 0
	s_barrier
	s_add_i32 s67, s67, 2
	s_add_u32 s42, s42, 0x100
	s_addc_u32 s43, s43, 0
	s_add_u32 s65, s65, 0x100
	s_addc_u32 s66, s66, 0
	s_cmp_gt_u32 s67, 13
	s_cbranch_scc1 .LBB0_854

; __device__ __forceinline__ unsigned pack4_fp8(const f32x4 v) { int w = __builtin_amdgcn_cvt_pk_fp8_f32(clamp448(v[0]), clamp448(v[1]), 0, false); w = __builtin_amdgcn_cvt_pk_fp8_f32(clamp448(v[2]), clamp448(v[3]), w, true); return (unsigned)w; }
; __device__ __forceinline__ float silu_f(float g) { return g * fast_rcp(1.0f + fast_exp(-g)); }
;     __device__ __forceinline__ void operator()(const f32x4 (&acc)[2][2][4][2], const Unit& u, int wr, int wc, int fr, int fq, const float (&pr)[8]) const {
;         const int row0 = u.pm * BM + wr * 64 + fr, col0 = u.pn * 128 + wc * 32 + 8 * fq;
;         f32x4 csg[2], csu[2];
;         if constexpr (I8IN) {
; #pragma unroll
;             for (int n = 0; n < 2; ++n) { const u32x4 a = *(const u32x4*)(colmax + u.pn * BM + wc * 32 + 8 * fq + 4 * n), b = *(const u32x4*)(colmax + u.pn * BM + HALF + wc * 32 + 8 * fq + 4 * n);
;                 csg[n] = (f32x4){__uint_as_float(a.x), __uint_as_float(a.y), __uint_as_float(a.z), __uint_as_float(a.w)} * (1.0f / 127.0f);
;                 csu[n] = (f32x4){__uint_as_float(b.x), __uint_as_float(b.y), __uint_as_float(b.z), __uint_as_float(b.w)} * (1.0f / 127.0f); }
;         }
; #pragma unroll
;         for (int ai = 0; ai < 2; ++ai)
; #pragma unroll
;             for (int m = 0; m < 4; ++m) { const int row = row0 + ai * HALF + m * 16; const float s = pr[ai * 4 + m];
;                 f32x4 h[2];
; #pragma unroll
;                 for (int n = 0; n < 2; ++n) { f32x4 g, uu;
;                     if constexpr (I8IN) { const i32x4 gi = __builtin_bit_cast(i32x4, acc[ai][0][m][n]), ui = __builtin_bit_cast(i32x4, acc[ai][1][m][n]);
;                         g = (f32x4){(float)gi[0], (float)gi[1], (float)gi[2], (float)gi[3]} * (csg[n] * s); uu = (f32x4){(float)ui[0], (float)ui[1], (float)ui[2], (float)ui[3]} * (csu[n] * s); }
;                     else { g = acc[ai][0][m][n] * s; uu = acc[ai][1][m][n] * s; }
; #pragma unroll
;                     for (int j = 0; j < 4; ++j) h[n][j] = silu_f(g[j]) * uu[j]; }
;                 if constexpr (F8OUT) { u32x2 w; w.x = pack4_fp8(h[0] * hscale); w.y = pack4_fp8(h[1] * hscale); *(u32x2*)((unsigned char*)H + (size_t)row * ldh + col0) = w; }
.LBB0_856:
	s_lshl_b32 s34, s64, 8
	s_ashr_i32 s35, s34, 31
	v_cvt_f32_i32_e32 v183, v125
	v_cvt_f32_i32_e32 v182, v124
	v_cvt_f32_i32_e32 v187, v121
	v_cvt_f32_i32_e32 v186, v120
	v_cvt_f32_i32_e32 v185, v127
	v_cvt_f32_i32_e32 v184, v126
	v_cvt_f32_i32_e32 v191, v119
	v_cvt_f32_i32_e32 v190, v118
	v_cvt_f32_i32_e32 v193, v123
	v_cvt_f32_i32_e32 v192, v122
	v_cvt_f32_i32_e32 v189, v117
	v_cvt_f32_i32_e32 v188, v116
	v_cvt_f32_i32_e32 v195, v113
	v_cvt_f32_i32_e32 v194, v112
	v_cvt_f32_i32_e32 v197, v115
	v_cvt_f32_i32_e32 v196, v114
	v_mov_b32_e32 v198, 0
	v_mov_b32_e32 v199, 0
	v_cvt_f32_i32_e32 v111, v111
	v_cvt_f32_i32_e32 v110, v110
	v_lshl_or_b32 v164, s64, 7, v151
	v_ashrrev_i32_e32 v165, 31, v164
	v_cvt_f32_i32_e32 v101, v101
	v_cvt_f32_i32_e32 v100, v100
	v_cvt_f32_i32_e32 v105, v105
	v_cvt_f32_i32_e32 v104, v104
	v_cvt_f32_i32_e32 v107, v107
	v_cvt_f32_i32_e32 v106, v106
	v_cvt_f32_i32_e32 v103, v103
	v_cvt_f32_i32_e32 v102, v102
	v_cvt_f32_i32_e32 v97, v97
	v_cvt_f32_i32_e32 v96, v96
	v_cvt_f32_i32_e32 v99, v99
	v_cvt_f32_i32_e32 v98, v98
	v_cvt_f32_i32_e32 v93, v93
	v_cvt_f32_i32_e32 v92, v92
	v_cvt_f32_i32_e32 v95, v95
	v_cvt_f32_i32_e32 v94, v94
	v_cvt_f32_i32_e32 v91, v91
	v_cvt_f32_i32_e32 v90, v90
	v_cvt_f32_i32_e32 v89, v89
	v_cvt_f32_i32_e32 v88, v88
	v_cvt_f32_i32_e32 v85, v85
	v_cvt_f32_i32_e32 v84, v84
	v_cvt_f32_i32_e32 v87, v87
	v_cvt_f32_i32_e32 v86, v86
	v_cvt_f32_i32_e32 v81, v81
	v_cvt_f32_i32_e32 v80, v80
	v_cvt_f32_i32_e32 v83, v83
	v_cvt_f32_i32_e32 v82, v82
	v_cvt_f32_i32_e32 v77, v77
	v_cvt_f32_i32_e32 v76, v76
	v_cvt_f32_i32_e32 v79, v79
	v_cvt_f32_i32_e32 v78, v78
	v_cvt_f32_i32_e32 v75, v75
	v_cvt_f32_i32_e32 v74, v74
	v_cvt_f32_i32_e32 v73, v73
	v_cvt_f32_i32_e32 v72, v72
	v_cvt_f32_i32_e32 v69, v69
	v_cvt_f32_i32_e32 v68, v68
	v_cvt_f32_i32_e32 v71, v71
	v_cvt_f32_i32_e32 v70, v70
	v_cvt_f32_i32_e32 v65, v65
	v_cvt_f32_i32_e32 v64, v64
	v_cvt_f32_i32_e32 v67, v67
	v_cvt_f32_i32_e32 v66, v66
	v_cvt_f32_i32_e32 v61, v61
	v_cvt_f32_i32_e32 v60, v60
	v_cvt_f32_i32_e32 v63, v63
	v_cvt_f32_i32_e32 v62, v62
	v_cvt_f32_i32_e32 v59, v59
	v_cvt_f32_i32_e32 v58, v58
	v_cvt_f32_i32_e32 v57, v57
	v_cvt_f32_i32_e32 v56, v56
	v_cvt_f32_i32_e32 v53, v53
	v_cvt_f32_i32_e32 v52, v52
	s_waitcnt vmcnt(0)
	v_mov_b64_e32 v[166:167], v[242:243]
	v_mov_b64_e32 v[168:169], v[244:245]
	v_mov_b64_e32 v[170:171], v[246:247]
	v_mov_b64_e32 v[172:173], v[248:249]
	v_mov_b64_e32 v[174:175], v[250:251]
	v_mov_b64_e32 v[176:177], v[252:253]
	v_mov_b32_e32 v178, v159
	v_mov_b32_e32 v179, v161
	v_mov_b32_e32 v180, v163
	v_mov_b32_e32 v181, v255
	v_pk_mul_f32 v[126:127], v[166:167], s[20:21] op_sel_hi:[1,0]
	v_pk_mul_f32 v[120:121], v[170:171], s[20:21] op_sel_hi:[1,0]
	v_pk_mul_f32 v[118:119], v[174:175], s[20:21] op_sel_hi:[1,0]
	v_pk_mul_f32 v[166:167], v[146:147], v[126:127] op_sel_hi:[0,1]
	v_pk_mul_f32 v[170:171], v[146:147], v[118:119] op_sel_hi:[0,1]
	v_pk_mul_f32 v[166:167], v[166:167], v[182:183]
	v_pk_mul_f32 v[170:171], v[170:171], v[186:187]
	v_mul_f32_e32 v157, 0xbfb8aa3b, v166
	v_mul_f32_e32 v159, 0xbfb8aa3b, v167
	v_mul_f32_e32 v182, 0xbfb8aa3b, v170
	v_mul_f32_e32 v183, 0xbfb8aa3b, v171
	v_exp_f32_e32 v157, v157
	v_exp_f32_e32 v159, v159
	v_pk_mul_f32 v[124:125], v[168:169], s[20:21] op_sel_hi:[1,0]
	v_exp_f32_e32 v182, v182
	v_exp_f32_e32 v183, v183
	v_pk_mul_f32 v[116:117], v[176:177], s[20:21] op_sel_hi:[1,0]
	v_pk_mul_f32 v[168:169], v[146:147], v[124:125] op_sel_hi:[0,1]
	v_pk_mul_f32 v[176:177], v[146:147], v[116:117] op_sel_hi:[0,1]
	v_pk_mul_f32 v[168:169], v[168:169], v[184:185]
	v_pk_mul_f32 v[176:177], v[176:177], v[192:193]
	v_mul_f32_e32 v161, 0xbfb8aa3b, v168
	v_mul_f32_e32 v163, 0xbfb8aa3b, v169
	v_add_f32_e32 v157, 1.0, v157
	v_add_f32_e32 v159, 1.0, v159
	v_mul_f32_e32 v184, 0xbfb8aa3b, v176
	v_mul_f32_e32 v185, 0xbfb8aa3b, v177
	v_exp_f32_e32 v161, v161
	v_exp_f32_e32 v163, v163
	v_add_f32_e32 v186, 1.0, v182
	v_add_f32_e32 v187, 1.0, v183
	v_rcp_f32_e32 v182, v157
	v_rcp_f32_e32 v183, v159
	v_exp_f32_e32 v184, v184
	v_exp_f32_e32 v185, v185
	v_rcp_f32_e32 v186, v186
	v_rcp_f32_e32 v187, v187
	v_pk_mul_f32 v[114:115], v[178:179], s[20:21] op_sel_hi:[1,0]
	v_pk_mul_f32 v[174:175], v[146:147], v[120:121] op_sel_hi:[0,1]
	v_pk_mul_f32 v[112:113], v[180:181], s[20:21] op_sel_hi:[1,0]
	v_pk_mul_f32 v[180:181], v[146:147], v[114:115] op_sel_hi:[0,1]
	v_pk_mul_f32 v[174:175], v[174:175], v[188:189]
	v_add_f32_e32 v161, 1.0, v161
	v_add_f32_e32 v163, 1.0, v163
	v_pk_mul_f32 v[166:167], v[166:167], v[182:183]
	v_pk_mul_f32 v[180:181], v[180:181], v[194:195]
	v_add_f32_e32 v188, 1.0, v184
	v_add_f32_e32 v189, 1.0, v185
	v_rcp_f32_e32 v184, v161
	v_rcp_f32_e32 v185, v163
	v_pk_mul_f32 v[170:171], v[170:171], v[186:187]
	v_pk_mul_f32 v[166:167], v[174:175], v[166:167]
	v_rcp_f32_e32 v188, v188
	v_rcp_f32_e32 v189, v189
	v_pk_mul_f32 v[170:171], v[180:181], v[170:171]
	v_pk_mul_f32 v[166:167], v[166:167], 4.0 op_sel_hi:[1,0]
	v_pk_mul_f32 v[122:123], v[172:173], s[20:21] op_sel_hi:[1,0]
	v_pk_mul_f32 v[170:171], v[170:171], 4.0 op_sel_hi:[1,0]
	v_med3_f32 v157, v166, s62, v155
	v_med3_f32 v159, v167, s62, v155
	v_pk_mul_f32 v[172:173], v[146:147], v[122:123] op_sel_hi:[0,1]
	v_med3_f32 v166, v170, s62, v155
	v_cvt_pk_fp8_f32 v198, v157, v159
	v_med3_f32 v157, v171, s62, v155
	v_pk_mul_f32 v[178:179], v[146:147], v[112:113] op_sel_hi:[0,1]
	v_pk_mul_f32 v[172:173], v[172:173], v[190:191]
	v_pk_mul_f32 v[168:169], v[168:169], v[184:185]
	v_cvt_pk_fp8_f32 v199, v166, v157
	v_cvt_f32_i32_e32 v167, v109
	v_cvt_f32_i32_e32 v166, v108
	v_pk_mul_f32 v[178:179], v[178:179], v[196:197]
	v_pk_mul_f32 v[176:177], v[176:177], v[188:189]
; __device__ __forceinline__ float silu_f(float g) { return g * fast_rcp(1.0f + fast_exp(-g)); }
; __device__ __forceinline__ float clamp448(float v) { return __builtin_amdgcn_fmed3f(v, -448.0f, 448.0f); }
; __device__ __forceinline__ unsigned pack4_fp8(const f32x4 v) { int w = __builtin_amdgcn_cvt_pk_fp8_f32(clamp448(v[0]), clamp448(v[1]), 0, false); w = __builtin_amdgcn_cvt_pk_fp8_f32(clamp448(v[2]), clamp448(v[3]), w, true); return (unsigned)w; }
;     __device__ __forceinline__ void operator()(const f32x4 (&acc)[2][2][4][2], const Unit& u, int wr, int wc, int fr, int fq, const float (&pr)[8]) const {
;     ...
;             for (int m = 0; m < 4; ++m) { const int row = row0 + ai * HALF + m * 16; const float s = pr[ai * 4 + m];
;                 f32x4 h[2];
; #pragma unroll
;                 for (int n = 0; n < 2; ++n) { f32x4 g, uu;
;                     if constexpr (I8IN) { const i32x4 gi = __builtin_bit_cast(i32x4, acc[ai][0][m][n]), ui = __builtin_bit_cast(i32x4, acc[ai][1][m][n]);
;                         g = (f32x4){(float)gi[0], (float)gi[1], (float)gi[2], (float)gi[3]} * (csg[n] * s); uu = (f32x4){(float)ui[0], (float)ui[1], (float)ui[2], (float)ui[3]} * (csu[n] * s); }
;                     else { g = acc[ai][0][m][n] * s; uu = acc[ai][1][m][n] * s; }
; #pragma unroll
;                     for (int j = 0; j < 4; ++j) h[n][j] = silu_f(g[j]) * uu[j]; }
;                 if constexpr (F8OUT) { u32x2 w; w.x = pack4_fp8(h[0] * hscale); w.y = pack4_fp8(h[1] * hscale); *(u32x2*)((unsigned char*)H + (size_t)row * ldh + col0) = w; }
	v_pk_mul_f32 v[168:169], v[172:173], v[168:169]
	v_pk_mul_f32 v[172:173], v[178:179], v[176:177]
	v_pk_mul_f32 v[168:169], v[168:169], 4.0 op_sel_hi:[1,0]
	v_pk_mul_f32 v[172:173], v[172:173], 4.0 op_sel_hi:[1,0]
	v_med3_f32 v161, v168, s62, v155
	v_med3_f32 v163, v169, s62, v155
	v_pk_mul_f32 v[168:169], v[148:149], v[126:127] op_sel_hi:[0,1]
	v_med3_f32 v159, v172, s62, v155
	v_med3_f32 v157, v173, s62, v155
	v_pk_mul_f32 v[166:167], v[168:169], v[166:167]
	v_cvt_pk_fp8_f32 v199, v159, v157 op_sel:[0,0,1]
	v_mul_f32_e32 v157, 0xbfb8aa3b, v166
	v_exp_f32_e32 v157, v157
	v_mul_f32_e32 v159, 0xbfb8aa3b, v167
	v_cvt_pk_fp8_f32 v198, v161, v163 op_sel:[0,0,1]
	v_exp_f32_e32 v159, v159
	v_mov_b64_e32 v[108:109], s[14:15]
	v_mad_i64_i32 v[168:169], s[34:35], v162, s63, v[108:109]
	v_pk_mul_f32 v[170:171], v[148:149], v[124:125] op_sel_hi:[0,1]
	v_lshl_add_u64 v[168:169], v[168:169], 0, v[164:165]
	v_add_f32_e32 v157, 1.0, v157
	v_pk_mul_f32 v[110:111], v[170:171], v[110:111]
	global_store_dwordx2 v[168:169], v[198:199], off
	v_rcp_f32_e32 v168, v157
	v_add_f32_e32 v157, 1.0, v159
	v_mul_f32_e32 v159, 0xbfb8aa3b, v110
	v_exp_f32_e32 v159, v159
	v_mul_f32_e32 v161, 0xbfb8aa3b, v111
	v_rcp_f32_e32 v169, v157
	v_exp_f32_e32 v161, v161
	v_add_f32_e32 v157, 1.0, v159
	v_rcp_f32_e32 v170, v157
	v_pk_mul_f32 v[166:167], v[166:167], v[168:169]
	v_pk_mul_f32 v[168:169], v[148:149], v[118:119] op_sel_hi:[0,1]
	v_add_f32_e32 v157, 1.0, v161
	v_pk_mul_f32 v[100:101], v[168:169], v[100:101]
	v_rcp_f32_e32 v171, v157
	v_mul_f32_e32 v157, 0xbfb8aa3b, v100
	v_pk_mul_f32 v[174:175], v[148:149], v[120:121] op_sel_hi:[0,1]
	v_exp_f32_e32 v157, v157
	v_pk_mul_f32 v[104:105], v[174:175], v[104:105]
	v_pk_mul_f32 v[172:173], v[148:149], v[122:123] op_sel_hi:[0,1]
	v_pk_mul_f32 v[104:105], v[104:105], v[166:167]
	v_pk_mul_f32 v[166:167], v[148:149], v[116:117] op_sel_hi:[0,1]
	v_pk_mul_f32 v[106:107], v[172:173], v[106:107]
	v_pk_mul_f32 v[110:111], v[110:111], v[170:171]
	v_pk_mul_f32 v[102:103], v[166:167], v[102:103]
	v_pk_mul_f32 v[106:107], v[106:107], v[110:111]
	v_add_f32_e32 v110, 1.0, v157
	v_mul_f32_e32 v111, 0xbfb8aa3b, v101
	v_mul_f32_e32 v157, 0xbfb8aa3b, v102
	v_exp_f32_e32 v111, v111
	v_exp_f32_e32 v157, v157
	v_mul_f32_e32 v159, 0xbfb8aa3b, v103
	v_exp_f32_e32 v159, v159
	v_add_f32_e32 v111, 1.0, v111
	v_add_f32_e32 v157, 1.0, v157
	v_rcp_f32_e32 v110, v110
	v_rcp_f32_e32 v111, v111
	v_rcp_f32_e32 v166, v157
	v_add_f32_e32 v157, 1.0, v159
	v_rcp_f32_e32 v167, v157
	v_pk_mul_f32 v[170:171], v[148:149], v[114:115] op_sel_hi:[0,1]
	v_pk_mul_f32 v[168:169], v[148:149], v[112:113] op_sel_hi:[0,1]
	v_pk_mul_f32 v[96:97], v[170:171], v[96:97]
	v_pk_mul_f32 v[100:101], v[100:101], v[110:111]
	v_pk_mul_f32 v[98:99], v[168:169], v[98:99]
	v_pk_mul_f32 v[102:103], v[102:103], v[166:167]
	v_pk_mul_f32 v[96:97], v[96:97], v[100:101]
	v_pk_mul_f32 v[100:101], v[104:105], 4.0 op_sel_hi:[1,0]
	v_pk_mul_f32 v[98:99], v[98:99], v[102:103]
	v_med3_f32 v102, v100, s62, v155
	v_med3_f32 v101, v101, s62, v155
	v_mov_b32_e32 v100, 0
	v_cvt_pk_fp8_f32 v100, v102, v101
	v_pk_mul_f32 v[102:103], v[106:107], 4.0 op_sel_hi:[1,0]
	v_pk_mul_f32 v[96:97], v[96:97], 4.0 op_sel_hi:[1,0]
	v_med3_f32 v101, v102, s62, v155
	v_med3_f32 v102, v103, s62, v155
	v_cvt_pk_fp8_f32 v100, v101, v102 op_sel:[0,0,1]
	v_med3_f32 v96, v96, s62, v155
	v_med3_f32 v97, v97, s62, v155
	v_mov_b32_e32 v101, 0
	v_cvt_pk_fp8_f32 v101, v96, v97
	v_pk_mul_f32 v[98:99], v[98:99], 4.0 op_sel_hi:[1,0]
	v_or_b32_e32 v110, 16, v162
	v_med3_f32 v96, v98, s62, v155
	v_med3_f32 v97, v99, s62, v155
	v_cvt_pk_fp8_f32 v101, v96, v97 op_sel:[0,0,1]
	v_pk_mul_f32 v[96:97], v[150:151], v[126:127] op_sel_hi:[0,1]
	v_pk_mul_f32 v[92:93], v[96:97], v[92:93]
	v_pk_mul_f32 v[102:103], v[150:151], v[120:121] op_sel_hi:[0,1]
	v_mul_f32_e32 v96, 0xbfb8aa3b, v92
	v_exp_f32_e32 v98, v96
	v_mad_i64_i32 v[96:97], s[34:35], v110, s63, v[108:109]
	v_lshl_add_u64 v[96:97], v[96:97], 0, v[164:165]
	global_store_dwordx2 v[96:97], v[100:101], off
	v_add_f32_e32 v96, 1.0, v98
	v_pk_mul_f32 v[98:99], v[150:151], v[124:125] op_sel_hi:[0,1]
	v_pk_mul_f32 v[94:95], v[98:99], v[94:95]
	v_mul_f32_e32 v97, 0xbfb8aa3b, v93
	v_mul_f32_e32 v98, 0xbfb8aa3b, v94
	v_mul_f32_e32 v99, 0xbfb8aa3b, v95
	v_exp_f32_e32 v97, v97
	v_exp_f32_e32 v98, v98
	v_exp_f32_e32 v99, v99
	v_rcp_f32_e32 v96, v96
	v_add_f32_e32 v97, 1.0, v97
	v_add_f32_e32 v98, 1.0, v98
	v_add_f32_e32 v99, 1.0, v99
	v_rcp_f32_e32 v97, v97
	v_rcp_f32_e32 v98, v98
	v_rcp_f32_e32 v99, v99
	v_pk_mul_f32 v[100:101], v[150:151], v[122:123] op_sel_hi:[0,1]
	v_pk_mul_f32 v[90:91], v[100:101], v[90:91]
	v_pk_mul_f32 v[92:93], v[92:93], v[96:97]
	v_pk_mul_f32 v[96:97], v[150:151], v[118:119] op_sel_hi:[0,1]
	v_pk_mul_f32 v[94:95], v[94:95], v[98:99]
	v_pk_mul_f32 v[88:89], v[102:103], v[88:89]
	v_pk_mul_f32 v[84:85], v[96:97], v[84:85]
	v_pk_mul_f32 v[90:91], v[90:91], v[94:95]
	v_pk_mul_f32 v[94:95], v[150:151], v[116:117] op_sel_hi:[0,1]
	v_mul_f32_e32 v96, 0xbfb8aa3b, v84
	v_pk_mul_f32 v[88:89], v[88:89], v[92:93]
	v_mul_f32_e32 v93, 0xbfb8aa3b, v85
	v_pk_mul_f32 v[86:87], v[94:95], v[86:87]
	v_exp_f32_e32 v96, v96
	v_exp_f32_e32 v93, v93
	v_mul_f32_e32 v94, 0xbfb8aa3b, v86
	v_mul_f32_e32 v95, 0xbfb8aa3b, v87
	v_exp_f32_e32 v94, v94
	v_exp_f32_e32 v95, v95
	v_add_f32_e32 v92, 1.0, v96
	v_add_f32_e32 v93, 1.0, v93
	v_rcp_f32_e32 v92, v92
	v_rcp_f32_e32 v93, v93
	v_add_f32_e32 v94, 1.0, v94
	v_add_f32_e32 v95, 1.0, v95
	v_rcp_f32_e32 v94, v94
	v_rcp_f32_e32 v95, v95
	v_pk_mul_f32 v[98:99], v[150:151], v[114:115] op_sel_hi:[0,1]
	v_pk_mul_f32 v[96:97], v[150:151], v[112:113] op_sel_hi:[0,1]
; __device__ __forceinline__ float silu_f(float g) { return g * fast_rcp(1.0f + fast_exp(-g)); }
; __device__ __forceinline__ float clamp448(float v) { return __builtin_amdgcn_fmed3f(v, -448.0f, 448.0f); }
; __device__ __forceinline__ unsigned pack4_fp8(const f32x4 v) { int w = __builtin_amdgcn_cvt_pk_fp8_f32(clamp448(v[0]), clamp448(v[1]), 0, false); w = __builtin_amdgcn_cvt_pk_fp8_f32(clamp448(v[2]), clamp448(v[3]), w, true); return (unsigned)w; }
;     __device__ __forceinline__ void operator()(const f32x4 (&acc)[2][2][4][2], const Unit& u, int wr, int wc, int fr, int fq, const float (&pr)[8]) const {
;     ...
;             for (int m = 0; m < 4; ++m) { const int row = row0 + ai * HALF + m * 16; const float s = pr[ai * 4 + m];
;                 f32x4 h[2];
; #pragma unroll
;                 for (int n = 0; n < 2; ++n) { f32x4 g, uu;
;                     if constexpr (I8IN) { const i32x4 gi = __builtin_bit_cast(i32x4, acc[ai][0][m][n]), ui = __builtin_bit_cast(i32x4, acc[ai][1][m][n]);
;                         g = (f32x4){(float)gi[0], (float)gi[1], (float)gi[2], (float)gi[3]} * (csg[n] * s); uu = (f32x4){(float)ui[0], (float)ui[1], (float)ui[2], (float)ui[3]} * (csu[n] * s); }
;                     else { g = acc[ai][0][m][n] * s; uu = acc[ai][1][m][n] * s; }
; #pragma unroll
;                     for (int j = 0; j < 4; ++j) h[n][j] = silu_f(g[j]) * uu[j]; }
;                 if constexpr (F8OUT) { u32x2 w; w.x = pack4_fp8(h[0] * hscale); w.y = pack4_fp8(h[1] * hscale); *(u32x2*)((unsigned char*)H + (size_t)row * ldh + col0) = w; }
	v_pk_mul_f32 v[80:81], v[98:99], v[80:81]
	v_pk_mul_f32 v[84:85], v[84:85], v[92:93]
	v_pk_mul_f32 v[82:83], v[96:97], v[82:83]
	v_pk_mul_f32 v[86:87], v[86:87], v[94:95]
	v_pk_mul_f32 v[80:81], v[80:81], v[84:85]
	v_pk_mul_f32 v[84:85], v[88:89], 4.0 op_sel_hi:[1,0]
	v_pk_mul_f32 v[82:83], v[82:83], v[86:87]
	v_med3_f32 v86, v84, s62, v155
	v_med3_f32 v85, v85, s62, v155
	v_mov_b32_e32 v84, 0
	v_cvt_pk_fp8_f32 v84, v86, v85
	v_pk_mul_f32 v[86:87], v[90:91], 4.0 op_sel_hi:[1,0]
	v_pk_mul_f32 v[80:81], v[80:81], 4.0 op_sel_hi:[1,0]
	v_med3_f32 v85, v86, s62, v155
	v_med3_f32 v86, v87, s62, v155
	v_cvt_pk_fp8_f32 v84, v85, v86 op_sel:[0,0,1]
	v_med3_f32 v80, v80, s62, v155
	v_med3_f32 v81, v81, s62, v155
	v_mov_b32_e32 v85, 0
	v_cvt_pk_fp8_f32 v85, v80, v81
	v_pk_mul_f32 v[82:83], v[82:83], 4.0 op_sel_hi:[1,0]
	v_or_b32_e32 v92, 32, v162
	v_med3_f32 v80, v82, s62, v155
	v_med3_f32 v81, v83, s62, v155
	v_cvt_pk_fp8_f32 v85, v80, v81 op_sel:[0,0,1]
	v_pk_mul_f32 v[80:81], v[152:153], v[126:127] op_sel_hi:[0,1]
	v_pk_mul_f32 v[76:77], v[80:81], v[76:77]
	v_pk_mul_f32 v[86:87], v[152:153], v[120:121] op_sel_hi:[0,1]
	v_mul_f32_e32 v80, 0xbfb8aa3b, v76
	v_exp_f32_e32 v82, v80
	v_mad_i64_i32 v[80:81], s[34:35], v92, s63, v[108:109]
	v_lshl_add_u64 v[80:81], v[80:81], 0, v[164:165]
	global_store_dwordx2 v[80:81], v[84:85], off
	v_add_f32_e32 v80, 1.0, v82
	v_pk_mul_f32 v[82:83], v[152:153], v[124:125] op_sel_hi:[0,1]
	v_pk_mul_f32 v[78:79], v[82:83], v[78:79]
	v_mul_f32_e32 v81, 0xbfb8aa3b, v77
	v_mul_f32_e32 v82, 0xbfb8aa3b, v78
	v_mul_f32_e32 v83, 0xbfb8aa3b, v79
	v_exp_f32_e32 v81, v81
	v_exp_f32_e32 v82, v82
	v_exp_f32_e32 v83, v83
	v_rcp_f32_e32 v80, v80
	v_add_f32_e32 v81, 1.0, v81
	v_add_f32_e32 v82, 1.0, v82
	v_add_f32_e32 v83, 1.0, v83
	v_rcp_f32_e32 v81, v81
	v_rcp_f32_e32 v82, v82
	v_rcp_f32_e32 v83, v83
	v_pk_mul_f32 v[84:85], v[152:153], v[122:123] op_sel_hi:[0,1]
	v_pk_mul_f32 v[74:75], v[84:85], v[74:75]
	v_pk_mul_f32 v[76:77], v[76:77], v[80:81]
	v_pk_mul_f32 v[80:81], v[152:153], v[118:119] op_sel_hi:[0,1]
	v_pk_mul_f32 v[78:79], v[78:79], v[82:83]
	v_pk_mul_f32 v[72:73], v[86:87], v[72:73]
	v_pk_mul_f32 v[68:69], v[80:81], v[68:69]
	v_pk_mul_f32 v[74:75], v[74:75], v[78:79]
	v_pk_mul_f32 v[78:79], v[152:153], v[116:117] op_sel_hi:[0,1]
	v_mul_f32_e32 v80, 0xbfb8aa3b, v68
	v_pk_mul_f32 v[72:73], v[72:73], v[76:77]
	v_mul_f32_e32 v77, 0xbfb8aa3b, v69
	v_pk_mul_f32 v[70:71], v[78:79], v[70:71]
	v_exp_f32_e32 v80, v80
	v_exp_f32_e32 v77, v77
	v_mul_f32_e32 v78, 0xbfb8aa3b, v70
	v_mul_f32_e32 v79, 0xbfb8aa3b, v71
	v_exp_f32_e32 v78, v78
	v_exp_f32_e32 v79, v79
	v_add_f32_e32 v76, 1.0, v80
	v_add_f32_e32 v77, 1.0, v77
	v_rcp_f32_e32 v76, v76
	v_rcp_f32_e32 v77, v77
	v_add_f32_e32 v78, 1.0, v78
	v_add_f32_e32 v79, 1.0, v79
	v_rcp_f32_e32 v78, v78
	v_rcp_f32_e32 v79, v79
	v_pk_mul_f32 v[82:83], v[152:153], v[114:115] op_sel_hi:[0,1]
	v_pk_mul_f32 v[80:81], v[152:153], v[112:113] op_sel_hi:[0,1]
	v_pk_mul_f32 v[64:65], v[82:83], v[64:65]
	v_pk_mul_f32 v[68:69], v[68:69], v[76:77]
	v_pk_mul_f32 v[66:67], v[80:81], v[66:67]
	v_pk_mul_f32 v[70:71], v[70:71], v[78:79]
	v_pk_mul_f32 v[64:65], v[64:65], v[68:69]
	v_pk_mul_f32 v[68:69], v[72:73], 4.0 op_sel_hi:[1,0]
	v_pk_mul_f32 v[66:67], v[66:67], v[70:71]
	v_med3_f32 v70, v68, s62, v155
	v_med3_f32 v69, v69, s62, v155
	v_mov_b32_e32 v68, 0
	v_cvt_pk_fp8_f32 v68, v70, v69
	v_pk_mul_f32 v[70:71], v[74:75], 4.0 op_sel_hi:[1,0]
	v_pk_mul_f32 v[64:65], v[64:65], 4.0 op_sel_hi:[1,0]
	v_med3_f32 v69, v70, s62, v155
	v_med3_f32 v70, v71, s62, v155
	v_cvt_pk_fp8_f32 v68, v69, v70 op_sel:[0,0,1]
	v_med3_f32 v64, v64, s62, v155
	v_med3_f32 v65, v65, s62, v155
	v_mov_b32_e32 v69, 0
	v_cvt_pk_fp8_f32 v69, v64, v65
	v_pk_mul_f32 v[64:65], v[66:67], 4.0 op_sel_hi:[1,0]
	v_pk_mul_f32 v[66:67], v[154:155], v[126:127] op_sel_hi:[0,1]
	v_pk_mul_f32 v[60:61], v[66:67], v[60:61]
	v_med3_f32 v64, v64, s62, v155
	v_med3_f32 v65, v65, s62, v155
	v_mul_f32_e32 v66, 0xbfb8aa3b, v60
	v_cvt_pk_fp8_f32 v69, v64, v65 op_sel:[0,0,1]
	v_exp_f32_e32 v66, v66
	v_or_b32_e32 v76, 48, v162
	v_mad_i64_i32 v[64:65], s[34:35], v76, s63, v[108:109]
	v_lshl_add_u64 v[64:65], v[64:65], 0, v[164:165]
	global_store_dwordx2 v[64:65], v[68:69], off
	v_add_f32_e32 v64, 1.0, v66
	v_pk_mul_f32 v[66:67], v[154:155], v[124:125] op_sel_hi:[0,1]
	v_pk_mul_f32 v[62:63], v[66:67], v[62:63]
	v_mul_f32_e32 v65, 0xbfb8aa3b, v61
	v_mul_f32_e32 v66, 0xbfb8aa3b, v62
	v_mul_f32_e32 v67, 0xbfb8aa3b, v63
	v_exp_f32_e32 v65, v65
	v_exp_f32_e32 v66, v66
	v_exp_f32_e32 v67, v67
	v_rcp_f32_e32 v64, v64
	v_add_f32_e32 v65, 1.0, v65
	v_add_f32_e32 v66, 1.0, v66
	v_add_f32_e32 v67, 1.0, v67
	v_rcp_f32_e32 v65, v65
	v_rcp_f32_e32 v66, v66
	v_rcp_f32_e32 v67, v67
	v_cvt_f32_i32_e32 v55, v55
	v_cvt_f32_i32_e32 v54, v54
	v_pk_mul_f32 v[68:69], v[154:155], v[122:123] op_sel_hi:[0,1]
	v_pk_mul_f32 v[70:71], v[154:155], v[120:121] op_sel_hi:[0,1]
	v_pk_mul_f32 v[58:59], v[68:69], v[58:59]
	v_pk_mul_f32 v[60:61], v[60:61], v[64:65]
	v_pk_mul_f32 v[64:65], v[154:155], v[118:119] op_sel_hi:[0,1]
	v_pk_mul_f32 v[62:63], v[62:63], v[66:67]
	v_pk_mul_f32 v[56:57], v[70:71], v[56:57]
	v_pk_mul_f32 v[52:53], v[64:65], v[52:53]
	v_pk_mul_f32 v[58:59], v[58:59], v[62:63]
	v_pk_mul_f32 v[62:63], v[154:155], v[116:117] op_sel_hi:[0,1]
	v_mul_f32_e32 v64, 0xbfb8aa3b, v52
	v_pk_mul_f32 v[56:57], v[56:57], v[60:61]
	v_mul_f32_e32 v61, 0xbfb8aa3b, v53
	v_pk_mul_f32 v[54:55], v[62:63], v[54:55]
	v_exp_f32_e32 v64, v64
	v_exp_f32_e32 v61, v61
	v_mul_f32_e32 v62, 0xbfb8aa3b, v54
	v_mul_f32_e32 v63, 0xbfb8aa3b, v55
	v_exp_f32_e32 v62, v62
	v_exp_f32_e32 v63, v63
	v_add_f32_e32 v60, 1.0, v64
; __device__ __forceinline__ float silu_f(float g) { return g * fast_rcp(1.0f + fast_exp(-g)); }
; __device__ __forceinline__ float clamp448(float v) { return __builtin_amdgcn_fmed3f(v, -448.0f, 448.0f); }
; __device__ __forceinline__ unsigned pack4_fp8(const f32x4 v) { int w = __builtin_amdgcn_cvt_pk_fp8_f32(clamp448(v[0]), clamp448(v[1]), 0, false); w = __builtin_amdgcn_cvt_pk_fp8_f32(clamp448(v[2]), clamp448(v[3]), w, true); return (unsigned)w; }
;     __device__ __forceinline__ void operator()(const f32x4 (&acc)[2][2][4][2], const Unit& u, int wr, int wc, int fr, int fq, const float (&pr)[8]) const {
;     ...
;             for (int m = 0; m < 4; ++m) { const int row = row0 + ai * HALF + m * 16; const float s = pr[ai * 4 + m];
;                 f32x4 h[2];
; #pragma unroll
;                 for (int n = 0; n < 2; ++n) { f32x4 g, uu;
;                     if constexpr (I8IN) { const i32x4 gi = __builtin_bit_cast(i32x4, acc[ai][0][m][n]), ui = __builtin_bit_cast(i32x4, acc[ai][1][m][n]);
;                         g = (f32x4){(float)gi[0], (float)gi[1], (float)gi[2], (float)gi[3]} * (csg[n] * s); uu = (f32x4){(float)ui[0], (float)ui[1], (float)ui[2], (float)ui[3]} * (csu[n] * s); }
;                     else { g = acc[ai][0][m][n] * s; uu = acc[ai][1][m][n] * s; }
; #pragma unroll
;                     for (int j = 0; j < 4; ++j) h[n][j] = silu_f(g[j]) * uu[j]; }
;                 if constexpr (F8OUT) { u32x2 w; w.x = pack4_fp8(h[0] * hscale); w.y = pack4_fp8(h[1] * hscale); *(u32x2*)((unsigned char*)H + (size_t)row * ldh + col0) = w; }
	v_add_f32_e32 v61, 1.0, v61
	v_rcp_f32_e32 v60, v60
	v_rcp_f32_e32 v61, v61
	v_add_f32_e32 v62, 1.0, v62
	v_add_f32_e32 v63, 1.0, v63
	v_cvt_f32_i32_e32 v49, v49
	v_cvt_f32_i32_e32 v48, v48
	v_rcp_f32_e32 v62, v62
	v_rcp_f32_e32 v63, v63
	v_cvt_f32_i32_e32 v51, v51
	v_cvt_f32_i32_e32 v50, v50
	v_pk_mul_f32 v[66:67], v[154:155], v[114:115] op_sel_hi:[0,1]
	v_pk_mul_f32 v[64:65], v[154:155], v[112:113] op_sel_hi:[0,1]
	v_pk_mul_f32 v[48:49], v[66:67], v[48:49]
	v_pk_mul_f32 v[52:53], v[52:53], v[60:61]
	v_pk_mul_f32 v[50:51], v[64:65], v[50:51]
	v_pk_mul_f32 v[54:55], v[54:55], v[62:63]
	v_pk_mul_f32 v[48:49], v[48:49], v[52:53]
	v_pk_mul_f32 v[52:53], v[56:57], 4.0 op_sel_hi:[1,0]
	v_pk_mul_f32 v[50:51], v[50:51], v[54:55]
	v_med3_f32 v54, v52, s62, v155
	v_med3_f32 v53, v53, s62, v155
	v_mov_b32_e32 v52, 0
	v_cvt_pk_fp8_f32 v52, v54, v53
	v_pk_mul_f32 v[54:55], v[58:59], 4.0 op_sel_hi:[1,0]
	v_pk_mul_f32 v[48:49], v[48:49], 4.0 op_sel_hi:[1,0]
	v_med3_f32 v53, v54, s62, v155
	v_med3_f32 v54, v55, s62, v155
	v_cvt_pk_fp8_f32 v52, v53, v54 op_sel:[0,0,1]
	v_med3_f32 v48, v48, s62, v155
	v_med3_f32 v49, v49, s62, v155
	v_mov_b32_e32 v53, 0
	v_cvt_pk_fp8_f32 v53, v48, v49
	v_cvt_f32_i32_e32 v45, v45
	v_cvt_f32_i32_e32 v44, v44
	v_pk_mul_f32 v[50:51], v[50:51], 4.0 op_sel_hi:[1,0]
	v_add_u32_e32 v72, 0x80, v162
	v_med3_f32 v48, v50, s62, v155
	v_med3_f32 v49, v51, s62, v155
	v_cvt_pk_fp8_f32 v53, v48, v49 op_sel:[0,0,1]
	v_pk_mul_f32 v[48:49], v[156:157], v[126:127] op_sel_hi:[0,1]
	v_pk_mul_f32 v[44:45], v[48:49], v[44:45]
	v_cvt_f32_i32_e32 v47, v47
	v_mul_f32_e32 v48, 0xbfb8aa3b, v44
	v_exp_f32_e32 v50, v48
	v_cvt_f32_i32_e32 v46, v46
	v_mad_i64_i32 v[48:49], s[34:35], v72, s63, v[108:109]
	v_lshl_add_u64 v[48:49], v[48:49], 0, v[164:165]
	global_store_dwordx2 v[48:49], v[52:53], off
	v_add_f32_e32 v48, 1.0, v50
	v_pk_mul_f32 v[50:51], v[156:157], v[124:125] op_sel_hi:[0,1]
	v_pk_mul_f32 v[46:47], v[50:51], v[46:47]
	v_mul_f32_e32 v49, 0xbfb8aa3b, v45
	v_mul_f32_e32 v50, 0xbfb8aa3b, v46
	v_mul_f32_e32 v51, 0xbfb8aa3b, v47
	v_exp_f32_e32 v49, v49
	v_exp_f32_e32 v50, v50
	v_exp_f32_e32 v51, v51
	v_rcp_f32_e32 v48, v48
	v_add_f32_e32 v49, 1.0, v49
	v_add_f32_e32 v50, 1.0, v50
	v_add_f32_e32 v51, 1.0, v51
	v_rcp_f32_e32 v49, v49
	v_rcp_f32_e32 v50, v50
	v_rcp_f32_e32 v51, v51
	v_cvt_f32_i32_e32 v43, v43
	v_cvt_f32_i32_e32 v42, v42
	v_cvt_f32_i32_e32 v41, v41
	v_cvt_f32_i32_e32 v40, v40
	v_cvt_f32_i32_e32 v37, v37
	v_cvt_f32_i32_e32 v36, v36
	v_cvt_f32_i32_e32 v39, v39
	v_cvt_f32_i32_e32 v38, v38
	v_pk_mul_f32 v[52:53], v[156:157], v[122:123] op_sel_hi:[0,1]
	v_pk_mul_f32 v[54:55], v[156:157], v[120:121] op_sel_hi:[0,1]
	v_pk_mul_f32 v[42:43], v[52:53], v[42:43]
	v_pk_mul_f32 v[44:45], v[44:45], v[48:49]
	v_pk_mul_f32 v[48:49], v[156:157], v[118:119] op_sel_hi:[0,1]
	v_pk_mul_f32 v[46:47], v[46:47], v[50:51]
	v_pk_mul_f32 v[40:41], v[54:55], v[40:41]
	v_pk_mul_f32 v[36:37], v[48:49], v[36:37]
	v_pk_mul_f32 v[42:43], v[42:43], v[46:47]
	v_pk_mul_f32 v[46:47], v[156:157], v[116:117] op_sel_hi:[0,1]
	v_mul_f32_e32 v48, 0xbfb8aa3b, v36
	v_pk_mul_f32 v[40:41], v[40:41], v[44:45]
	v_mul_f32_e32 v45, 0xbfb8aa3b, v37
	v_pk_mul_f32 v[38:39], v[46:47], v[38:39]
	v_exp_f32_e32 v48, v48
	v_exp_f32_e32 v45, v45
	v_mul_f32_e32 v46, 0xbfb8aa3b, v38
	v_mul_f32_e32 v47, 0xbfb8aa3b, v39
	v_exp_f32_e32 v46, v46
	v_exp_f32_e32 v47, v47
	v_add_f32_e32 v44, 1.0, v48
	v_add_f32_e32 v45, 1.0, v45
	v_rcp_f32_e32 v44, v44
	v_rcp_f32_e32 v45, v45
	v_add_f32_e32 v46, 1.0, v46
	v_add_f32_e32 v47, 1.0, v47
	v_cvt_f32_i32_e32 v33, v33
	v_cvt_f32_i32_e32 v32, v32
	v_rcp_f32_e32 v46, v46
	v_rcp_f32_e32 v47, v47
	v_cvt_f32_i32_e32 v35, v35
	v_cvt_f32_i32_e32 v34, v34
	v_pk_mul_f32 v[50:51], v[156:157], v[114:115] op_sel_hi:[0,1]
	v_pk_mul_f32 v[48:49], v[156:157], v[112:113] op_sel_hi:[0,1]
	v_pk_mul_f32 v[32:33], v[50:51], v[32:33]
	v_pk_mul_f32 v[36:37], v[36:37], v[44:45]
	v_pk_mul_f32 v[34:35], v[48:49], v[34:35]
	v_pk_mul_f32 v[38:39], v[38:39], v[46:47]
	v_pk_mul_f32 v[32:33], v[32:33], v[36:37]
	v_pk_mul_f32 v[36:37], v[40:41], 4.0 op_sel_hi:[1,0]
	v_pk_mul_f32 v[34:35], v[34:35], v[38:39]
	v_med3_f32 v38, v36, s62, v155
	v_med3_f32 v37, v37, s62, v155
	v_mov_b32_e32 v36, 0
	v_cvt_pk_fp8_f32 v36, v38, v37
	v_pk_mul_f32 v[38:39], v[42:43], 4.0 op_sel_hi:[1,0]
	v_pk_mul_f32 v[32:33], v[32:33], 4.0 op_sel_hi:[1,0]
	v_med3_f32 v37, v38, s62, v155
	v_med3_f32 v38, v39, s62, v155
	v_cvt_pk_fp8_f32 v36, v37, v38 op_sel:[0,0,1]
	v_med3_f32 v32, v32, s62, v155
	v_med3_f32 v33, v33, s62, v155
	v_mov_b32_e32 v37, 0
	v_cvt_pk_fp8_f32 v37, v32, v33
	v_cvt_f32_i32_e32 v29, v29
	v_cvt_f32_i32_e32 v28, v28
	v_pk_mul_f32 v[34:35], v[34:35], 4.0 op_sel_hi:[1,0]
	v_add_u32_e32 v44, 0x90, v162
	v_med3_f32 v32, v34, s62, v155
	v_med3_f32 v33, v35, s62, v155
	v_cvt_pk_fp8_f32 v37, v32, v33 op_sel:[0,0,1]
	v_pk_mul_f32 v[32:33], v[158:159], v[126:127] op_sel_hi:[0,1]
	v_pk_mul_f32 v[28:29], v[32:33], v[28:29]
	v_cvt_f32_i32_e32 v31, v31
	v_mul_f32_e32 v32, 0xbfb8aa3b, v28
	v_exp_f32_e32 v34, v32
	v_cvt_f32_i32_e32 v30, v30
	v_mad_i64_i32 v[32:33], s[34:35], v44, s63, v[108:109]
	v_lshl_add_u64 v[32:33], v[32:33], 0, v[164:165]
	global_store_dwordx2 v[32:33], v[36:37], off
	v_add_f32_e32 v32, 1.0, v34
	v_pk_mul_f32 v[34:35], v[158:159], v[124:125] op_sel_hi:[0,1]
	v_pk_mul_f32 v[30:31], v[34:35], v[30:31]
	v_mul_f32_e32 v33, 0xbfb8aa3b, v29
	v_mul_f32_e32 v34, 0xbfb8aa3b, v30
	v_mul_f32_e32 v35, 0xbfb8aa3b, v31
	v_exp_f32_e32 v33, v33
	v_exp_f32_e32 v34, v34
	v_exp_f32_e32 v35, v35
	v_rcp_f32_e32 v32, v32
	v_add_f32_e32 v33, 1.0, v33
	v_add_f32_e32 v34, 1.0, v34
	v_add_f32_e32 v35, 1.0, v35
; __device__ __forceinline__ unsigned pack4_fp8(const f32x4 v) { int w = __builtin_amdgcn_cvt_pk_fp8_f32(clamp448(v[0]), clamp448(v[1]), 0, false); w = __builtin_amdgcn_cvt_pk_fp8_f32(clamp448(v[2]), clamp448(v[3]), w, true); return (unsigned)w; }
; __device__ __forceinline__ float silu_f(float g) { return g * fast_rcp(1.0f + fast_exp(-g)); }
; #define PG8_BAR __builtin_amdgcn_s_barrier()
;     __device__ __forceinline__ void operator()(const f32x4 (&acc)[2][2][4][2], const Unit& u, int wr, int wc, int fr, int fq, const float (&pr)[8]) const {
;     ...
;             for (int m = 0; m < 4; ++m) { const int row = row0 + ai * HALF + m * 16; const float s = pr[ai * 4 + m];
;                 f32x4 h[2];
; #pragma unroll
;                 for (int n = 0; n < 2; ++n) { f32x4 g, uu;
;                     if constexpr (I8IN) { const i32x4 gi = __builtin_bit_cast(i32x4, acc[ai][0][m][n]), ui = __builtin_bit_cast(i32x4, acc[ai][1][m][n]);
;                         g = (f32x4){(float)gi[0], (float)gi[1], (float)gi[2], (float)gi[3]} * (csg[n] * s); uu = (f32x4){(float)ui[0], (float)ui[1], (float)ui[2], (float)ui[3]} * (csu[n] * s); }
;                     else { g = acc[ai][0][m][n] * s; uu = acc[ai][1][m][n] * s; }
; #pragma unroll
;                     for (int j = 0; j < 4; ++j) h[n][j] = silu_f(g[j]) * uu[j]; }
;                 if constexpr (F8OUT) { u32x2 w; w.x = pack4_fp8(h[0] * hscale); w.y = pack4_fp8(h[1] * hscale); *(u32x2*)((unsigned char*)H + (size_t)row * ldh + col0) = w; }
;     ...
;         if constexpr (!Epi::AFTER_DRAIN) { E(acc, cur, wr, wc, fr, fq, pre); S.done(cur); }
;         if (!has_next) break;
; #pragma unroll
;         for (int a = 0; a < 2; ++a)
; #pragma unroll
;             for (int b = 0; b < 2; ++b)
; #pragma unroll
;                 for (int m = 0; m < 4; ++m)
; #pragma unroll
;                     for (int n = 0; n < 2; ++n) acc[a][b][m][n] = (f32x4){0.f, 0.f, 0.f, 0.f};
;         cur = nxt; cA = nA; cB = nB; ++ui;
;         if constexpr (ALIGN_EPI) { if (wr == 1) PG8_BAR; }
	v_rcp_f32_e32 v33, v33
	v_rcp_f32_e32 v34, v34
	v_rcp_f32_e32 v35, v35
	v_cvt_f32_i32_e32 v27, v27
	v_cvt_f32_i32_e32 v26, v26
	v_cvt_f32_i32_e32 v25, v25
	v_cvt_f32_i32_e32 v24, v24
	v_cvt_f32_i32_e32 v21, v21
	v_cvt_f32_i32_e32 v20, v20
	v_cvt_f32_i32_e32 v23, v23
	v_cvt_f32_i32_e32 v22, v22
	v_pk_mul_f32 v[36:37], v[158:159], v[122:123] op_sel_hi:[0,1]
	v_pk_mul_f32 v[38:39], v[158:159], v[120:121] op_sel_hi:[0,1]
	v_pk_mul_f32 v[26:27], v[36:37], v[26:27]
	v_pk_mul_f32 v[28:29], v[28:29], v[32:33]
	v_pk_mul_f32 v[32:33], v[158:159], v[118:119] op_sel_hi:[0,1]
	v_pk_mul_f32 v[30:31], v[30:31], v[34:35]
	v_pk_mul_f32 v[24:25], v[38:39], v[24:25]
	v_pk_mul_f32 v[20:21], v[32:33], v[20:21]
	v_pk_mul_f32 v[26:27], v[26:27], v[30:31]
	v_pk_mul_f32 v[30:31], v[158:159], v[116:117] op_sel_hi:[0,1]
	v_mul_f32_e32 v32, 0xbfb8aa3b, v20
	v_pk_mul_f32 v[24:25], v[24:25], v[28:29]
	v_mul_f32_e32 v29, 0xbfb8aa3b, v21
	v_pk_mul_f32 v[22:23], v[30:31], v[22:23]
	v_exp_f32_e32 v32, v32
	v_exp_f32_e32 v29, v29
	v_mul_f32_e32 v30, 0xbfb8aa3b, v22
	v_mul_f32_e32 v31, 0xbfb8aa3b, v23
	v_exp_f32_e32 v30, v30
	v_exp_f32_e32 v31, v31
	v_add_f32_e32 v28, 1.0, v32
	v_add_f32_e32 v29, 1.0, v29
	v_rcp_f32_e32 v28, v28
	v_rcp_f32_e32 v29, v29
	v_add_f32_e32 v30, 1.0, v30
	v_add_f32_e32 v31, 1.0, v31
	v_cvt_f32_i32_e32 v17, v17
	v_cvt_f32_i32_e32 v16, v16
	v_rcp_f32_e32 v30, v30
	v_rcp_f32_e32 v31, v31
	v_cvt_f32_i32_e32 v19, v19
	v_cvt_f32_i32_e32 v18, v18
	v_pk_mul_f32 v[34:35], v[158:159], v[114:115] op_sel_hi:[0,1]
	v_pk_mul_f32 v[32:33], v[158:159], v[112:113] op_sel_hi:[0,1]
	v_pk_mul_f32 v[16:17], v[34:35], v[16:17]
	v_pk_mul_f32 v[20:21], v[20:21], v[28:29]
	v_pk_mul_f32 v[18:19], v[32:33], v[18:19]
	v_pk_mul_f32 v[22:23], v[22:23], v[30:31]
	v_pk_mul_f32 v[16:17], v[16:17], v[20:21]
	v_pk_mul_f32 v[20:21], v[24:25], 4.0 op_sel_hi:[1,0]
	v_pk_mul_f32 v[18:19], v[18:19], v[22:23]
	v_med3_f32 v22, v20, s62, v155
	v_med3_f32 v21, v21, s62, v155
	v_mov_b32_e32 v20, 0
	v_cvt_pk_fp8_f32 v20, v22, v21
	v_pk_mul_f32 v[22:23], v[26:27], 4.0 op_sel_hi:[1,0]
	v_pk_mul_f32 v[16:17], v[16:17], 4.0 op_sel_hi:[1,0]
	v_med3_f32 v21, v22, s62, v155
	v_med3_f32 v22, v23, s62, v155
	v_cvt_pk_fp8_f32 v20, v21, v22 op_sel:[0,0,1]
	v_med3_f32 v16, v16, s62, v155
	v_med3_f32 v17, v17, s62, v155
	v_mov_b32_e32 v21, 0
	v_cvt_pk_fp8_f32 v21, v16, v17
	v_cvt_f32_i32_e32 v13, v13
	v_cvt_f32_i32_e32 v12, v12
	v_pk_mul_f32 v[18:19], v[18:19], 4.0 op_sel_hi:[1,0]
	v_add_u32_e32 v28, 0xa0, v162
	v_med3_f32 v16, v18, s62, v155
	v_med3_f32 v17, v19, s62, v155
	v_cvt_pk_fp8_f32 v21, v16, v17 op_sel:[0,0,1]
	v_pk_mul_f32 v[16:17], v[160:161], v[126:127] op_sel_hi:[0,1]
	v_pk_mul_f32 v[12:13], v[16:17], v[12:13]
	v_cvt_f32_i32_e32 v15, v15
	v_mul_f32_e32 v16, 0xbfb8aa3b, v12
	v_exp_f32_e32 v18, v16
	v_cvt_f32_i32_e32 v14, v14
	v_mad_i64_i32 v[16:17], s[34:35], v28, s63, v[108:109]
	v_lshl_add_u64 v[16:17], v[16:17], 0, v[164:165]
	global_store_dwordx2 v[16:17], v[20:21], off
	v_add_f32_e32 v16, 1.0, v18
	v_pk_mul_f32 v[18:19], v[160:161], v[124:125] op_sel_hi:[0,1]
	v_pk_mul_f32 v[14:15], v[18:19], v[14:15]
	v_mul_f32_e32 v17, 0xbfb8aa3b, v13
	v_mul_f32_e32 v18, 0xbfb8aa3b, v14
	v_mul_f32_e32 v19, 0xbfb8aa3b, v15
	v_exp_f32_e32 v17, v17
	v_exp_f32_e32 v18, v18
	v_exp_f32_e32 v19, v19
	v_rcp_f32_e32 v16, v16
	v_add_f32_e32 v17, 1.0, v17
	v_add_f32_e32 v18, 1.0, v18
	v_add_f32_e32 v19, 1.0, v19
	v_rcp_f32_e32 v17, v17
	v_rcp_f32_e32 v18, v18
	v_rcp_f32_e32 v19, v19
	v_cvt_f32_i32_e32 v11, v11
	v_cvt_f32_i32_e32 v10, v10
	v_cvt_f32_i32_e32 v9, v9
	v_cvt_f32_i32_e32 v8, v8
	v_cvt_f32_i32_e32 v5, v5
	v_cvt_f32_i32_e32 v4, v4
	v_cvt_f32_i32_e32 v7, v7
	v_cvt_f32_i32_e32 v6, v6
	v_pk_mul_f32 v[20:21], v[160:161], v[122:123] op_sel_hi:[0,1]
	v_pk_mul_f32 v[22:23], v[160:161], v[120:121] op_sel_hi:[0,1]
	v_pk_mul_f32 v[10:11], v[20:21], v[10:11]
	v_pk_mul_f32 v[12:13], v[12:13], v[16:17]
	v_pk_mul_f32 v[16:17], v[160:161], v[118:119] op_sel_hi:[0,1]
	v_pk_mul_f32 v[14:15], v[14:15], v[18:19]
	v_pk_mul_f32 v[8:9], v[22:23], v[8:9]
	v_pk_mul_f32 v[4:5], v[16:17], v[4:5]
	v_pk_mul_f32 v[10:11], v[10:11], v[14:15]
	v_pk_mul_f32 v[14:15], v[160:161], v[116:117] op_sel_hi:[0,1]
	v_mul_f32_e32 v16, 0xbfb8aa3b, v4
	v_pk_mul_f32 v[8:9], v[8:9], v[12:13]
	v_mul_f32_e32 v13, 0xbfb8aa3b, v5
	v_pk_mul_f32 v[6:7], v[14:15], v[6:7]
	v_exp_f32_e32 v16, v16
	v_exp_f32_e32 v13, v13
	v_mul_f32_e32 v14, 0xbfb8aa3b, v6
	v_mul_f32_e32 v15, 0xbfb8aa3b, v7
	v_exp_f32_e32 v14, v14
	v_exp_f32_e32 v15, v15
	v_add_f32_e32 v12, 1.0, v16
	v_add_f32_e32 v13, 1.0, v13
	v_rcp_f32_e32 v12, v12
	v_rcp_f32_e32 v13, v13
	v_add_f32_e32 v14, 1.0, v14
	v_add_f32_e32 v15, 1.0, v15
	v_cvt_f32_i32_e32 v1, v1
	v_cvt_f32_i32_e32 v0, v0
	v_rcp_f32_e32 v14, v14
	v_rcp_f32_e32 v15, v15
	v_cvt_f32_i32_e32 v3, v3
	v_cvt_f32_i32_e32 v2, v2
	v_pk_mul_f32 v[18:19], v[160:161], v[114:115] op_sel_hi:[0,1]
	v_pk_mul_f32 v[16:17], v[160:161], v[112:113] op_sel_hi:[0,1]
	v_pk_mul_f32 v[0:1], v[18:19], v[0:1]
	v_pk_mul_f32 v[4:5], v[4:5], v[12:13]
	v_pk_mul_f32 v[2:3], v[16:17], v[2:3]
	v_pk_mul_f32 v[6:7], v[6:7], v[14:15]
	v_pk_mul_f32 v[0:1], v[0:1], v[4:5]
	v_pk_mul_f32 v[4:5], v[8:9], 4.0 op_sel_hi:[1,0]
	v_pk_mul_f32 v[2:3], v[2:3], v[6:7]
	v_med3_f32 v6, v4, s62, v155
	v_med3_f32 v5, v5, s62, v155
	v_mov_b32_e32 v4, 0
	v_cvt_pk_fp8_f32 v4, v6, v5
	v_pk_mul_f32 v[6:7], v[10:11], 4.0 op_sel_hi:[1,0]
	v_pk_mul_f32 v[0:1], v[0:1], 4.0 op_sel_hi:[1,0]
	v_med3_f32 v5, v6, s62, v155
	v_med3_f32 v6, v7, s62, v155
	v_cvt_pk_fp8_f32 v4, v5, v6 op_sel:[0,0,1]
	v_med3_f32 v0, v0, s62, v155
	v_med3_f32 v1, v1, s62, v155
	v_mov_b32_e32 v5, 0
	v_cvt_pk_fp8_f32 v5, v0, v1
	v_pk_mul_f32 v[0:1], v[2:3], 4.0 op_sel_hi:[1,0]
	v_add_u32_e32 v12, 0xb0, v162
	v_med3_f32 v0, v0, s62, v155
	v_med3_f32 v1, v1, s62, v155
	v_cvt_pk_fp8_f32 v5, v0, v1 op_sel:[0,0,1]
	v_mad_i64_i32 v[0:1], s[34:35], v12, s63, v[108:109]
	v_lshl_add_u64 v[0:1], v[0:1], 0, v[164:165]
	s_andn2_b64 vcc, exec, s[4:5]
	s_mov_b64 s[4:5], -1
	global_store_dwordx2 v[0:1], v[4:5], off
	s_cbranch_vccnz .LBB0_847
	s_andn2_b64 vcc, exec, s[8:9]
	s_cbranch_vccnz .LBB0_846
	s_barrier
	s_branch .LBB0_846

;     __device__ __forceinline__ void operator()(const f32x4 (&acc)[2][2][4][2], const Unit& u, int wr, int wc, int fr, int fq, const float (&pr)[8]) const {
;     ...
;             for (int n = 0; n < 2; ++n) { const u32x4 a = *(const u32x4*)(colmax + u.pn * BM + wc * 32 + 8 * fq + 4 * n), b = *(const u32x4*)(colmax + u.pn * BM + HALF + wc * 32 + 8 * fq + 4 * n);
;                 csg[n] = (f32x4){__uint_as_float(a.x), __uint_as_float(a.y), __uint_as_float(a.z), __uint_as_float(a.w)} * (1.0f / 127.0f);
;                 csu[n] = (f32x4){__uint_as_float(b.x), __uint_as_float(b.y), __uint_as_float(b.z), __uint_as_float(b.w)} * (1.0f / 127.0f); }
.Lp1_cm_load:
	s_lshl_b32 s98, s71, 8
	s_ashr_i32 s99, s98, 31
	v_lshl_add_u64 v[250:251], s[98:99], 2, v[136:137]
	global_load_dwordx4 v[242:245], v[250:251], off
	global_load_dwordx4 v[246:249], v[250:251], off offset:512
	global_load_dword v157, v[250:251], off offset:528
	global_load_dword v159, v[250:251], off offset:532
	global_load_dword v161, v[250:251], off offset:536
	global_load_dword v163, v[250:251], off offset:540
	s_nop 0
	global_load_dwordx4 v[250:253], v[250:251], off offset:16
	s_branch .Lp1_cm_back
.Lp9_cm_load:
	s_lshl_b32 s98, s64, 8
	s_ashr_i32 s99, s98, 31
	v_lshl_add_u64 v[250:251], s[98:99], 2, v[136:137]
	global_load_dwordx4 v[242:245], v[250:251], off
	global_load_dwordx4 v[246:249], v[250:251], off offset:512
	global_load_dword v159, v[250:251], off offset:528
	global_load_dword v161, v[250:251], off offset:532
	global_load_dword v163, v[250:251], off offset:536
	global_load_dword v255, v[250:251], off offset:540
	s_nop 0
	global_load_dwordx4 v[250:253], v[250:251], off offset:16
	s_branch .Lp9_cm_back

; #define LAS __attribute__((address_space(3)))
; __global__ void __launch_bounds__(NTHREADS, 2) hymba_fwd(Args A) {
;     extern __shared__ __attribute__((aligned(16))) unsigned char lds_raw[];
;     LAS unsigned char* lds = (LAS unsigned char*)lds_raw;
;     cg::grid_group grid = cg::this_grid();
;     const int tid = threadIdx.x, G = gridDim.x, lo = A.ph_lo, hi = A.ph_hi;
	.amdhsa_kernel _Z9hymba_fwd4Args
		.amdhsa_group_segment_fixed_size 0
		.amdhsa_private_segment_fixed_size 0
		.amdhsa_kernarg_size 448
		.amdhsa_user_sgpr_count 2
		.amdhsa_user_sgpr_dispatch_ptr 0
		.amdhsa_user_sgpr_queue_ptr 0
		.amdhsa_user_sgpr_kernarg_segment_ptr 1
		.amdhsa_user_sgpr_dispatch_id 0
		.amdhsa_user_sgpr_kernarg_preload_length 0
		.amdhsa_user_sgpr_kernarg_preload_offset 0
		.amdhsa_user_sgpr_private_segment_size 0
		.amdhsa_uses_dynamic_stack 0
		.amdhsa_enable_private_segment 0
		.amdhsa_system_sgpr_workgroup_id_x 1
		.amdhsa_system_sgpr_workgroup_id_y 0
		.amdhsa_system_sgpr_workgroup_id_z 0
		.amdhsa_system_sgpr_workgroup_info 0
		.amdhsa_system_vgpr_workitem_id 2
		.amdhsa_next_free_vgpr 256
		.amdhsa_next_free_sgpr 100
		.amdhsa_accum_offset 256
		.amdhsa_reserve_vcc 1
		.amdhsa_float_round_mode_32 0
		.amdhsa_float_round_mode_16_64 0
		.amdhsa_float_denorm_mode_32 3
		.amdhsa_float_denorm_mode_16_64 3
		.amdhsa_dx10_clamp 1
		.amdhsa_ieee_mode 1
		.amdhsa_fp16_overflow 0
		.amdhsa_tg_split 0
		.amdhsa_exception_fp_ieee_invalid_op 0
		.amdhsa_exception_fp_denorm_src 0
		.amdhsa_exception_fp_ieee_div_zero 0
		.amdhsa_exception_fp_ieee_overflow 0
		.amdhsa_exception_fp_ieee_underflow 0
		.amdhsa_exception_fp_ieee_inexact 0
		.amdhsa_exception_int_div_zero 0
	.end_amdhsa_kernel

; #define LAS __attribute__((address_space(3)))
; __global__ void __launch_bounds__(NTHREADS, 2) hymba_fwd(Args A) {
;     extern __shared__ __attribute__((aligned(16))) unsigned char lds_raw[];
;     LAS unsigned char* lds = (LAS unsigned char*)lds_raw;
;     cg::grid_group grid = cg::this_grid();
;     const int tid = threadIdx.x, G = gridDim.x, lo = A.ph_lo, hi = A.ph_hi;
amdhsa.kernels:
  - .agpr_count:     0
    .args:
      - .offset:         0
        .size:           192
        .value_kind:     by_value
      - .offset:         192
        .size:           4
        .value_kind:     hidden_block_count_x
      - .offset:         196
        .size:           4
        .value_kind:     hidden_block_count_y
      - .offset:         200
        .size:           4
        .value_kind:     hidden_block_count_z
      - .offset:         204
        .size:           2
        .value_kind:     hidden_group_size_x
      - .offset:         206
        .size:           2
        .value_kind:     hidden_group_size_y
      - .offset:         208
        .size:           2
        .value_kind:     hidden_group_size_z
      - .offset:         210
        .size:           2
        .value_kind:     hidden_remainder_x
      - .offset:         212
        .size:           2
        .value_kind:     hidden_remainder_y
      - .offset:         214
        .size:           2
        .value_kind:     hidden_remainder_z
      - .offset:         232
        .size:           8
        .value_kind:     hidden_global_offset_x
      - .offset:         240
        .size:           8
        .value_kind:     hidden_global_offset_y
      - .offset:         248
        .size:           8
        .value_kind:     hidden_global_offset_z
      - .offset:         256
        .size:           2
        .value_kind:     hidden_grid_dims
      - .offset:         280
        .size:           8
        .value_kind:     hidden_multigrid_sync_arg
      - .offset:         312
        .size:           4
        .value_kind:     hidden_dynamic_lds_size
    .group_segment_fixed_size: 0
    .kernarg_segment_align: 8
    .kernarg_segment_size: 448
    .language:       OpenCL C
    .language_version:
      - 2
      - 0
    .max_flat_workgroup_size: 512
    .name:           _Z9hymba_fwd4Args
    .private_segment_fixed_size: 0
    .sgpr_count:     106
    .sgpr_spill_count: 20
    .symbol:         _Z9hymba_fwd4Args.kd
    .uniform_work_group_size: 1
    .uses_dynamic_stack: false
    .vgpr_count:     256
    .vgpr_spill_count: 0
    .wavefront_size: 64
